# NA attention unit rewritten by hand: static masks folded into MFMA C operand, aligned b128 bias reads, dead S registers and PV MFMAs skipped, software-pipelined slots
# speedup vs baseline: 1.1132x; 1.0483x over previous
.LBB0_1698:
	s_cmpk_lt_i32 s2, 0x200
	v_writelane_b32 v250, s86, 1
	s_cselect_b64 s[0:1], -1, 0
	v_writelane_b32 v250, s0, 2
	s_cmpk_gt_i32 s2, 0x1ff
	v_and_b32_e32 v160, 31, v0
	v_lshrrev_b32_e32 v1, 5, v198
	v_lshlrev_b32_e32 v178, 4, v0
	v_lshrrev_b32_e32 v147, 3, v0
	v_writelane_b32 v250, s1, 3
	v_writelane_b32 v251, s2, 61
	s_cbranch_scc1 .LBB0_1875
	v_readlane_b32 s4, v251, 48
	v_readlane_b32 s5, v251, 49
	v_readlane_b32 s6, v251, 15
	v_readlane_b32 s7, v251, 16
	v_readlane_b32 s8, v251, 52
	v_readlane_b32 s9, v251, 23
	v_readlane_b32 s10, v251, 61
	s_nop 3
	s_and_b32 s11, s8, 1
	v_and_b32_e32 v216, 31, v0
	v_bfe_u32 v217, v0, 5, 1
	v_mov_b32_e32 v228, 0
	v_mov_b32_e32 v229, 0xf149f2ca
	s_lshl_b32 s36, s11, 5
	v_add_u32_e32 v222, s36, v216
	v_mul_u32_u24_e32 v199, 0x90, v222
	v_lshl_add_u32 v199, v217, 4, v199
	s_cmp_eq_u32 s11, 0
	s_cselect_b32 s37, 0, 24
	s_cselect_b32 s38, 32, 0
	v_add_u32_e32 v222, s37, v216
	v_and_b32_e32 v222, 31, v222
	v_add_u32_e32 v222, s38, v222
	v_mul_u32_u24_e32 v200, 0x90, v222
	v_lshl_add_u32 v200, v217, 4, v200
	v_mul_u32_u24_e32 v222, 0x88, v216
	v_lshl_add_u32 v222, v217, 3, v222
	v_add_u32_e32 v222, 0x4800, v222
	s_lshl_b32 s36, s11, 6
	v_add_u32_e32 v201, s36, v222
	s_cmp_eq_u32 s11, 0
	s_cselect_b32 s37, 64, 48
	s_cselect_b32 s38, 0x50, 0
	v_add_u32_e32 v202, s37, v222
	v_add_u32_e32 v203, s38, v222
	v_lshrrev_b32_e32 v222, 3, v0
	v_and_b32_e32 v223, 7, v0
	v_mul_u32_u24_e32 v204, 0x90, v222
	v_lshl_add_u32 v204, v223, 4, v204
	v_mul_u32_u24_e32 v205, 0x88, v222
	v_lshl_add_u32 v205, v223, 4, v205
	v_add_u32_e32 v205, 0x4800, v205
	v_lshlrev_b32_e32 v206, 4, v0
	v_mul_u32_u24_e32 v207, 0x2200, v222
	v_lshl_add_u32 v207, v223, 4, v207
	v_lshl_or_b32 v222, s8, 5, v216
	v_lshlrev_b32_e32 v219, 7, v222
	v_lshl_add_u32 v219, v217, 4, v219
	v_lshlrev_b32_e32 v218, 10, v222
	v_lshl_add_u32 v218, v217, 3, v218
	v_and_b32_e32 v222, 3, v216
	v_add_u32_e32 v223, 1, v222
	v_and_b32_e32 v223, 3, v223
	v_lshl_add_u32 v223, v217, 2, v223
	v_sub_u32_e32 v223, v223, v216
	v_add_u32_e32 v223, 39, v223
	v_lshlrev_b32_e32 v223, 2, v223
	v_mul_u32_u24_e32 v222, 5040, v222
	v_add_u32_e32 v208, v222, v223
	v_add_u32_e32 v208, 0x8c00, v208
	s_cmp_eq_u32 s11, 0
	s_mov_b32 s37, 0x80
	s_cselect_b32 s37, s37, 0xffffffe0
	v_add_u32_e32 v209, s37, v208
	v_mov_b32_e32 v186, 0
	v_mov_b32_e32 v187, 0
	s_lshr_b32 s36, s10, 4
	s_and_b32 s36, s36, 7
	s_mul_i32 s36, s36, 0x744
	s_add_u32 s38, s6, s36
	s_addc_u32 s39, s7, 0
	v_mov_b32_e32 v222, v0
	s_mov_b32 s36, 0xd00e
	v_mul_lo_u32 v223, v222, s36
	v_lshrrev_b32_e32 v223, 26, v223
	v_mul_u32_u24_e32 v224, 1260, v223
	v_sub_u32_e32 v224, v222, v224
	v_mul_u32_u24_e32 v225, 49933, v224
	v_lshrrev_b32_e32 v225, 22, v225
	v_mul_u32_u24_e32 v226, 84, v225
	v_sub_u32_e32 v226, v224, v226
	v_add_u32_e32 v227, 1, v223
	v_and_b32_e32 v227, 3, v227
	v_sub_u32_e32 v226, v226, v227
	v_subrev_u32_e32 v226, 24, v226
	v_cmp_gt_u32_e32 vcc, 31, v226
	v_cndmask_b32_e32 v227, 0, v226, vcc
	v_mad_u32_u24 v227, v225, 31, v227
	v_lshlrev_b32_e32 v227, 2, v227
	global_load_dword v227, v227, s[38:39]
	v_lshlrev_b32_e32 v222, 2, v222
	s_waitcnt vmcnt(0)
	v_mul_f32_e32 v227, 0x3fb8aa3b, v227
	v_cndmask_b32_e32 v227, 0, v227, vcc
	ds_write_b32 v222, v227 offset:35840
	v_add_u32_e32 v222, 512, v0
	s_mov_b32 s36, 0xd00e
	v_mul_lo_u32 v223, v222, s36
	v_lshrrev_b32_e32 v223, 26, v223
	v_mul_u32_u24_e32 v224, 1260, v223
	v_sub_u32_e32 v224, v222, v224
	v_mul_u32_u24_e32 v225, 49933, v224
	v_lshrrev_b32_e32 v225, 22, v225
	v_mul_u32_u24_e32 v226, 84, v225
	v_sub_u32_e32 v226, v224, v226
	v_add_u32_e32 v227, 1, v223
	v_and_b32_e32 v227, 3, v227
	v_sub_u32_e32 v226, v226, v227
	v_subrev_u32_e32 v226, 24, v226
	v_cmp_gt_u32_e32 vcc, 31, v226
	v_cndmask_b32_e32 v227, 0, v226, vcc
	v_mad_u32_u24 v227, v225, 31, v227
	v_lshlrev_b32_e32 v227, 2, v227
	global_load_dword v227, v227, s[38:39]
	v_lshlrev_b32_e32 v222, 2, v222
	s_waitcnt vmcnt(0)
	v_mul_f32_e32 v227, 0x3fb8aa3b, v227
	v_cndmask_b32_e32 v227, 0, v227, vcc
	ds_write_b32 v222, v227 offset:35840
	v_add_u32_e32 v222, 1024, v0
	s_mov_b32 s36, 0xd00e
	v_mul_lo_u32 v223, v222, s36
	v_lshrrev_b32_e32 v223, 26, v223
	v_mul_u32_u24_e32 v224, 1260, v223
	v_sub_u32_e32 v224, v222, v224
	v_mul_u32_u24_e32 v225, 49933, v224
	v_lshrrev_b32_e32 v225, 22, v225
	v_mul_u32_u24_e32 v226, 84, v225
	v_sub_u32_e32 v226, v224, v226
	v_add_u32_e32 v227, 1, v223
	v_and_b32_e32 v227, 3, v227
	v_sub_u32_e32 v226, v226, v227
	v_subrev_u32_e32 v226, 24, v226
	v_cmp_gt_u32_e32 vcc, 31, v226
	v_cndmask_b32_e32 v227, 0, v226, vcc
	v_mad_u32_u24 v227, v225, 31, v227
	v_lshlrev_b32_e32 v227, 2, v227
	global_load_dword v227, v227, s[38:39]
	v_lshlrev_b32_e32 v222, 2, v222
	s_waitcnt vmcnt(0)
	v_mul_f32_e32 v227, 0x3fb8aa3b, v227
	v_cndmask_b32_e32 v227, 0, v227, vcc
	ds_write_b32 v222, v227 offset:35840
	v_add_u32_e32 v222, 1536, v0
	s_mov_b32 s36, 0xd00e
	v_mul_lo_u32 v223, v222, s36
	v_lshrrev_b32_e32 v223, 26, v223
	v_mul_u32_u24_e32 v224, 1260, v223
	v_sub_u32_e32 v224, v222, v224
	v_mul_u32_u24_e32 v225, 49933, v224
	v_lshrrev_b32_e32 v225, 22, v225
	v_mul_u32_u24_e32 v226, 84, v225
	v_sub_u32_e32 v226, v224, v226
	v_add_u32_e32 v227, 1, v223
	v_and_b32_e32 v227, 3, v227
	v_sub_u32_e32 v226, v226, v227
	v_subrev_u32_e32 v226, 24, v226
	v_cmp_gt_u32_e32 vcc, 31, v226
	v_cndmask_b32_e32 v227, 0, v226, vcc
	v_mad_u32_u24 v227, v225, 31, v227
	v_lshlrev_b32_e32 v227, 2, v227
	global_load_dword v227, v227, s[38:39]
	v_lshlrev_b32_e32 v222, 2, v222
	s_waitcnt vmcnt(0)
	v_mul_f32_e32 v227, 0x3fb8aa3b, v227
	v_cndmask_b32_e32 v227, 0, v227, vcc
	ds_write_b32 v222, v227 offset:35840
	v_add_u32_e32 v222, 2048, v0
	s_mov_b32 s36, 0xd00e
	v_mul_lo_u32 v223, v222, s36
	v_lshrrev_b32_e32 v223, 26, v223
	v_mul_u32_u24_e32 v224, 1260, v223
	v_sub_u32_e32 v224, v222, v224
	v_mul_u32_u24_e32 v225, 49933, v224
	v_lshrrev_b32_e32 v225, 22, v225
	v_mul_u32_u24_e32 v226, 84, v225
	v_sub_u32_e32 v226, v224, v226
	v_add_u32_e32 v227, 1, v223
	v_and_b32_e32 v227, 3, v227
	v_sub_u32_e32 v226, v226, v227
	v_subrev_u32_e32 v226, 24, v226
	v_cmp_gt_u32_e32 vcc, 31, v226
	v_cndmask_b32_e32 v227, 0, v226, vcc
	v_mad_u32_u24 v227, v225, 31, v227
	v_lshlrev_b32_e32 v227, 2, v227
	global_load_dword v227, v227, s[38:39]
	v_lshlrev_b32_e32 v222, 2, v222
	s_waitcnt vmcnt(0)
	v_mul_f32_e32 v227, 0x3fb8aa3b, v227
	v_cndmask_b32_e32 v227, 0, v227, vcc
	ds_write_b32 v222, v227 offset:35840
	v_add_u32_e32 v222, 2560, v0
	s_mov_b32 s36, 0xd00e
	v_mul_lo_u32 v223, v222, s36
	v_lshrrev_b32_e32 v223, 26, v223
	v_mul_u32_u24_e32 v224, 1260, v223
	v_sub_u32_e32 v224, v222, v224
	v_mul_u32_u24_e32 v225, 49933, v224
	v_lshrrev_b32_e32 v225, 22, v225
	v_mul_u32_u24_e32 v226, 84, v225
	v_sub_u32_e32 v226, v224, v226
	v_add_u32_e32 v227, 1, v223
	v_and_b32_e32 v227, 3, v227
	v_sub_u32_e32 v226, v226, v227
	v_subrev_u32_e32 v226, 24, v226
	v_cmp_gt_u32_e32 vcc, 31, v226
	v_cndmask_b32_e32 v227, 0, v226, vcc
	v_mad_u32_u24 v227, v225, 31, v227
	v_lshlrev_b32_e32 v227, 2, v227
	global_load_dword v227, v227, s[38:39]
	v_lshlrev_b32_e32 v222, 2, v222
	s_waitcnt vmcnt(0)
	v_mul_f32_e32 v227, 0x3fb8aa3b, v227
	v_cndmask_b32_e32 v227, 0, v227, vcc
	ds_write_b32 v222, v227 offset:35840
	v_add_u32_e32 v222, 3072, v0
	s_mov_b32 s36, 0xd00e
	v_mul_lo_u32 v223, v222, s36
	v_lshrrev_b32_e32 v223, 26, v223
	v_mul_u32_u24_e32 v224, 1260, v223
	v_sub_u32_e32 v224, v222, v224
	v_mul_u32_u24_e32 v225, 49933, v224
	v_lshrrev_b32_e32 v225, 22, v225
	v_mul_u32_u24_e32 v226, 84, v225
	v_sub_u32_e32 v226, v224, v226
	v_add_u32_e32 v227, 1, v223
	v_and_b32_e32 v227, 3, v227
	v_sub_u32_e32 v226, v226, v227
	v_subrev_u32_e32 v226, 24, v226
	v_cmp_gt_u32_e32 vcc, 31, v226
	v_cndmask_b32_e32 v227, 0, v226, vcc
	v_mad_u32_u24 v227, v225, 31, v227
	v_lshlrev_b32_e32 v227, 2, v227
	global_load_dword v227, v227, s[38:39]
	v_lshlrev_b32_e32 v222, 2, v222
	s_waitcnt vmcnt(0)
	v_mul_f32_e32 v227, 0x3fb8aa3b, v227
	v_cndmask_b32_e32 v227, 0, v227, vcc
	ds_write_b32 v222, v227 offset:35840
	v_add_u32_e32 v222, 3584, v0
	s_mov_b32 s36, 0xd00e
	v_mul_lo_u32 v223, v222, s36
	v_lshrrev_b32_e32 v223, 26, v223
	v_mul_u32_u24_e32 v224, 1260, v223
	v_sub_u32_e32 v224, v222, v224
	v_mul_u32_u24_e32 v225, 49933, v224
	v_lshrrev_b32_e32 v225, 22, v225
	v_mul_u32_u24_e32 v226, 84, v225
	v_sub_u32_e32 v226, v224, v226
	v_add_u32_e32 v227, 1, v223
	v_and_b32_e32 v227, 3, v227
	v_sub_u32_e32 v226, v226, v227
	v_subrev_u32_e32 v226, 24, v226
	v_cmp_gt_u32_e32 vcc, 31, v226
	v_cndmask_b32_e32 v227, 0, v226, vcc
	v_mad_u32_u24 v227, v225, 31, v227
	v_lshlrev_b32_e32 v227, 2, v227
	global_load_dword v227, v227, s[38:39]
	v_lshlrev_b32_e32 v222, 2, v222
	s_waitcnt vmcnt(0)
	v_mul_f32_e32 v227, 0x3fb8aa3b, v227
	v_cndmask_b32_e32 v227, 0, v227, vcc
	ds_write_b32 v222, v227 offset:35840
	v_add_u32_e32 v222, 4096, v0
	s_mov_b32 s36, 0xd00e
	v_mul_lo_u32 v223, v222, s36
	v_lshrrev_b32_e32 v223, 26, v223
	v_mul_u32_u24_e32 v224, 1260, v223
	v_sub_u32_e32 v224, v222, v224
	v_mul_u32_u24_e32 v225, 49933, v224
	v_lshrrev_b32_e32 v225, 22, v225
	v_mul_u32_u24_e32 v226, 84, v225
	v_sub_u32_e32 v226, v224, v226
	v_add_u32_e32 v227, 1, v223
	v_and_b32_e32 v227, 3, v227
	v_sub_u32_e32 v226, v226, v227
	v_subrev_u32_e32 v226, 24, v226
	v_cmp_gt_u32_e32 vcc, 31, v226
	v_cndmask_b32_e32 v227, 0, v226, vcc
	v_mad_u32_u24 v227, v225, 31, v227
	v_lshlrev_b32_e32 v227, 2, v227
	global_load_dword v227, v227, s[38:39]
	v_lshlrev_b32_e32 v222, 2, v222
	s_waitcnt vmcnt(0)
	v_mul_f32_e32 v227, 0x3fb8aa3b, v227
	v_cndmask_b32_e32 v227, 0, v227, vcc
	ds_write_b32 v222, v227 offset:35840
	v_add_u32_e32 v222, 4608, v0
	s_mov_b32 s36, 0xd00e
	v_mul_lo_u32 v223, v222, s36
	v_lshrrev_b32_e32 v223, 26, v223
	v_mul_u32_u24_e32 v224, 1260, v223
	v_sub_u32_e32 v224, v222, v224
	v_mul_u32_u24_e32 v225, 49933, v224
	v_lshrrev_b32_e32 v225, 22, v225
	v_mul_u32_u24_e32 v226, 84, v225
	v_sub_u32_e32 v226, v224, v226
	v_add_u32_e32 v227, 1, v223
	v_and_b32_e32 v227, 3, v227
	v_sub_u32_e32 v226, v226, v227
	v_subrev_u32_e32 v226, 24, v226
	v_cmp_gt_u32_e32 vcc, 31, v226
	v_cndmask_b32_e32 v227, 0, v226, vcc
	v_mad_u32_u24 v227, v225, 31, v227
	v_lshlrev_b32_e32 v227, 2, v227
	global_load_dword v227, v227, s[38:39]
	v_lshlrev_b32_e32 v222, 2, v222
	s_waitcnt vmcnt(0)
	v_mul_f32_e32 v227, 0x3fb8aa3b, v227
	v_cndmask_b32_e32 v227, 0, v227, vcc
	v_cmp_gt_u32_e32 vcc, 0x4ec0, v222
	s_and_saveexec_b64 s[40:41], vcc
	ds_write_b32 v222, v227 offset:35840
	s_mov_b64 exec, s[40:41]
.Lna_unit:
	s_lshr_b32 s36, s10, 4
	s_and_b32 s37, s10, 15
	s_mul_i32 s38, s36, 0x88000
	s_add_u32 s38, s38, 0x4700000
	s_add_u32 s12, s4, s38
	s_addc_u32 s13, s5, 0
	s_add_u32 s38, s38, 0x1100000
	s_add_u32 s14, s4, s38
	s_addc_u32 s15, s5, 0
	s_add_u32 s16, s12, 0x80000
	s_addc_u32 s17, s13, 0
	s_add_u32 s18, s14, 0x2000
	s_addc_u32 s19, s15, 0
	s_lshr_b32 s40, s8, 1
	s_add_i32 s41, s40, 1
	s_add_i32 s38, s37, -1
	s_cmp_lt_u32 s38, 14
	s_cselect_b32 s22, 12, 8
	s_cselect_b32 s39, 1, 0
	s_cselect_b32 s23, s41, 0
	s_lshl_b32 s41, s37, 2
	s_add_i32 s42, s41, -4
	s_max_i32 s42, s42, 0
	s_min_i32 s42, s42, 56
	s_sub_i32 s42, s42, s39
	s_add_i32 s43, s41, s40
	s_sub_i32 s43, s42, s43
	s_add_i32 s43, s43, 7
	s_mul_i32 s25, s43, 0x150
	s_ashr_i32 s43, s42, 31
	s_lshl_b64 s[44:45], s[42:43], 13
	s_add_u32 s12, s12, s44
	s_addc_u32 s13, s13, s45
	s_lshl_b64 s[44:45], s[42:43], 7
	s_add_u32 s14, s14, s44
	s_addc_u32 s15, s15, s45
	s_lshl_b32 s38, s36, 12
	s_lshl_b32 s39, s37, 8
	s_add_u32 s38, s38, s39
	s_lshl_b32 s38, s38, 7
	s_add_u32 s38, s38, 0x6900000
	s_add_u32 s34, s4, s38
	s_addc_u32 s35, s5, 0
	s_lshr_b32 s38, s36, 3
	s_lshl_b32 s38, s38, 12
	s_add_u32 s38, s38, s39
	s_lshl_b32 s38, s38, 10
	s_and_b32 s40, s36, 7
	s_lshl_b32 s40, s40, 7
	s_add_u32 s38, s38, s40
	s_add_u32 s38, s38, 0x8900000
	s_add_u32 s30, s4, s38
	s_addc_u32 s31, s5, 0
	global_load_dwordx4 v[98:101], v219, s[34:35] offset:0
	global_load_dwordx4 v[102:105], v219, s[34:35] offset:32
	global_load_dwordx4 v[106:109], v219, s[34:35] offset:64
	global_load_dwordx4 v[110:113], v219, s[34:35] offset:96
	global_load_dwordx4 v[146:149], v206, s[12:13]
	s_add_u32 s12, s12, 0x2000
	s_addc_u32 s13, s13, 0
	global_load_dwordx4 v[188:191], v206, s[12:13]
	s_add_u32 s12, s12, 0x2000
	s_addc_u32 s13, s13, 0
	global_load_dwordx4 v[192:195], v207, s[14:15]
	s_add_u32 s14, s14, 0x80
	s_addc_u32 s15, s15, 0
	s_mov_b32 s20, 2
	s_mov_b32 s21, 1
	v_mov_b32_e32 v2, 0
	v_mov_b32_e32 v3, 0
	v_mov_b32_e32 v4, 0
	v_mov_b32_e32 v5, 0
	v_mov_b32_e32 v6, 0
	v_mov_b32_e32 v7, 0
	v_mov_b32_e32 v8, 0
	v_mov_b32_e32 v9, 0
	v_mov_b32_e32 v10, 0
	v_mov_b32_e32 v11, 0
	v_mov_b32_e32 v12, 0
	v_mov_b32_e32 v13, 0
	v_mov_b32_e32 v14, 0
	v_mov_b32_e32 v15, 0
	v_mov_b32_e32 v16, 0
	v_mov_b32_e32 v17, 0
	v_mov_b32_e32 v18, 0
	v_mov_b32_e32 v19, 0
	v_mov_b32_e32 v20, 0
	v_mov_b32_e32 v21, 0
	v_mov_b32_e32 v22, 0
	v_mov_b32_e32 v23, 0
	v_mov_b32_e32 v24, 0
	v_mov_b32_e32 v25, 0
	v_mov_b32_e32 v26, 0
	v_mov_b32_e32 v27, 0
	v_mov_b32_e32 v28, 0
	v_mov_b32_e32 v29, 0
	v_mov_b32_e32 v30, 0
	v_mov_b32_e32 v31, 0
	v_mov_b32_e32 v32, 0
	v_mov_b32_e32 v33, 0
	v_mov_b32_e32 v212, 0
	v_mov_b32_e32 v213, 0
	v_mov_b32_e32 v214, 0
	v_mov_b32_e32 v220, 0xff7fffff
	v_mov_b32_e32 v221, 0
	s_mov_b64 s[26:27], -1
	v_and_b32_e32 v216, 31, v0
	v_bfe_u32 v217, v0, 5, 1
	s_lshl_b32 s36, s11, 5
	v_add_u32_e32 v222, s36, v216
	v_subrev_u32_e32 v223, 8, v222
	v_med3_i32 v223, v223, 0, 48
	v_lshl_add_u32 v224, v217, 2, s36
	v_sub_u32_e32 v224, v224, v223
	v_add_u32_e32 v225, 0, v224
	v_cmp_gt_u32_e32 vcc, 16, v225
	v_cndmask_b32_e32 v114, v229, v228, vcc
	v_add_u32_e32 v225, 1, v224
	v_cmp_gt_u32_e32 vcc, 16, v225
	v_cndmask_b32_e32 v115, v229, v228, vcc
	v_add_u32_e32 v225, 2, v224
	v_cmp_gt_u32_e32 vcc, 16, v225
	v_cndmask_b32_e32 v116, v229, v228, vcc
	v_add_u32_e32 v225, 3, v224
	v_cmp_gt_u32_e32 vcc, 16, v225
	v_cndmask_b32_e32 v117, v229, v228, vcc
	v_add_u32_e32 v225, 8, v224
	v_cmp_gt_u32_e32 vcc, 16, v225
	v_cndmask_b32_e32 v118, v229, v228, vcc
	v_add_u32_e32 v225, 9, v224
	v_cmp_gt_u32_e32 vcc, 16, v225
	v_cndmask_b32_e32 v119, v229, v228, vcc
	v_add_u32_e32 v225, 10, v224
	v_cmp_gt_u32_e32 vcc, 16, v225
	v_cndmask_b32_e32 v120, v229, v228, vcc
	v_add_u32_e32 v225, 11, v224
	v_cmp_gt_u32_e32 vcc, 16, v225
	v_cndmask_b32_e32 v121, v229, v228, vcc
	v_add_u32_e32 v225, 16, v224
	v_cmp_gt_u32_e32 vcc, 16, v225
	v_cndmask_b32_e32 v122, v229, v228, vcc
	v_add_u32_e32 v225, 17, v224
	v_cmp_gt_u32_e32 vcc, 16, v225
	v_cndmask_b32_e32 v123, v229, v228, vcc
	v_add_u32_e32 v225, 18, v224
	v_cmp_gt_u32_e32 vcc, 16, v225
	v_cndmask_b32_e32 v124, v229, v228, vcc
	v_add_u32_e32 v225, 19, v224
	v_cmp_gt_u32_e32 vcc, 16, v225
	v_cndmask_b32_e32 v125, v229, v228, vcc
	v_add_u32_e32 v225, 24, v224
	v_cmp_gt_u32_e32 vcc, 16, v225
	v_cndmask_b32_e32 v126, v229, v228, vcc
	v_add_u32_e32 v225, 25, v224
	v_cmp_gt_u32_e32 vcc, 16, v225
	v_cndmask_b32_e32 v127, v229, v228, vcc
	v_add_u32_e32 v225, 26, v224
	v_cmp_gt_u32_e32 vcc, 16, v225
	v_cndmask_b32_e32 v128, v229, v228, vcc
	v_add_u32_e32 v225, 27, v224
	v_cmp_gt_u32_e32 vcc, 16, v225
	v_cndmask_b32_e32 v129, v229, v228, vcc
	s_cmp_eq_u32 s11, 0
	s_cselect_b32 s37, 32, 24
	v_lshl_add_u32 v224, v217, 2, s37
	v_sub_u32_e32 v224, v224, v223
	v_add_u32_e32 v225, 0, v224
	v_cmp_gt_u32_e32 vcc, 16, v225
	v_cndmask_b32_e32 v130, v229, v228, vcc
	v_add_u32_e32 v225, 1, v224
	v_cmp_gt_u32_e32 vcc, 16, v225
	v_cndmask_b32_e32 v131, v229, v228, vcc
	v_add_u32_e32 v225, 2, v224
	v_cmp_gt_u32_e32 vcc, 16, v225
	v_cndmask_b32_e32 v132, v229, v228, vcc
	v_add_u32_e32 v225, 3, v224
	v_cmp_gt_u32_e32 vcc, 16, v225
	v_cndmask_b32_e32 v133, v229, v228, vcc
	v_mov_b32_e32 v134, 0
	v_mov_b32_e32 v135, 0
	v_mov_b32_e32 v136, 0
	v_mov_b32_e32 v137, 0
	v_mov_b32_e32 v138, 0
	v_mov_b32_e32 v139, 0
	v_mov_b32_e32 v140, 0
	v_mov_b32_e32 v141, 0
	v_mov_b32_e32 v142, 0
	v_mov_b32_e32 v143, 0
	v_mov_b32_e32 v144, 0
	v_mov_b32_e32 v145, 0
	s_waitcnt vmcnt(2)
	ds_write_b128 v204, v[146:149]
	s_waitcnt lgkmcnt(0)
	s_barrier
	s_mov_b32 s24, -1
	s_lshr_b32 s33, s22, 1
.Lna_wloop:
	s_sub_i32 s36, s24, s23
	s_cmp_lt_u32 s36, 8
	s_cselect_b64 s[40:41], -1, 0
	s_add_i32 s36, s36, 1
	s_cmp_lt_u32 s36, 8
	s_cselect_b64 s[42:43], -1, 0
	s_and_b64 s[44:45], s[40:41], s[42:43]
	s_cmp_eq_u64 s[44:45], 0
	s_cbranch_scc1 .Lna_slow_w1
	ds_read_b128 v[146:149], v199 offset:0
	ds_read_b128 v[150:153], v200 offset:0
	ds_read_b128 v[154:157], v199 offset:32
	ds_read_b128 v[158:161], v200 offset:32
	v_add_u32_e32 v210, s25, v208
	v_add_u32_e32 v211, s25, v209
	v_exp_f32_e32 v66, v66
	v_exp_f32_e32 v67, v67
	v_exp_f32_e32 v68, v68
	v_exp_f32_e32 v69, v69
	s_waitcnt lgkmcnt(3)
	v_mfma_f32_32x32x16_bf16 v[34:49], v[146:149], v[98:101], v[114:129]
	ds_read_b128 v[146:149], v199 offset:64
	v_add_f32_e32 v213, v213, v66
	v_add_f32_e32 v214, v214, v67
	v_add_f32_e32 v213, v213, v68
	v_add_f32_e32 v214, v214, v69
	v_exp_f32_e32 v70, v70
	v_exp_f32_e32 v71, v71
	s_waitcnt lgkmcnt(3)
	v_mfma_f32_32x32x16_bf16 v[50:65], v[150:153], v[98:101], v[130:145]
	ds_read_b128 v[150:153], v200 offset:64
	v_exp_f32_e32 v72, v72
	v_exp_f32_e32 v73, v73
	v_add_f32_e32 v213, v213, v70
	v_add_f32_e32 v214, v214, v71
	s_waitcnt lgkmcnt(3)
	v_mfma_f32_32x32x16_bf16 v[34:49], v[154:157], v[102:105], v[34:49]
	ds_read_b128 v[154:157], v199 offset:96
	v_add_f32_e32 v213, v213, v72
	v_add_f32_e32 v214, v214, v73
	v_cvt_pk_bf16_f32 v66, v66, v67
	v_cvt_pk_bf16_f32 v67, v68, v69
	v_cvt_pk_bf16_f32 v68, v70, v71
	v_cvt_pk_bf16_f32 v69, v72, v73
	v_exp_f32_e32 v74, v74
	s_waitcnt lgkmcnt(3)
	v_mfma_f32_32x32x16_bf16 v[50:65], v[158:161], v[102:105], v[50:65]
	ds_read_b128 v[158:161], v200 offset:96
	v_exp_f32_e32 v75, v75
	v_exp_f32_e32 v76, v76
	v_exp_f32_e32 v77, v77
	s_waitcnt lgkmcnt(3)
	v_mfma_f32_32x32x16_bf16 v[34:49], v[146:149], v[106:109], v[34:49]
	ds_read_b64 v[162:163], v201 offset:8704
	ds_read_b64 v[164:165], v201 offset:8720
	v_add_f32_e32 v213, v213, v74
	v_add_f32_e32 v214, v214, v75
	v_add_f32_e32 v213, v213, v76
	v_add_f32_e32 v214, v214, v77
	v_exp_f32_e32 v78, v78
	v_exp_f32_e32 v79, v79
	s_waitcnt lgkmcnt(4)
	v_mfma_f32_32x32x16_bf16 v[50:65], v[150:153], v[106:109], v[50:65]
	ds_read_b64 v[166:167], v201 offset:13056
	ds_read_b64 v[168:169], v201 offset:13072
	v_exp_f32_e32 v80, v80
	v_exp_f32_e32 v81, v81
	v_add_f32_e32 v213, v213, v78
	v_add_f32_e32 v214, v214, v79
	s_waitcnt lgkmcnt(5)
	v_mfma_f32_32x32x16_bf16 v[34:49], v[154:157], v[110:113], v[34:49]
	ds_read_b64 v[170:171], v201 offset:8736
	ds_read_b64 v[172:173], v201 offset:8752
	v_add_f32_e32 v213, v213, v80
	v_add_f32_e32 v214, v214, v81
	v_cvt_pk_bf16_f32 v74, v74, v75
	v_cvt_pk_bf16_f32 v75, v76, v77
	v_cvt_pk_bf16_f32 v76, v78, v79
	v_cvt_pk_bf16_f32 v77, v80, v81
	v_exp_f32_e32 v82, v82
	s_waitcnt lgkmcnt(6)
	v_mfma_f32_32x32x16_bf16 v[50:65], v[158:161], v[110:113], v[50:65]
	ds_read_b64 v[174:175], v201 offset:13088
	ds_read_b64 v[176:177], v201 offset:13104
	ds_read_b128 v[146:149], v210 offset:0
	ds_read_b128 v[150:153], v210 offset:32
	ds_read_b128 v[154:157], v210 offset:64
	ds_read_b128 v[158:161], v210 offset:96
	ds_read_b128 v[180:183], v211
	v_exp_f32_e32 v83, v83
	v_exp_f32_e32 v84, v84
	v_exp_f32_e32 v85, v85
	s_waitcnt lgkmcnt(11)
	s_nop 1
	v_mfma_f32_32x32x16_bf16 v[2:17], v[162:165], v[66:69], v[2:17]
	ds_read_b64 v[162:163], v202 offset:8704
	ds_read_b64 v[164:165], v203 offset:8704
	v_add_f32_e32 v213, v213, v82
	v_add_f32_e32 v214, v214, v83
	v_add_f32_e32 v213, v213, v84
	v_add_f32_e32 v214, v214, v85
	v_cvt_pk_bf16_f32 v184, v82, v83
	v_cvt_pk_bf16_f32 v185, v84, v85
	s_waitcnt lgkmcnt(11)
	v_mfma_f32_32x32x16_bf16 v[18:33], v[166:169], v[66:69], v[18:33]
	ds_read_b64 v[166:167], v202 offset:13056
	ds_read_b64 v[168:169], v203 offset:13056
	s_waitcnt lgkmcnt(4)
	v_add_f32_e32 v34, v34, v146
	v_add_f32_e32 v35, v35, v147
	v_add_f32_e32 v36, v36, v148
	v_add_f32_e32 v37, v37, v149
	v_add_f32_e32 v38, v38, v150
	v_add_f32_e32 v39, v39, v151
	v_add_f32_e32 v40, v40, v152
	v_add_f32_e32 v41, v41, v153
	v_mfma_f32_32x32x16_bf16 v[2:17], v[170:173], v[74:77], v[2:17]
	v_add_f32_e32 v42, v42, v154
	v_add_f32_e32 v43, v43, v155
	v_add_f32_e32 v44, v44, v156
	v_add_f32_e32 v45, v45, v157
	v_add_f32_e32 v46, v46, v158
	v_add_f32_e32 v47, v47, v159
	v_add_f32_e32 v48, v48, v160
	v_mfma_f32_32x32x16_bf16 v[18:33], v[174:177], v[74:77], v[18:33]
	s_waitcnt vmcnt(0)
	ds_write_b128 v204, v[188:191] offset:9216
	ds_write_b64 v205, v[192:193] offset:0
	ds_write_b64 v205, v[194:195] offset:8
	global_load_dwordx4 v[188:191], v206, s[12:13]
	s_add_i32 s20, s20, 1
	s_add_u32 s12, s12, 0x2000
	s_addc_u32 s13, s13, 0
	s_cmp_eq_u32 s20, s22
	s_cselect_b32 s12, s16, s12
	s_cselect_b32 s13, s17, s13
	global_load_dwordx4 v[192:195], v207, s[14:15]
	s_add_i32 s21, s21, 1
	s_add_u32 s14, s14, 0x80
	s_addc_u32 s15, s15, 0
	s_cmp_eq_u32 s21, s22
	s_cselect_b32 s14, s18, s14
	s_cselect_b32 s15, s19, s15
	v_add_f32_e32 v49, v49, v161
	v_add_f32_e32 v50, v50, v180
	v_add_f32_e32 v51, v51, v181
	v_add_f32_e32 v52, v52, v182
	v_add_f32_e32 v53, v53, v183
	v_max3_f32 v216, v34, v35, v36
	v_max3_f32 v217, v44, v45, v46
	s_waitcnt lgkmcnt(5)
	v_mfma_f32_32x32x16_bf16 v[2:17], v[162:165], v[184:187], v[2:17]
	v_max3_f32 v216, v216, v37, v38
	v_max3_f32 v217, v217, v47, v48
	v_max3_f32 v216, v216, v39, v40
	v_max3_f32 v217, v217, v49, v50
	v_max3_f32 v216, v216, v41, v42
	v_max3_f32 v217, v217, v51, v52
	v_max_f32_e32 v216, v216, v43
	s_waitcnt lgkmcnt(3)
	v_mfma_f32_32x32x16_bf16 v[18:33], v[166:169], v[184:187], v[18:33]
	v_max_f32_e32 v217, v217, v53
	v_max_f32_e32 v216, v216, v217
	v_mov_b32_e32 v217, v216
	s_nop 1
	v_permlane32_swap_b32_e32 v216, v217
	v_max_f32_e32 v215, v216, v217
	v_cmp_lt_f32_e32 vcc, 4.0, v215
	s_or_b64 s[28:29], vcc, s[26:27]
	s_cmp_lg_u64 s[28:29], 0
	s_cbranch_scc0 .Lna_nr_w1f
	s_nop 15
	v_max_f32_e32 v216, v215, v220
	v_exp_f32_e64 v217, -v216
	v_add_f32_e32 v212, v212, v216
	v_and_b32_e32 v217, v217, v221
	v_sub_f32_e32 v34, v34, v216
	v_sub_f32_e32 v35, v35, v216
	v_sub_f32_e32 v36, v36, v216
	v_sub_f32_e32 v37, v37, v216
	v_sub_f32_e32 v38, v38, v216
	v_sub_f32_e32 v39, v39, v216
	v_sub_f32_e32 v40, v40, v216
	v_sub_f32_e32 v41, v41, v216
	v_sub_f32_e32 v42, v42, v216
	v_sub_f32_e32 v43, v43, v216
	v_sub_f32_e32 v44, v44, v216
	v_sub_f32_e32 v45, v45, v216
	v_sub_f32_e32 v46, v46, v216
	v_sub_f32_e32 v47, v47, v216
	v_sub_f32_e32 v48, v48, v216
	v_sub_f32_e32 v49, v49, v216
	v_sub_f32_e32 v50, v50, v216
	v_sub_f32_e32 v51, v51, v216
	v_sub_f32_e32 v52, v52, v216
	v_sub_f32_e32 v53, v53, v216
	v_sub_f32_e32 v114, v114, v216
	v_sub_f32_e32 v115, v115, v216
	v_sub_f32_e32 v116, v116, v216
	v_sub_f32_e32 v117, v117, v216
	v_sub_f32_e32 v118, v118, v216
	v_sub_f32_e32 v119, v119, v216
	v_sub_f32_e32 v120, v120, v216
	v_sub_f32_e32 v121, v121, v216
	v_sub_f32_e32 v122, v122, v216
	v_sub_f32_e32 v123, v123, v216
	v_sub_f32_e32 v124, v124, v216
	v_sub_f32_e32 v125, v125, v216
	v_sub_f32_e32 v126, v126, v216
	v_sub_f32_e32 v127, v127, v216
	v_sub_f32_e32 v128, v128, v216
	v_sub_f32_e32 v129, v129, v216
	v_sub_f32_e32 v130, v130, v216
	v_sub_f32_e32 v131, v131, v216
	v_sub_f32_e32 v132, v132, v216
	v_sub_f32_e32 v133, v133, v216
	v_mul_f32_e32 v213, v213, v217
	v_mul_f32_e32 v214, v214, v217
	v_mul_f32_e32 v2, v2, v217
	v_mul_f32_e32 v3, v3, v217
	v_mul_f32_e32 v4, v4, v217
	v_mul_f32_e32 v5, v5, v217
	v_mul_f32_e32 v6, v6, v217
	v_mul_f32_e32 v7, v7, v217
	v_mul_f32_e32 v8, v8, v217
	v_mul_f32_e32 v9, v9, v217
	v_mul_f32_e32 v10, v10, v217
	v_mul_f32_e32 v11, v11, v217
	v_mul_f32_e32 v12, v12, v217
	v_mul_f32_e32 v13, v13, v217
	v_mul_f32_e32 v14, v14, v217
	v_mul_f32_e32 v15, v15, v217
	v_mul_f32_e32 v16, v16, v217
	v_mul_f32_e32 v17, v17, v217
	v_mul_f32_e32 v18, v18, v217
	v_mul_f32_e32 v19, v19, v217
	v_mul_f32_e32 v20, v20, v217
	v_mul_f32_e32 v21, v21, v217
	v_mul_f32_e32 v22, v22, v217
	v_mul_f32_e32 v23, v23, v217
	v_mul_f32_e32 v24, v24, v217
	v_mul_f32_e32 v25, v25, v217
	v_mul_f32_e32 v26, v26, v217
	v_mul_f32_e32 v27, v27, v217
	v_mul_f32_e32 v28, v28, v217
	v_mul_f32_e32 v29, v29, v217
	v_mul_f32_e32 v30, v30, v217
	v_mul_f32_e32 v31, v31, v217
	v_mul_f32_e32 v32, v32, v217
	v_mul_f32_e32 v33, v33, v217
	v_mov_b32_e32 v220, 0
	v_mov_b32_e32 v221, -1
	s_mov_b64 s[26:27], 0
.Lna_nr_w1f:
	s_waitcnt lgkmcnt(0)
	s_barrier
	s_branch .Lna_done_w1
.Lna_slow_w1:
	s_cmp_eq_u64 s[40:41], 0
	s_cbranch_scc1 .Lna_sl_a_w1s
	ds_read_b64 v[162:163], v201 offset:8704
	ds_read_b64 v[164:165], v201 offset:8720
	ds_read_b64 v[166:167], v201 offset:13056
	ds_read_b64 v[168:169], v201 offset:13072
	ds_read_b64 v[170:171], v201 offset:8736
	ds_read_b64 v[172:173], v201 offset:8752
	ds_read_b64 v[174:175], v201 offset:13088
	ds_read_b64 v[176:177], v201 offset:13104
	v_exp_f32_e32 v66, v66
	v_exp_f32_e32 v67, v67
	v_exp_f32_e32 v68, v68
	v_exp_f32_e32 v69, v69
	v_add_f32_e32 v213, v213, v66
	v_add_f32_e32 v214, v214, v67
	v_add_f32_e32 v213, v213, v68
	v_add_f32_e32 v214, v214, v69
	v_exp_f32_e32 v70, v70
	v_exp_f32_e32 v71, v71
	v_exp_f32_e32 v72, v72
	v_exp_f32_e32 v73, v73
	v_add_f32_e32 v213, v213, v70
	v_add_f32_e32 v214, v214, v71
	v_add_f32_e32 v213, v213, v72
	v_add_f32_e32 v214, v214, v73
	v_cvt_pk_bf16_f32 v66, v66, v67
	v_cvt_pk_bf16_f32 v67, v68, v69
	v_cvt_pk_bf16_f32 v68, v70, v71
	v_cvt_pk_bf16_f32 v69, v72, v73
	v_exp_f32_e32 v74, v74
	v_exp_f32_e32 v75, v75
	v_exp_f32_e32 v76, v76
	v_exp_f32_e32 v77, v77
	v_add_f32_e32 v213, v213, v74
	v_add_f32_e32 v214, v214, v75
	v_add_f32_e32 v213, v213, v76
	v_add_f32_e32 v214, v214, v77
	v_exp_f32_e32 v78, v78
	v_exp_f32_e32 v79, v79
	v_exp_f32_e32 v80, v80
	v_exp_f32_e32 v81, v81
	v_add_f32_e32 v213, v213, v78
	v_add_f32_e32 v214, v214, v79
	v_add_f32_e32 v213, v213, v80
	v_add_f32_e32 v214, v214, v81
	v_cvt_pk_bf16_f32 v74, v74, v75
	v_cvt_pk_bf16_f32 v75, v76, v77
	v_cvt_pk_bf16_f32 v76, v78, v79
	v_cvt_pk_bf16_f32 v77, v80, v81
	v_exp_f32_e32 v82, v82
	v_exp_f32_e32 v83, v83
	v_exp_f32_e32 v84, v84
	v_exp_f32_e32 v85, v85
	v_add_f32_e32 v213, v213, v82
	v_add_f32_e32 v214, v214, v83
	v_add_f32_e32 v213, v213, v84
	v_add_f32_e32 v214, v214, v85
	v_cvt_pk_bf16_f32 v184, v82, v83
	v_cvt_pk_bf16_f32 v185, v84, v85
	s_nop 1
	s_waitcnt lgkmcnt(6)
	v_mfma_f32_32x32x16_bf16 v[2:17], v[162:165], v[66:69], v[2:17]
	ds_read_b64 v[162:163], v202 offset:8704
	ds_read_b64 v[164:165], v203 offset:8704
	s_waitcnt lgkmcnt(6)
	v_mfma_f32_32x32x16_bf16 v[18:33], v[166:169], v[66:69], v[18:33]
	ds_read_b64 v[166:167], v202 offset:13056
	ds_read_b64 v[168:169], v203 offset:13056
	s_waitcnt lgkmcnt(6)
	v_mfma_f32_32x32x16_bf16 v[2:17], v[170:173], v[74:77], v[2:17]
	s_waitcnt lgkmcnt(4)
	v_mfma_f32_32x32x16_bf16 v[18:33], v[174:177], v[74:77], v[18:33]
	s_waitcnt lgkmcnt(2)
	v_mfma_f32_32x32x16_bf16 v[2:17], v[162:165], v[184:187], v[2:17]
	s_waitcnt lgkmcnt(0)
	v_mfma_f32_32x32x16_bf16 v[18:33], v[166:169], v[184:187], v[18:33]
.Lna_sl_a_w1s:
	s_waitcnt lgkmcnt(0)
	s_cmp_eq_u64 s[42:43], 0
	s_cbranch_scc1 .Lna_sl_b_w1s
	ds_read_b128 v[146:149], v199 offset:0
	ds_read_b128 v[150:153], v200 offset:0
	ds_read_b128 v[154:157], v199 offset:32
	ds_read_b128 v[158:161], v200 offset:32
	ds_read_b128 v[162:165], v199 offset:64
	ds_read_b128 v[166:169], v200 offset:64
	ds_read_b128 v[170:173], v199 offset:96
	ds_read_b128 v[174:177], v200 offset:96
	s_waitcnt lgkmcnt(7)
	v_mfma_f32_32x32x16_bf16 v[34:49], v[146:149], v[98:101], v[114:129]
	s_waitcnt lgkmcnt(6)
	v_mfma_f32_32x32x16_bf16 v[50:65], v[150:153], v[98:101], v[130:145]
	s_waitcnt lgkmcnt(5)
	v_mfma_f32_32x32x16_bf16 v[34:49], v[154:157], v[102:105], v[34:49]
	s_waitcnt lgkmcnt(4)
	v_mfma_f32_32x32x16_bf16 v[50:65], v[158:161], v[102:105], v[50:65]
	s_waitcnt lgkmcnt(3)
	v_mfma_f32_32x32x16_bf16 v[34:49], v[162:165], v[106:109], v[34:49]
	s_waitcnt lgkmcnt(2)
	v_mfma_f32_32x32x16_bf16 v[50:65], v[166:169], v[106:109], v[50:65]
	s_waitcnt lgkmcnt(1)
	v_mfma_f32_32x32x16_bf16 v[34:49], v[170:173], v[110:113], v[34:49]
	s_waitcnt lgkmcnt(0)
	v_mfma_f32_32x32x16_bf16 v[50:65], v[174:177], v[110:113], v[50:65]
	v_add_u32_e32 v210, s25, v208
	v_add_u32_e32 v211, s25, v209
	ds_read_b128 v[146:149], v210 offset:0
	ds_read_b128 v[150:153], v210 offset:32
	ds_read_b128 v[154:157], v210 offset:64
	ds_read_b128 v[158:161], v210 offset:96
	ds_read_b128 v[180:183], v211
	s_waitcnt lgkmcnt(0)
	s_nop 15
	v_add_f32_e32 v34, v34, v146
	v_add_f32_e32 v35, v35, v147
	v_add_f32_e32 v36, v36, v148
	v_add_f32_e32 v37, v37, v149
	v_add_f32_e32 v38, v38, v150
	v_add_f32_e32 v39, v39, v151
	v_add_f32_e32 v40, v40, v152
	v_add_f32_e32 v41, v41, v153
	v_add_f32_e32 v42, v42, v154
	v_add_f32_e32 v43, v43, v155
	v_add_f32_e32 v44, v44, v156
	v_add_f32_e32 v45, v45, v157
	v_add_f32_e32 v46, v46, v158
	v_add_f32_e32 v47, v47, v159
	v_add_f32_e32 v48, v48, v160
	v_add_f32_e32 v49, v49, v161
	v_add_f32_e32 v50, v50, v180
	v_add_f32_e32 v51, v51, v181
	v_add_f32_e32 v52, v52, v182
	v_add_f32_e32 v53, v53, v183
	v_max3_f32 v216, v34, v35, v36
	v_max3_f32 v217, v44, v45, v46
	v_max3_f32 v216, v216, v37, v38
	v_max3_f32 v217, v217, v47, v48
	v_max3_f32 v216, v216, v39, v40
	v_max3_f32 v217, v217, v49, v50
	v_max3_f32 v216, v216, v41, v42
	v_max3_f32 v217, v217, v51, v52
	v_max_f32_e32 v216, v216, v43
	v_max_f32_e32 v217, v217, v53
	v_max_f32_e32 v216, v216, v217
	v_mov_b32_e32 v217, v216
	s_nop 1
	v_permlane32_swap_b32_e32 v216, v217
	v_max_f32_e32 v215, v216, v217
	v_cmp_lt_f32_e32 vcc, 4.0, v215
	s_or_b64 s[28:29], vcc, s[26:27]
	s_cmp_lg_u64 s[28:29], 0
	s_cbranch_scc0 .Lna_nr_w1s
	s_nop 15
	v_max_f32_e32 v216, v215, v220
	v_exp_f32_e64 v217, -v216
	v_add_f32_e32 v212, v212, v216
	v_and_b32_e32 v217, v217, v221
	v_sub_f32_e32 v34, v34, v216
	v_sub_f32_e32 v35, v35, v216
	v_sub_f32_e32 v36, v36, v216
	v_sub_f32_e32 v37, v37, v216
	v_sub_f32_e32 v38, v38, v216
	v_sub_f32_e32 v39, v39, v216
	v_sub_f32_e32 v40, v40, v216
	v_sub_f32_e32 v41, v41, v216
	v_sub_f32_e32 v42, v42, v216
	v_sub_f32_e32 v43, v43, v216
	v_sub_f32_e32 v44, v44, v216
	v_sub_f32_e32 v45, v45, v216
	v_sub_f32_e32 v46, v46, v216
	v_sub_f32_e32 v47, v47, v216
	v_sub_f32_e32 v48, v48, v216
	v_sub_f32_e32 v49, v49, v216
	v_sub_f32_e32 v50, v50, v216
	v_sub_f32_e32 v51, v51, v216
	v_sub_f32_e32 v52, v52, v216
	v_sub_f32_e32 v53, v53, v216
	v_sub_f32_e32 v114, v114, v216
	v_sub_f32_e32 v115, v115, v216
	v_sub_f32_e32 v116, v116, v216
	v_sub_f32_e32 v117, v117, v216
	v_sub_f32_e32 v118, v118, v216
	v_sub_f32_e32 v119, v119, v216
	v_sub_f32_e32 v120, v120, v216
	v_sub_f32_e32 v121, v121, v216
	v_sub_f32_e32 v122, v122, v216
	v_sub_f32_e32 v123, v123, v216
	v_sub_f32_e32 v124, v124, v216
	v_sub_f32_e32 v125, v125, v216
	v_sub_f32_e32 v126, v126, v216
	v_sub_f32_e32 v127, v127, v216
	v_sub_f32_e32 v128, v128, v216
	v_sub_f32_e32 v129, v129, v216
	v_sub_f32_e32 v130, v130, v216
	v_sub_f32_e32 v131, v131, v216
	v_sub_f32_e32 v132, v132, v216
	v_sub_f32_e32 v133, v133, v216
	v_mul_f32_e32 v213, v213, v217
	v_mul_f32_e32 v214, v214, v217
	v_mul_f32_e32 v2, v2, v217
	v_mul_f32_e32 v3, v3, v217
	v_mul_f32_e32 v4, v4, v217
	v_mul_f32_e32 v5, v5, v217
	v_mul_f32_e32 v6, v6, v217
	v_mul_f32_e32 v7, v7, v217
	v_mul_f32_e32 v8, v8, v217
	v_mul_f32_e32 v9, v9, v217
	v_mul_f32_e32 v10, v10, v217
	v_mul_f32_e32 v11, v11, v217
	v_mul_f32_e32 v12, v12, v217
	v_mul_f32_e32 v13, v13, v217
	v_mul_f32_e32 v14, v14, v217
	v_mul_f32_e32 v15, v15, v217
	v_mul_f32_e32 v16, v16, v217
	v_mul_f32_e32 v17, v17, v217
	v_mul_f32_e32 v18, v18, v217
	v_mul_f32_e32 v19, v19, v217
	v_mul_f32_e32 v20, v20, v217
	v_mul_f32_e32 v21, v21, v217
	v_mul_f32_e32 v22, v22, v217
	v_mul_f32_e32 v23, v23, v217
	v_mul_f32_e32 v24, v24, v217
	v_mul_f32_e32 v25, v25, v217
	v_mul_f32_e32 v26, v26, v217
	v_mul_f32_e32 v27, v27, v217
	v_mul_f32_e32 v28, v28, v217
	v_mul_f32_e32 v29, v29, v217
	v_mul_f32_e32 v30, v30, v217
	v_mul_f32_e32 v31, v31, v217
	v_mul_f32_e32 v32, v32, v217
	v_mul_f32_e32 v33, v33, v217
	v_mov_b32_e32 v220, 0
	v_mov_b32_e32 v221, -1
	s_mov_b64 s[26:27], 0
.Lna_nr_w1s:
.Lna_sl_b_w1s:
	s_waitcnt vmcnt(0)
	ds_write_b128 v204, v[188:191] offset:9216
	ds_write_b64 v205, v[192:193] offset:0
	ds_write_b64 v205, v[194:195] offset:8
	global_load_dwordx4 v[188:191], v206, s[12:13]
	s_add_i32 s20, s20, 1
	s_add_u32 s12, s12, 0x2000
	s_addc_u32 s13, s13, 0
	s_cmp_eq_u32 s20, s22
	s_cselect_b32 s12, s16, s12
	s_cselect_b32 s13, s17, s13
	global_load_dwordx4 v[192:195], v207, s[14:15]
	s_add_i32 s21, s21, 1
	s_add_u32 s14, s14, 0x80
	s_addc_u32 s15, s15, 0
	s_cmp_eq_u32 s21, s22
	s_cselect_b32 s14, s18, s14
	s_cselect_b32 s15, s19, s15
	s_waitcnt lgkmcnt(0)
	s_barrier
.Lna_done_w1:
	s_add_i32 s24, s24, 1
	s_add_i32 s25, s25, 0x150
	s_sub_i32 s36, s24, s23
	s_cmp_lt_u32 s36, 8
	s_cselect_b64 s[40:41], -1, 0
	s_add_i32 s36, s36, 1
	s_cmp_lt_u32 s36, 8
	s_cselect_b64 s[42:43], -1, 0
	s_and_b64 s[44:45], s[40:41], s[42:43]
	s_cmp_eq_u64 s[44:45], 0
	s_cbranch_scc1 .Lna_slow_w0
	ds_read_b128 v[146:149], v199 offset:9216
	ds_read_b128 v[150:153], v200 offset:9216
	ds_read_b128 v[154:157], v199 offset:9248
	ds_read_b128 v[158:161], v200 offset:9248
	v_add_u32_e32 v210, s25, v208
	v_add_u32_e32 v211, s25, v209
	v_exp_f32_e32 v34, v34
	v_exp_f32_e32 v35, v35
	v_exp_f32_e32 v36, v36
	v_exp_f32_e32 v37, v37
	s_waitcnt lgkmcnt(3)
	v_mfma_f32_32x32x16_bf16 v[66:81], v[146:149], v[98:101], v[114:129]
	ds_read_b128 v[146:149], v199 offset:9280
	v_add_f32_e32 v213, v213, v34
	v_add_f32_e32 v214, v214, v35
	v_add_f32_e32 v213, v213, v36
	v_add_f32_e32 v214, v214, v37
	v_exp_f32_e32 v38, v38
	v_exp_f32_e32 v39, v39
	s_waitcnt lgkmcnt(3)
	v_mfma_f32_32x32x16_bf16 v[82:97], v[150:153], v[98:101], v[130:145]
	ds_read_b128 v[150:153], v200 offset:9280
	v_exp_f32_e32 v40, v40
	v_exp_f32_e32 v41, v41
	v_add_f32_e32 v213, v213, v38
	v_add_f32_e32 v214, v214, v39
	s_waitcnt lgkmcnt(3)
	v_mfma_f32_32x32x16_bf16 v[66:81], v[154:157], v[102:105], v[66:81]
	ds_read_b128 v[154:157], v199 offset:9312
	v_add_f32_e32 v213, v213, v40
	v_add_f32_e32 v214, v214, v41
	v_cvt_pk_bf16_f32 v34, v34, v35
	v_cvt_pk_bf16_f32 v35, v36, v37
	v_cvt_pk_bf16_f32 v36, v38, v39
	v_cvt_pk_bf16_f32 v37, v40, v41
	v_exp_f32_e32 v42, v42
	s_waitcnt lgkmcnt(3)
	v_mfma_f32_32x32x16_bf16 v[82:97], v[158:161], v[102:105], v[82:97]
	ds_read_b128 v[158:161], v200 offset:9312
	v_exp_f32_e32 v43, v43
	v_exp_f32_e32 v44, v44
	v_exp_f32_e32 v45, v45
	s_waitcnt lgkmcnt(3)
	v_mfma_f32_32x32x16_bf16 v[66:81], v[146:149], v[106:109], v[66:81]
	ds_read_b64 v[162:163], v201 offset:0
	ds_read_b64 v[164:165], v201 offset:16
	v_add_f32_e32 v213, v213, v42
	v_add_f32_e32 v214, v214, v43
	v_add_f32_e32 v213, v213, v44
	v_add_f32_e32 v214, v214, v45
	v_exp_f32_e32 v46, v46
	v_exp_f32_e32 v47, v47
	s_waitcnt lgkmcnt(4)
	v_mfma_f32_32x32x16_bf16 v[82:97], v[150:153], v[106:109], v[82:97]
	ds_read_b64 v[166:167], v201 offset:4352
	ds_read_b64 v[168:169], v201 offset:4368
	v_exp_f32_e32 v48, v48
	v_exp_f32_e32 v49, v49
	v_add_f32_e32 v213, v213, v46
	v_add_f32_e32 v214, v214, v47
	s_waitcnt lgkmcnt(5)
	v_mfma_f32_32x32x16_bf16 v[66:81], v[154:157], v[110:113], v[66:81]
	ds_read_b64 v[170:171], v201 offset:32
	ds_read_b64 v[172:173], v201 offset:48
	v_add_f32_e32 v213, v213, v48
	v_add_f32_e32 v214, v214, v49
	v_cvt_pk_bf16_f32 v42, v42, v43
	v_cvt_pk_bf16_f32 v43, v44, v45
	v_cvt_pk_bf16_f32 v44, v46, v47
	v_cvt_pk_bf16_f32 v45, v48, v49
	v_exp_f32_e32 v50, v50
	s_waitcnt lgkmcnt(6)
	v_mfma_f32_32x32x16_bf16 v[82:97], v[158:161], v[110:113], v[82:97]
	ds_read_b64 v[174:175], v201 offset:4384
	ds_read_b64 v[176:177], v201 offset:4400
	ds_read_b128 v[146:149], v210 offset:0
	ds_read_b128 v[150:153], v210 offset:32
	ds_read_b128 v[154:157], v210 offset:64
	ds_read_b128 v[158:161], v210 offset:96
	ds_read_b128 v[180:183], v211
	v_exp_f32_e32 v51, v51
	v_exp_f32_e32 v52, v52
	v_exp_f32_e32 v53, v53
	s_waitcnt lgkmcnt(11)
	s_nop 1
	v_mfma_f32_32x32x16_bf16 v[2:17], v[162:165], v[34:37], v[2:17]
	ds_read_b64 v[162:163], v202 offset:0
	ds_read_b64 v[164:165], v203 offset:0
	v_add_f32_e32 v213, v213, v50
	v_add_f32_e32 v214, v214, v51
	v_add_f32_e32 v213, v213, v52
	v_add_f32_e32 v214, v214, v53
	v_cvt_pk_bf16_f32 v184, v50, v51
	v_cvt_pk_bf16_f32 v185, v52, v53
	s_waitcnt lgkmcnt(11)
	v_mfma_f32_32x32x16_bf16 v[18:33], v[166:169], v[34:37], v[18:33]
	ds_read_b64 v[166:167], v202 offset:4352
	ds_read_b64 v[168:169], v203 offset:4352
	s_waitcnt lgkmcnt(4)
	v_add_f32_e32 v66, v66, v146
	v_add_f32_e32 v67, v67, v147
	v_add_f32_e32 v68, v68, v148
	v_add_f32_e32 v69, v69, v149
	v_add_f32_e32 v70, v70, v150
	v_add_f32_e32 v71, v71, v151
	v_add_f32_e32 v72, v72, v152
	v_add_f32_e32 v73, v73, v153
	v_mfma_f32_32x32x16_bf16 v[2:17], v[170:173], v[42:45], v[2:17]
	v_add_f32_e32 v74, v74, v154
	v_add_f32_e32 v75, v75, v155
	v_add_f32_e32 v76, v76, v156
	v_add_f32_e32 v77, v77, v157
	v_add_f32_e32 v78, v78, v158
	v_add_f32_e32 v79, v79, v159
	v_add_f32_e32 v80, v80, v160
	v_mfma_f32_32x32x16_bf16 v[18:33], v[174:177], v[42:45], v[18:33]
	s_waitcnt vmcnt(0)
	ds_write_b128 v204, v[188:191] offset:0
	ds_write_b64 v205, v[192:193] offset:8704
	ds_write_b64 v205, v[194:195] offset:8712
	global_load_dwordx4 v[188:191], v206, s[12:13]
	s_add_i32 s20, s20, 1
	s_add_u32 s12, s12, 0x2000
	s_addc_u32 s13, s13, 0
	s_cmp_eq_u32 s20, s22
	s_cselect_b32 s12, s16, s12
	s_cselect_b32 s13, s17, s13
	global_load_dwordx4 v[192:195], v207, s[14:15]
	s_add_i32 s21, s21, 1
	s_add_u32 s14, s14, 0x80
	s_addc_u32 s15, s15, 0
	s_cmp_eq_u32 s21, s22
	s_cselect_b32 s14, s18, s14
	s_cselect_b32 s15, s19, s15
	v_add_f32_e32 v81, v81, v161
	v_add_f32_e32 v82, v82, v180
	v_add_f32_e32 v83, v83, v181
	v_add_f32_e32 v84, v84, v182
	v_add_f32_e32 v85, v85, v183
	v_max3_f32 v216, v66, v67, v68
	v_max3_f32 v217, v76, v77, v78
	s_waitcnt lgkmcnt(5)
	v_mfma_f32_32x32x16_bf16 v[2:17], v[162:165], v[184:187], v[2:17]
	v_max3_f32 v216, v216, v69, v70
	v_max3_f32 v217, v217, v79, v80
	v_max3_f32 v216, v216, v71, v72
	v_max3_f32 v217, v217, v81, v82
	v_max3_f32 v216, v216, v73, v74
	v_max3_f32 v217, v217, v83, v84
	v_max_f32_e32 v216, v216, v75
	s_waitcnt lgkmcnt(3)
	v_mfma_f32_32x32x16_bf16 v[18:33], v[166:169], v[184:187], v[18:33]
	v_max_f32_e32 v217, v217, v85
	v_max_f32_e32 v216, v216, v217
	v_mov_b32_e32 v217, v216
	s_nop 1
	v_permlane32_swap_b32_e32 v216, v217
	v_max_f32_e32 v215, v216, v217
	v_cmp_lt_f32_e32 vcc, 4.0, v215
	s_or_b64 s[28:29], vcc, s[26:27]
	s_cmp_lg_u64 s[28:29], 0
	s_cbranch_scc0 .Lna_nr_w0f
	s_nop 15
	v_max_f32_e32 v216, v215, v220
	v_exp_f32_e64 v217, -v216
	v_add_f32_e32 v212, v212, v216
	v_and_b32_e32 v217, v217, v221
	v_sub_f32_e32 v66, v66, v216
	v_sub_f32_e32 v67, v67, v216
	v_sub_f32_e32 v68, v68, v216
	v_sub_f32_e32 v69, v69, v216
	v_sub_f32_e32 v70, v70, v216
	v_sub_f32_e32 v71, v71, v216
	v_sub_f32_e32 v72, v72, v216
	v_sub_f32_e32 v73, v73, v216
	v_sub_f32_e32 v74, v74, v216
	v_sub_f32_e32 v75, v75, v216
	v_sub_f32_e32 v76, v76, v216
	v_sub_f32_e32 v77, v77, v216
	v_sub_f32_e32 v78, v78, v216
	v_sub_f32_e32 v79, v79, v216
	v_sub_f32_e32 v80, v80, v216
	v_sub_f32_e32 v81, v81, v216
	v_sub_f32_e32 v82, v82, v216
	v_sub_f32_e32 v83, v83, v216
	v_sub_f32_e32 v84, v84, v216
	v_sub_f32_e32 v85, v85, v216
	v_sub_f32_e32 v114, v114, v216
	v_sub_f32_e32 v115, v115, v216
	v_sub_f32_e32 v116, v116, v216
	v_sub_f32_e32 v117, v117, v216
	v_sub_f32_e32 v118, v118, v216
	v_sub_f32_e32 v119, v119, v216
	v_sub_f32_e32 v120, v120, v216
	v_sub_f32_e32 v121, v121, v216
	v_sub_f32_e32 v122, v122, v216
	v_sub_f32_e32 v123, v123, v216
	v_sub_f32_e32 v124, v124, v216
	v_sub_f32_e32 v125, v125, v216
	v_sub_f32_e32 v126, v126, v216
	v_sub_f32_e32 v127, v127, v216
	v_sub_f32_e32 v128, v128, v216
	v_sub_f32_e32 v129, v129, v216
	v_sub_f32_e32 v130, v130, v216
	v_sub_f32_e32 v131, v131, v216
	v_sub_f32_e32 v132, v132, v216
	v_sub_f32_e32 v133, v133, v216
	v_mul_f32_e32 v213, v213, v217
	v_mul_f32_e32 v214, v214, v217
	v_mul_f32_e32 v2, v2, v217
	v_mul_f32_e32 v3, v3, v217
	v_mul_f32_e32 v4, v4, v217
	v_mul_f32_e32 v5, v5, v217
	v_mul_f32_e32 v6, v6, v217
	v_mul_f32_e32 v7, v7, v217
	v_mul_f32_e32 v8, v8, v217
	v_mul_f32_e32 v9, v9, v217
	v_mul_f32_e32 v10, v10, v217
	v_mul_f32_e32 v11, v11, v217
	v_mul_f32_e32 v12, v12, v217
	v_mul_f32_e32 v13, v13, v217
	v_mul_f32_e32 v14, v14, v217
	v_mul_f32_e32 v15, v15, v217
	v_mul_f32_e32 v16, v16, v217
	v_mul_f32_e32 v17, v17, v217
	v_mul_f32_e32 v18, v18, v217
	v_mul_f32_e32 v19, v19, v217
	v_mul_f32_e32 v20, v20, v217
	v_mul_f32_e32 v21, v21, v217
	v_mul_f32_e32 v22, v22, v217
	v_mul_f32_e32 v23, v23, v217
	v_mul_f32_e32 v24, v24, v217
	v_mul_f32_e32 v25, v25, v217
	v_mul_f32_e32 v26, v26, v217
	v_mul_f32_e32 v27, v27, v217
	v_mul_f32_e32 v28, v28, v217
	v_mul_f32_e32 v29, v29, v217
	v_mul_f32_e32 v30, v30, v217
	v_mul_f32_e32 v31, v31, v217
	v_mul_f32_e32 v32, v32, v217
	v_mul_f32_e32 v33, v33, v217
	v_mov_b32_e32 v220, 0
	v_mov_b32_e32 v221, -1
	s_mov_b64 s[26:27], 0

.Lna_slow_w0:
	s_cmp_eq_u64 s[40:41], 0
	s_cbranch_scc1 .Lna_sl_a_w0s
	ds_read_b64 v[162:163], v201 offset:0
	ds_read_b64 v[164:165], v201 offset:16
	ds_read_b64 v[166:167], v201 offset:4352
	ds_read_b64 v[168:169], v201 offset:4368
	ds_read_b64 v[170:171], v201 offset:32
	ds_read_b64 v[172:173], v201 offset:48
	ds_read_b64 v[174:175], v201 offset:4384
	ds_read_b64 v[176:177], v201 offset:4400
	v_exp_f32_e32 v34, v34
	v_exp_f32_e32 v35, v35
	v_exp_f32_e32 v36, v36
	v_exp_f32_e32 v37, v37
	v_add_f32_e32 v213, v213, v34
	v_add_f32_e32 v214, v214, v35
	v_add_f32_e32 v213, v213, v36
	v_add_f32_e32 v214, v214, v37
	v_exp_f32_e32 v38, v38
	v_exp_f32_e32 v39, v39
	v_exp_f32_e32 v40, v40
	v_exp_f32_e32 v41, v41
	v_add_f32_e32 v213, v213, v38
	v_add_f32_e32 v214, v214, v39
	v_add_f32_e32 v213, v213, v40
	v_add_f32_e32 v214, v214, v41
	v_cvt_pk_bf16_f32 v34, v34, v35
	v_cvt_pk_bf16_f32 v35, v36, v37
	v_cvt_pk_bf16_f32 v36, v38, v39
	v_cvt_pk_bf16_f32 v37, v40, v41
	v_exp_f32_e32 v42, v42
	v_exp_f32_e32 v43, v43
	v_exp_f32_e32 v44, v44
	v_exp_f32_e32 v45, v45
	v_add_f32_e32 v213, v213, v42
	v_add_f32_e32 v214, v214, v43
	v_add_f32_e32 v213, v213, v44
	v_add_f32_e32 v214, v214, v45
	v_exp_f32_e32 v46, v46
	v_exp_f32_e32 v47, v47
	v_exp_f32_e32 v48, v48
	v_exp_f32_e32 v49, v49
	v_add_f32_e32 v213, v213, v46
	v_add_f32_e32 v214, v214, v47
	v_add_f32_e32 v213, v213, v48
	v_add_f32_e32 v214, v214, v49
	v_cvt_pk_bf16_f32 v42, v42, v43
	v_cvt_pk_bf16_f32 v43, v44, v45
	v_cvt_pk_bf16_f32 v44, v46, v47
	v_cvt_pk_bf16_f32 v45, v48, v49
	v_exp_f32_e32 v50, v50
	v_exp_f32_e32 v51, v51
	v_exp_f32_e32 v52, v52
	v_exp_f32_e32 v53, v53
	v_add_f32_e32 v213, v213, v50
	v_add_f32_e32 v214, v214, v51
	v_add_f32_e32 v213, v213, v52
	v_add_f32_e32 v214, v214, v53
	v_cvt_pk_bf16_f32 v184, v50, v51
	v_cvt_pk_bf16_f32 v185, v52, v53
	s_nop 1
	s_waitcnt lgkmcnt(6)
	v_mfma_f32_32x32x16_bf16 v[2:17], v[162:165], v[34:37], v[2:17]
	ds_read_b64 v[162:163], v202 offset:0
	ds_read_b64 v[164:165], v203 offset:0
	s_waitcnt lgkmcnt(6)
	v_mfma_f32_32x32x16_bf16 v[18:33], v[166:169], v[34:37], v[18:33]
	ds_read_b64 v[166:167], v202 offset:4352
	ds_read_b64 v[168:169], v203 offset:4352
	s_waitcnt lgkmcnt(6)
	v_mfma_f32_32x32x16_bf16 v[2:17], v[170:173], v[42:45], v[2:17]
	s_waitcnt lgkmcnt(4)
	v_mfma_f32_32x32x16_bf16 v[18:33], v[174:177], v[42:45], v[18:33]
	s_waitcnt lgkmcnt(2)
	v_mfma_f32_32x32x16_bf16 v[2:17], v[162:165], v[184:187], v[2:17]
	s_waitcnt lgkmcnt(0)
	v_mfma_f32_32x32x16_bf16 v[18:33], v[166:169], v[184:187], v[18:33]
.Lna_sl_a_w0s:
	s_waitcnt lgkmcnt(0)
	s_cmp_eq_u64 s[42:43], 0
	s_cbranch_scc1 .Lna_sl_b_w0s
	ds_read_b128 v[146:149], v199 offset:9216
	ds_read_b128 v[150:153], v200 offset:9216
	ds_read_b128 v[154:157], v199 offset:9248
	ds_read_b128 v[158:161], v200 offset:9248
	ds_read_b128 v[162:165], v199 offset:9280
	ds_read_b128 v[166:169], v200 offset:9280
	ds_read_b128 v[170:173], v199 offset:9312
	ds_read_b128 v[174:177], v200 offset:9312
	s_waitcnt lgkmcnt(7)
	v_mfma_f32_32x32x16_bf16 v[66:81], v[146:149], v[98:101], v[114:129]
	s_waitcnt lgkmcnt(6)
	v_mfma_f32_32x32x16_bf16 v[82:97], v[150:153], v[98:101], v[130:145]
	s_waitcnt lgkmcnt(5)
	v_mfma_f32_32x32x16_bf16 v[66:81], v[154:157], v[102:105], v[66:81]
	s_waitcnt lgkmcnt(4)
	v_mfma_f32_32x32x16_bf16 v[82:97], v[158:161], v[102:105], v[82:97]
	s_waitcnt lgkmcnt(3)
	v_mfma_f32_32x32x16_bf16 v[66:81], v[162:165], v[106:109], v[66:81]
	s_waitcnt lgkmcnt(2)
	v_mfma_f32_32x32x16_bf16 v[82:97], v[166:169], v[106:109], v[82:97]
	s_waitcnt lgkmcnt(1)
	v_mfma_f32_32x32x16_bf16 v[66:81], v[170:173], v[110:113], v[66:81]
	s_waitcnt lgkmcnt(0)
	v_mfma_f32_32x32x16_bf16 v[82:97], v[174:177], v[110:113], v[82:97]
	v_add_u32_e32 v210, s25, v208
	v_add_u32_e32 v211, s25, v209
	ds_read_b128 v[146:149], v210 offset:0
	ds_read_b128 v[150:153], v210 offset:32
	ds_read_b128 v[154:157], v210 offset:64
	ds_read_b128 v[158:161], v210 offset:96
	ds_read_b128 v[180:183], v211
	s_waitcnt lgkmcnt(0)
	s_nop 15
	v_add_f32_e32 v66, v66, v146
	v_add_f32_e32 v67, v67, v147
	v_add_f32_e32 v68, v68, v148
	v_add_f32_e32 v69, v69, v149
	v_add_f32_e32 v70, v70, v150
	v_add_f32_e32 v71, v71, v151
	v_add_f32_e32 v72, v72, v152
	v_add_f32_e32 v73, v73, v153
	v_add_f32_e32 v74, v74, v154
	v_add_f32_e32 v75, v75, v155
	v_add_f32_e32 v76, v76, v156
	v_add_f32_e32 v77, v77, v157
	v_add_f32_e32 v78, v78, v158
	v_add_f32_e32 v79, v79, v159
	v_add_f32_e32 v80, v80, v160
	v_add_f32_e32 v81, v81, v161
	v_add_f32_e32 v82, v82, v180
	v_add_f32_e32 v83, v83, v181
	v_add_f32_e32 v84, v84, v182
	v_add_f32_e32 v85, v85, v183
	v_max3_f32 v216, v66, v67, v68
	v_max3_f32 v217, v76, v77, v78
	v_max3_f32 v216, v216, v69, v70
	v_max3_f32 v217, v217, v79, v80
	v_max3_f32 v216, v216, v71, v72
	v_max3_f32 v217, v217, v81, v82
	v_max3_f32 v216, v216, v73, v74
	v_max3_f32 v217, v217, v83, v84
	v_max_f32_e32 v216, v216, v75
	v_max_f32_e32 v217, v217, v85
	v_max_f32_e32 v216, v216, v217
	v_mov_b32_e32 v217, v216
	s_nop 1
	v_permlane32_swap_b32_e32 v216, v217
	v_max_f32_e32 v215, v216, v217
	v_cmp_lt_f32_e32 vcc, 4.0, v215
	s_or_b64 s[28:29], vcc, s[26:27]
	s_cmp_lg_u64 s[28:29], 0
	s_cbranch_scc0 .Lna_nr_w0s
	s_nop 15
	v_max_f32_e32 v216, v215, v220
	v_exp_f32_e64 v217, -v216
	v_add_f32_e32 v212, v212, v216
	v_and_b32_e32 v217, v217, v221
	v_sub_f32_e32 v66, v66, v216
	v_sub_f32_e32 v67, v67, v216
	v_sub_f32_e32 v68, v68, v216
	v_sub_f32_e32 v69, v69, v216
	v_sub_f32_e32 v70, v70, v216
	v_sub_f32_e32 v71, v71, v216
	v_sub_f32_e32 v72, v72, v216
	v_sub_f32_e32 v73, v73, v216
	v_sub_f32_e32 v74, v74, v216
	v_sub_f32_e32 v75, v75, v216
	v_sub_f32_e32 v76, v76, v216
	v_sub_f32_e32 v77, v77, v216
	v_sub_f32_e32 v78, v78, v216
	v_sub_f32_e32 v79, v79, v216
	v_sub_f32_e32 v80, v80, v216
	v_sub_f32_e32 v81, v81, v216
	v_sub_f32_e32 v82, v82, v216
	v_sub_f32_e32 v83, v83, v216
	v_sub_f32_e32 v84, v84, v216
	v_sub_f32_e32 v85, v85, v216
	v_sub_f32_e32 v114, v114, v216
	v_sub_f32_e32 v115, v115, v216
	v_sub_f32_e32 v116, v116, v216
	v_sub_f32_e32 v117, v117, v216
	v_sub_f32_e32 v118, v118, v216
	v_sub_f32_e32 v119, v119, v216
	v_sub_f32_e32 v120, v120, v216
	v_sub_f32_e32 v121, v121, v216
	v_sub_f32_e32 v122, v122, v216
	v_sub_f32_e32 v123, v123, v216
	v_sub_f32_e32 v124, v124, v216
	v_sub_f32_e32 v125, v125, v216
	v_sub_f32_e32 v126, v126, v216
	v_sub_f32_e32 v127, v127, v216
	v_sub_f32_e32 v128, v128, v216
	v_sub_f32_e32 v129, v129, v216
	v_sub_f32_e32 v130, v130, v216
	v_sub_f32_e32 v131, v131, v216
	v_sub_f32_e32 v132, v132, v216
	v_sub_f32_e32 v133, v133, v216
	v_mul_f32_e32 v213, v213, v217
	v_mul_f32_e32 v214, v214, v217
	v_mul_f32_e32 v2, v2, v217
	v_mul_f32_e32 v3, v3, v217
	v_mul_f32_e32 v4, v4, v217
	v_mul_f32_e32 v5, v5, v217
	v_mul_f32_e32 v6, v6, v217
	v_mul_f32_e32 v7, v7, v217
	v_mul_f32_e32 v8, v8, v217
	v_mul_f32_e32 v9, v9, v217
	v_mul_f32_e32 v10, v10, v217
	v_mul_f32_e32 v11, v11, v217
	v_mul_f32_e32 v12, v12, v217
	v_mul_f32_e32 v13, v13, v217
	v_mul_f32_e32 v14, v14, v217
	v_mul_f32_e32 v15, v15, v217
	v_mul_f32_e32 v16, v16, v217
	v_mul_f32_e32 v17, v17, v217
	v_mul_f32_e32 v18, v18, v217
	v_mul_f32_e32 v19, v19, v217
	v_mul_f32_e32 v20, v20, v217
	v_mul_f32_e32 v21, v21, v217
	v_mul_f32_e32 v22, v22, v217
	v_mul_f32_e32 v23, v23, v217
	v_mul_f32_e32 v24, v24, v217
	v_mul_f32_e32 v25, v25, v217
	v_mul_f32_e32 v26, v26, v217
	v_mul_f32_e32 v27, v27, v217
	v_mul_f32_e32 v28, v28, v217
	v_mul_f32_e32 v29, v29, v217
	v_mul_f32_e32 v30, v30, v217
	v_mul_f32_e32 v31, v31, v217
	v_mul_f32_e32 v32, v32, v217
	v_mul_f32_e32 v33, v33, v217
	v_mov_b32_e32 v220, 0
	v_mov_b32_e32 v221, -1
	s_mov_b64 s[26:27], 0
.Lna_nr_w0s:
.Lna_sl_b_w0s:
	s_waitcnt vmcnt(0)
	ds_write_b128 v204, v[188:191] offset:0
	ds_write_b64 v205, v[192:193] offset:8704
	ds_write_b64 v205, v[194:195] offset:8712
	global_load_dwordx4 v[188:191], v206, s[12:13]
	s_add_i32 s20, s20, 1
	s_add_u32 s12, s12, 0x2000
	s_addc_u32 s13, s13, 0
	s_cmp_eq_u32 s20, s22
	s_cselect_b32 s12, s16, s12
	s_cselect_b32 s13, s17, s13
	global_load_dwordx4 v[192:195], v207, s[14:15]
	s_add_i32 s21, s21, 1
	s_add_u32 s14, s14, 0x80
	s_addc_u32 s15, s15, 0
	s_cmp_eq_u32 s21, s22
	s_cselect_b32 s14, s18, s14
	s_cselect_b32 s15, s19, s15
	s_waitcnt lgkmcnt(0)
	s_barrier
.Lna_done_w0:
	s_add_i32 s24, s24, 1
	s_add_i32 s25, s25, 0x150
	s_add_i32 s33, s33, -1
	s_cmp_lg_u32 s33, 0
	s_cbranch_scc1 .Lna_wloop
	v_sub_f32_e32 v114, 0, v212
	v_mov_b32_e32 v115, v114
	v_mov_b32_e32 v116, v114
	v_mov_b32_e32 v117, v114
	v_mov_b32_e32 v118, v114
	v_mov_b32_e32 v119, v114
	v_mov_b32_e32 v120, v114
	v_mov_b32_e32 v121, v114
	v_mov_b32_e32 v122, v114
	v_mov_b32_e32 v123, v114
	v_mov_b32_e32 v124, v114
	v_mov_b32_e32 v125, v114
	v_mov_b32_e32 v126, v114
	v_mov_b32_e32 v127, v114
	v_mov_b32_e32 v128, v114
	v_mov_b32_e32 v129, v114
	v_mov_b32_e32 v130, v114
	v_mov_b32_e32 v131, v114
	v_mov_b32_e32 v132, v114
	v_mov_b32_e32 v133, v114
	v_mov_b32_e32 v134, v114
	v_mov_b32_e32 v135, v114
	v_mov_b32_e32 v136, v114
	v_mov_b32_e32 v137, v114
	v_mov_b32_e32 v138, v114
	v_mov_b32_e32 v139, v114
	v_mov_b32_e32 v140, v114
	v_mov_b32_e32 v141, v114
	v_mov_b32_e32 v142, v114
	v_mov_b32_e32 v143, v114
	v_mov_b32_e32 v144, v114
	v_mov_b32_e32 v145, v114
	s_sub_i32 s36, s24, s23
	s_cmp_lt_u32 s36, 8
	s_cselect_b64 s[40:41], -1, 0
	s_mov_b64 s[42:43], -1
	s_cmp_eq_u64 s[40:41], 0
	s_cbranch_scc1 .Lna_slow_wc
	ds_read_b128 v[146:149], v199 offset:0
	ds_read_b128 v[150:153], v200 offset:0
	ds_read_b128 v[154:157], v199 offset:32
	ds_read_b128 v[158:161], v200 offset:32
	v_exp_f32_e32 v66, v66
	v_exp_f32_e32 v67, v67
	v_exp_f32_e32 v68, v68
	v_exp_f32_e32 v69, v69
	s_waitcnt lgkmcnt(3)
	v_mfma_f32_32x32x16_bf16 v[34:49], v[146:149], v[98:101], v[114:129]
	ds_read_b128 v[146:149], v199 offset:64
	v_add_f32_e32 v213, v213, v66
	v_add_f32_e32 v214, v214, v67
	v_add_f32_e32 v213, v213, v68
	v_add_f32_e32 v214, v214, v69
	v_exp_f32_e32 v70, v70
	s_waitcnt lgkmcnt(3)
	v_mfma_f32_32x32x16_bf16 v[50:65], v[150:153], v[98:101], v[130:145]
	ds_read_b128 v[150:153], v200 offset:64
	v_exp_f32_e32 v71, v71
	v_exp_f32_e32 v72, v72
	v_exp_f32_e32 v73, v73
	s_waitcnt lgkmcnt(3)
	v_mfma_f32_32x32x16_bf16 v[34:49], v[154:157], v[102:105], v[34:49]
	ds_read_b128 v[154:157], v199 offset:96
	v_add_f32_e32 v213, v213, v70
	v_add_f32_e32 v214, v214, v71
	v_add_f32_e32 v213, v213, v72
	v_add_f32_e32 v214, v214, v73
	v_cvt_pk_bf16_f32 v66, v66, v67
	s_waitcnt lgkmcnt(3)
	v_mfma_f32_32x32x16_bf16 v[50:65], v[158:161], v[102:105], v[50:65]
	ds_read_b128 v[158:161], v200 offset:96
	v_cvt_pk_bf16_f32 v67, v68, v69
	v_cvt_pk_bf16_f32 v68, v70, v71
	v_cvt_pk_bf16_f32 v69, v72, v73
	v_exp_f32_e32 v74, v74
	v_exp_f32_e32 v75, v75
	s_waitcnt lgkmcnt(3)
	v_mfma_f32_32x32x16_bf16 v[34:49], v[146:149], v[106:109], v[34:49]
	ds_read_b64 v[162:163], v201 offset:8704
	ds_read_b64 v[164:165], v201 offset:8720
	v_exp_f32_e32 v76, v76
	v_exp_f32_e32 v77, v77
	v_add_f32_e32 v213, v213, v74
	s_waitcnt lgkmcnt(4)
	v_mfma_f32_32x32x16_bf16 v[50:65], v[150:153], v[106:109], v[50:65]
	ds_read_b64 v[166:167], v201 offset:13056
	ds_read_b64 v[168:169], v201 offset:13072
	v_add_f32_e32 v214, v214, v75
	v_add_f32_e32 v213, v213, v76
	v_add_f32_e32 v214, v214, v77
	v_exp_f32_e32 v78, v78
	v_exp_f32_e32 v79, v79
	s_waitcnt lgkmcnt(5)
	v_mfma_f32_32x32x16_bf16 v[34:49], v[154:157], v[110:113], v[34:49]
	ds_read_b64 v[170:171], v201 offset:8736
	ds_read_b64 v[172:173], v201 offset:8752
	v_exp_f32_e32 v80, v80
	v_exp_f32_e32 v81, v81
	v_add_f32_e32 v213, v213, v78
	v_add_f32_e32 v214, v214, v79
	s_waitcnt lgkmcnt(6)
	v_mfma_f32_32x32x16_bf16 v[50:65], v[158:161], v[110:113], v[50:65]
	ds_read_b64 v[174:175], v201 offset:13088
	ds_read_b64 v[176:177], v201 offset:13104
	v_add_f32_e32 v213, v213, v80
	v_add_f32_e32 v214, v214, v81
	v_cvt_pk_bf16_f32 v74, v74, v75
	v_cvt_pk_bf16_f32 v75, v76, v77
	v_cvt_pk_bf16_f32 v76, v78, v79
	v_cvt_pk_bf16_f32 v77, v80, v81
	s_waitcnt lgkmcnt(6)
	s_nop 1
	v_mfma_f32_32x32x16_bf16 v[2:17], v[162:165], v[66:69], v[2:17]
	ds_read_b64 v[162:163], v202 offset:8704
	ds_read_b64 v[164:165], v203 offset:8704
	v_exp_f32_e32 v82, v82
	v_exp_f32_e32 v83, v83
	v_exp_f32_e32 v84, v84
	s_waitcnt lgkmcnt(6)
	v_mfma_f32_32x32x16_bf16 v[18:33], v[166:169], v[66:69], v[18:33]
	ds_read_b64 v[166:167], v202 offset:13056
	ds_read_b64 v[168:169], v203 offset:13056
	v_exp_f32_e32 v85, v85
	v_add_f32_e32 v213, v213, v82
	v_add_f32_e32 v214, v214, v83
	v_add_f32_e32 v213, v213, v84
	v_add_f32_e32 v214, v214, v85
	s_waitcnt lgkmcnt(6)
	v_mfma_f32_32x32x16_bf16 v[2:17], v[170:173], v[74:77], v[2:17]
	v_cvt_pk_bf16_f32 v184, v82, v83
	v_cvt_pk_bf16_f32 v185, v84, v85
	v_max3_f32 v216, v34, v35, v36
	v_max3_f32 v217, v50, v51, v52
	v_max3_f32 v216, v216, v37, v38
	v_max3_f32 v217, v217, v53, v54
	s_waitcnt lgkmcnt(4)
	v_mfma_f32_32x32x16_bf16 v[18:33], v[174:177], v[74:77], v[18:33]
	s_waitcnt vmcnt(0)
	ds_write_b128 v204, v[188:191] offset:9216
	ds_write_b64 v205, v[192:193] offset:0
	ds_write_b64 v205, v[194:195] offset:8
	global_load_dwordx4 v[188:191], v206, s[12:13]
	s_add_u32 s12, s12, 0x2000
	s_addc_u32 s13, s13, 0
	global_load_dwordx4 v[192:195], v207, s[14:15]
	s_add_u32 s14, s14, 0x80
	s_addc_u32 s15, s15, 0
	v_max3_f32 v216, v216, v39, v40
	v_max3_f32 v217, v217, v55, v56
	v_max3_f32 v216, v216, v41, v42
	v_max3_f32 v217, v217, v57, v58
	v_max3_f32 v216, v216, v43, v44
	v_max3_f32 v217, v217, v59, v60
	s_waitcnt lgkmcnt(5)
	v_mfma_f32_32x32x16_bf16 v[2:17], v[162:165], v[184:187], v[2:17]
	v_max3_f32 v216, v216, v45, v46
	v_max3_f32 v217, v217, v61, v62
	v_max3_f32 v216, v216, v47, v48
	v_max3_f32 v217, v217, v63, v64
	v_max_f32_e32 v216, v216, v49
	v_max_f32_e32 v217, v217, v65
	s_waitcnt lgkmcnt(3)
	v_mfma_f32_32x32x16_bf16 v[18:33], v[166:169], v[184:187], v[18:33]
	v_max_f32_e32 v216, v216, v217
	v_mov_b32_e32 v217, v216
	s_nop 1
	v_permlane32_swap_b32_e32 v216, v217
	v_max_f32_e32 v215, v216, v217
	v_cmp_lt_f32_e32 vcc, 4.0, v215
	s_cbranch_vccz .Lna_nr_wcf
	s_nop 15
	v_max_f32_e32 v216, v215, v220
	v_exp_f32_e64 v217, -v216
	v_add_f32_e32 v212, v212, v216
	v_and_b32_e32 v217, v217, v221
	v_sub_f32_e32 v34, v34, v216
	v_sub_f32_e32 v35, v35, v216
	v_sub_f32_e32 v36, v36, v216
	v_sub_f32_e32 v37, v37, v216
	v_sub_f32_e32 v38, v38, v216
	v_sub_f32_e32 v39, v39, v216
	v_sub_f32_e32 v40, v40, v216
	v_sub_f32_e32 v41, v41, v216
	v_sub_f32_e32 v42, v42, v216
	v_sub_f32_e32 v43, v43, v216
	v_sub_f32_e32 v44, v44, v216
	v_sub_f32_e32 v45, v45, v216
	v_sub_f32_e32 v46, v46, v216
	v_sub_f32_e32 v47, v47, v216
	v_sub_f32_e32 v48, v48, v216
	v_sub_f32_e32 v49, v49, v216
	v_sub_f32_e32 v50, v50, v216
	v_sub_f32_e32 v51, v51, v216
	v_sub_f32_e32 v52, v52, v216
	v_sub_f32_e32 v53, v53, v216
	v_sub_f32_e32 v54, v54, v216
	v_sub_f32_e32 v55, v55, v216
	v_sub_f32_e32 v56, v56, v216
	v_sub_f32_e32 v57, v57, v216
	v_sub_f32_e32 v58, v58, v216
	v_sub_f32_e32 v59, v59, v216
	v_sub_f32_e32 v60, v60, v216
	v_sub_f32_e32 v61, v61, v216
	v_sub_f32_e32 v62, v62, v216
	v_sub_f32_e32 v63, v63, v216
	v_sub_f32_e32 v64, v64, v216
	v_sub_f32_e32 v65, v65, v216
	v_sub_f32_e32 v114, v114, v216
	v_sub_f32_e32 v115, v115, v216
	v_sub_f32_e32 v116, v116, v216
	v_sub_f32_e32 v117, v117, v216
	v_sub_f32_e32 v118, v118, v216
	v_sub_f32_e32 v119, v119, v216
	v_sub_f32_e32 v120, v120, v216
	v_sub_f32_e32 v121, v121, v216
	v_sub_f32_e32 v122, v122, v216
	v_sub_f32_e32 v123, v123, v216
	v_sub_f32_e32 v124, v124, v216
	v_sub_f32_e32 v125, v125, v216
	v_sub_f32_e32 v126, v126, v216
	v_sub_f32_e32 v127, v127, v216
	v_sub_f32_e32 v128, v128, v216
	v_sub_f32_e32 v129, v129, v216
	v_sub_f32_e32 v130, v130, v216
	v_sub_f32_e32 v131, v131, v216
	v_sub_f32_e32 v132, v132, v216
	v_sub_f32_e32 v133, v133, v216
	v_sub_f32_e32 v134, v134, v216
	v_sub_f32_e32 v135, v135, v216
	v_sub_f32_e32 v136, v136, v216
	v_sub_f32_e32 v137, v137, v216
	v_sub_f32_e32 v138, v138, v216
	v_sub_f32_e32 v139, v139, v216
	v_sub_f32_e32 v140, v140, v216
	v_sub_f32_e32 v141, v141, v216
	v_sub_f32_e32 v142, v142, v216
	v_sub_f32_e32 v143, v143, v216
	v_sub_f32_e32 v144, v144, v216
	v_sub_f32_e32 v145, v145, v216
	v_mul_f32_e32 v213, v213, v217
	v_mul_f32_e32 v214, v214, v217
	v_mul_f32_e32 v2, v2, v217
	v_mul_f32_e32 v3, v3, v217
	v_mul_f32_e32 v4, v4, v217
	v_mul_f32_e32 v5, v5, v217
	v_mul_f32_e32 v6, v6, v217
	v_mul_f32_e32 v7, v7, v217
	v_mul_f32_e32 v8, v8, v217
	v_mul_f32_e32 v9, v9, v217
	v_mul_f32_e32 v10, v10, v217
	v_mul_f32_e32 v11, v11, v217
	v_mul_f32_e32 v12, v12, v217
	v_mul_f32_e32 v13, v13, v217
	v_mul_f32_e32 v14, v14, v217
	v_mul_f32_e32 v15, v15, v217
	v_mul_f32_e32 v16, v16, v217
	v_mul_f32_e32 v17, v17, v217
	v_mul_f32_e32 v18, v18, v217
	v_mul_f32_e32 v19, v19, v217
	v_mul_f32_e32 v20, v20, v217
	v_mul_f32_e32 v21, v21, v217
	v_mul_f32_e32 v22, v22, v217
	v_mul_f32_e32 v23, v23, v217
	v_mul_f32_e32 v24, v24, v217
	v_mul_f32_e32 v25, v25, v217
	v_mul_f32_e32 v26, v26, v217
	v_mul_f32_e32 v27, v27, v217
	v_mul_f32_e32 v28, v28, v217
	v_mul_f32_e32 v29, v29, v217
	v_mul_f32_e32 v30, v30, v217
	v_mul_f32_e32 v31, v31, v217
	v_mul_f32_e32 v32, v32, v217
	v_mul_f32_e32 v33, v33, v217

.Lna_sl_a_wcs:
	s_waitcnt lgkmcnt(0)
	s_cmp_eq_u64 s[42:43], 0
	s_cbranch_scc1 .Lna_sl_b_wcs
	ds_read_b128 v[146:149], v199 offset:0
	ds_read_b128 v[150:153], v200 offset:0
	ds_read_b128 v[154:157], v199 offset:32
	ds_read_b128 v[158:161], v200 offset:32
	ds_read_b128 v[162:165], v199 offset:64
	ds_read_b128 v[166:169], v200 offset:64
	ds_read_b128 v[170:173], v199 offset:96
	ds_read_b128 v[174:177], v200 offset:96
	s_waitcnt lgkmcnt(7)
	v_mfma_f32_32x32x16_bf16 v[34:49], v[146:149], v[98:101], v[114:129]
	s_waitcnt lgkmcnt(6)
	v_mfma_f32_32x32x16_bf16 v[50:65], v[150:153], v[98:101], v[130:145]
	s_waitcnt lgkmcnt(5)
	v_mfma_f32_32x32x16_bf16 v[34:49], v[154:157], v[102:105], v[34:49]
	s_waitcnt lgkmcnt(4)
	v_mfma_f32_32x32x16_bf16 v[50:65], v[158:161], v[102:105], v[50:65]
	s_waitcnt lgkmcnt(3)
	v_mfma_f32_32x32x16_bf16 v[34:49], v[162:165], v[106:109], v[34:49]
	s_waitcnt lgkmcnt(2)
	v_mfma_f32_32x32x16_bf16 v[50:65], v[166:169], v[106:109], v[50:65]
	s_waitcnt lgkmcnt(1)
	v_mfma_f32_32x32x16_bf16 v[34:49], v[170:173], v[110:113], v[34:49]
	s_waitcnt lgkmcnt(0)
	v_mfma_f32_32x32x16_bf16 v[50:65], v[174:177], v[110:113], v[50:65]
	s_nop 15
	v_max3_f32 v216, v34, v35, v36
	v_max3_f32 v217, v50, v51, v52
	v_max3_f32 v216, v216, v37, v38
	v_max3_f32 v217, v217, v53, v54
	v_max3_f32 v216, v216, v39, v40
	v_max3_f32 v217, v217, v55, v56
	v_max3_f32 v216, v216, v41, v42
	v_max3_f32 v217, v217, v57, v58
	v_max3_f32 v216, v216, v43, v44
	v_max3_f32 v217, v217, v59, v60
	v_max3_f32 v216, v216, v45, v46
	v_max3_f32 v217, v217, v61, v62
	v_max3_f32 v216, v216, v47, v48
	v_max3_f32 v217, v217, v63, v64
	v_max_f32_e32 v216, v216, v49
	v_max_f32_e32 v217, v217, v65
	v_max_f32_e32 v216, v216, v217
	v_mov_b32_e32 v217, v216
	s_nop 1
	v_permlane32_swap_b32_e32 v216, v217
	v_max_f32_e32 v215, v216, v217
	v_cmp_lt_f32_e32 vcc, 4.0, v215
	s_cbranch_vccz .Lna_nr_wcs
	s_nop 15
	v_max_f32_e32 v216, v215, v220
	v_exp_f32_e64 v217, -v216
	v_add_f32_e32 v212, v212, v216
	v_and_b32_e32 v217, v217, v221
	v_sub_f32_e32 v34, v34, v216
	v_sub_f32_e32 v35, v35, v216
	v_sub_f32_e32 v36, v36, v216
	v_sub_f32_e32 v37, v37, v216
	v_sub_f32_e32 v38, v38, v216
	v_sub_f32_e32 v39, v39, v216
	v_sub_f32_e32 v40, v40, v216
	v_sub_f32_e32 v41, v41, v216
	v_sub_f32_e32 v42, v42, v216
	v_sub_f32_e32 v43, v43, v216
	v_sub_f32_e32 v44, v44, v216
	v_sub_f32_e32 v45, v45, v216
	v_sub_f32_e32 v46, v46, v216
	v_sub_f32_e32 v47, v47, v216
	v_sub_f32_e32 v48, v48, v216
	v_sub_f32_e32 v49, v49, v216
	v_sub_f32_e32 v50, v50, v216
	v_sub_f32_e32 v51, v51, v216
	v_sub_f32_e32 v52, v52, v216
	v_sub_f32_e32 v53, v53, v216
	v_sub_f32_e32 v54, v54, v216
	v_sub_f32_e32 v55, v55, v216
	v_sub_f32_e32 v56, v56, v216
	v_sub_f32_e32 v57, v57, v216
	v_sub_f32_e32 v58, v58, v216
	v_sub_f32_e32 v59, v59, v216
	v_sub_f32_e32 v60, v60, v216
	v_sub_f32_e32 v61, v61, v216
	v_sub_f32_e32 v62, v62, v216
	v_sub_f32_e32 v63, v63, v216
	v_sub_f32_e32 v64, v64, v216
	v_sub_f32_e32 v65, v65, v216
	v_sub_f32_e32 v114, v114, v216
	v_sub_f32_e32 v115, v115, v216
	v_sub_f32_e32 v116, v116, v216
	v_sub_f32_e32 v117, v117, v216
	v_sub_f32_e32 v118, v118, v216
	v_sub_f32_e32 v119, v119, v216
	v_sub_f32_e32 v120, v120, v216
	v_sub_f32_e32 v121, v121, v216
	v_sub_f32_e32 v122, v122, v216
	v_sub_f32_e32 v123, v123, v216
	v_sub_f32_e32 v124, v124, v216
	v_sub_f32_e32 v125, v125, v216
	v_sub_f32_e32 v126, v126, v216
	v_sub_f32_e32 v127, v127, v216
	v_sub_f32_e32 v128, v128, v216
	v_sub_f32_e32 v129, v129, v216
	v_sub_f32_e32 v130, v130, v216
	v_sub_f32_e32 v131, v131, v216
	v_sub_f32_e32 v132, v132, v216
	v_sub_f32_e32 v133, v133, v216
	v_sub_f32_e32 v134, v134, v216
	v_sub_f32_e32 v135, v135, v216
	v_sub_f32_e32 v136, v136, v216
	v_sub_f32_e32 v137, v137, v216
	v_sub_f32_e32 v138, v138, v216
	v_sub_f32_e32 v139, v139, v216
	v_sub_f32_e32 v140, v140, v216
	v_sub_f32_e32 v141, v141, v216
	v_sub_f32_e32 v142, v142, v216
	v_sub_f32_e32 v143, v143, v216
	v_sub_f32_e32 v144, v144, v216
	v_sub_f32_e32 v145, v145, v216
	v_mul_f32_e32 v213, v213, v217
	v_mul_f32_e32 v214, v214, v217
	v_mul_f32_e32 v2, v2, v217
	v_mul_f32_e32 v3, v3, v217
	v_mul_f32_e32 v4, v4, v217
	v_mul_f32_e32 v5, v5, v217
	v_mul_f32_e32 v6, v6, v217
	v_mul_f32_e32 v7, v7, v217
	v_mul_f32_e32 v8, v8, v217
	v_mul_f32_e32 v9, v9, v217
	v_mul_f32_e32 v10, v10, v217
	v_mul_f32_e32 v11, v11, v217
	v_mul_f32_e32 v12, v12, v217
	v_mul_f32_e32 v13, v13, v217
	v_mul_f32_e32 v14, v14, v217
	v_mul_f32_e32 v15, v15, v217
	v_mul_f32_e32 v16, v16, v217
	v_mul_f32_e32 v17, v17, v217
	v_mul_f32_e32 v18, v18, v217
	v_mul_f32_e32 v19, v19, v217
	v_mul_f32_e32 v20, v20, v217
	v_mul_f32_e32 v21, v21, v217
	v_mul_f32_e32 v22, v22, v217
	v_mul_f32_e32 v23, v23, v217
	v_mul_f32_e32 v24, v24, v217
	v_mul_f32_e32 v25, v25, v217
	v_mul_f32_e32 v26, v26, v217
	v_mul_f32_e32 v27, v27, v217
	v_mul_f32_e32 v28, v28, v217
	v_mul_f32_e32 v29, v29, v217
	v_mul_f32_e32 v30, v30, v217
	v_mul_f32_e32 v31, v31, v217
	v_mul_f32_e32 v32, v32, v217
	v_mul_f32_e32 v33, v33, v217
.Lna_nr_wcs:
.Lna_sl_b_wcs:
	s_waitcnt vmcnt(0)
	ds_write_b128 v204, v[188:191] offset:9216
	ds_write_b64 v205, v[192:193] offset:0
	ds_write_b64 v205, v[194:195] offset:8
	global_load_dwordx4 v[188:191], v206, s[12:13]
	s_add_u32 s12, s12, 0x2000
	s_addc_u32 s13, s13, 0
	global_load_dwordx4 v[192:195], v207, s[14:15]
	s_add_u32 s14, s14, 0x80
	s_addc_u32 s15, s15, 0
	s_waitcnt lgkmcnt(0)
	s_barrier
.Lna_done_wc:
	ds_read_b128 v[146:149], v199 offset:9216
	ds_read_b128 v[150:153], v200 offset:9216
	ds_read_b128 v[154:157], v199 offset:9248
	ds_read_b128 v[158:161], v200 offset:9248
	v_exp_f32_e32 v34, v34
	v_exp_f32_e32 v35, v35
	v_exp_f32_e32 v36, v36
	v_exp_f32_e32 v37, v37
	s_waitcnt lgkmcnt(3)
	v_mfma_f32_32x32x16_bf16 v[66:81], v[146:149], v[98:101], v[114:129]
	ds_read_b128 v[146:149], v199 offset:9280
	v_add_f32_e32 v213, v213, v34
	v_add_f32_e32 v214, v214, v35
	v_add_f32_e32 v213, v213, v36
	v_add_f32_e32 v214, v214, v37
	v_exp_f32_e32 v38, v38
	v_exp_f32_e32 v39, v39
	s_waitcnt lgkmcnt(3)
	v_mfma_f32_32x32x16_bf16 v[82:97], v[150:153], v[98:101], v[130:145]
	ds_read_b128 v[150:153], v200 offset:9280
	v_exp_f32_e32 v40, v40
	v_exp_f32_e32 v41, v41
	v_add_f32_e32 v213, v213, v38
	v_add_f32_e32 v214, v214, v39
	v_add_f32_e32 v213, v213, v40
	v_add_f32_e32 v214, v214, v41
	s_waitcnt lgkmcnt(3)
	v_mfma_f32_32x32x16_bf16 v[66:81], v[154:157], v[102:105], v[66:81]
	ds_read_b128 v[154:157], v199 offset:9312
	v_cvt_pk_bf16_f32 v34, v34, v35
	v_cvt_pk_bf16_f32 v35, v36, v37
	v_cvt_pk_bf16_f32 v36, v38, v39
	v_cvt_pk_bf16_f32 v37, v40, v41
	v_exp_f32_e32 v42, v42
	v_exp_f32_e32 v43, v43
	s_waitcnt lgkmcnt(3)
	v_mfma_f32_32x32x16_bf16 v[82:97], v[158:161], v[102:105], v[82:97]
	ds_read_b128 v[158:161], v200 offset:9312
	v_exp_f32_e32 v44, v44
	v_exp_f32_e32 v45, v45
	v_add_f32_e32 v213, v213, v42
	v_add_f32_e32 v214, v214, v43
	v_add_f32_e32 v213, v213, v44
	v_add_f32_e32 v214, v214, v45
	s_waitcnt lgkmcnt(3)
	v_mfma_f32_32x32x16_bf16 v[66:81], v[146:149], v[106:109], v[66:81]
	ds_read_b64 v[162:163], v201 offset:0
	ds_read_b64 v[164:165], v201 offset:16
	v_exp_f32_e32 v46, v46
	v_exp_f32_e32 v47, v47
	v_exp_f32_e32 v48, v48
	v_exp_f32_e32 v49, v49
	s_waitcnt lgkmcnt(4)
	v_mfma_f32_32x32x16_bf16 v[82:97], v[150:153], v[106:109], v[82:97]
	ds_read_b64 v[166:167], v201 offset:4352
	ds_read_b64 v[168:169], v201 offset:4368
	v_add_f32_e32 v213, v213, v46
	v_add_f32_e32 v214, v214, v47
	v_add_f32_e32 v213, v213, v48
	v_add_f32_e32 v214, v214, v49
	v_cvt_pk_bf16_f32 v42, v42, v43
	v_cvt_pk_bf16_f32 v43, v44, v45
	v_cvt_pk_bf16_f32 v44, v46, v47
	v_cvt_pk_bf16_f32 v45, v48, v49
	s_waitcnt lgkmcnt(5)
	v_mfma_f32_32x32x16_bf16 v[66:81], v[154:157], v[110:113], v[66:81]
	ds_read_b64 v[170:171], v201 offset:32
	ds_read_b64 v[172:173], v201 offset:48
	v_exp_f32_e32 v50, v50
	v_exp_f32_e32 v51, v51
	v_exp_f32_e32 v52, v52
	v_exp_f32_e32 v53, v53
	s_waitcnt lgkmcnt(6)
	v_mfma_f32_32x32x16_bf16 v[82:97], v[158:161], v[110:113], v[82:97]
	ds_read_b64 v[174:175], v201 offset:4384
	ds_read_b64 v[176:177], v201 offset:4400
	v_add_f32_e32 v213, v213, v50
	v_add_f32_e32 v214, v214, v51
	v_add_f32_e32 v213, v213, v52
	v_add_f32_e32 v214, v214, v53
	v_exp_f32_e32 v54, v54
	v_exp_f32_e32 v55, v55
	s_waitcnt lgkmcnt(6)
	s_nop 1
	v_mfma_f32_32x32x16_bf16 v[2:17], v[162:165], v[34:37], v[2:17]
	ds_read_b64 v[162:163], v202 offset:0
	ds_read_b64 v[164:165], v203 offset:0
	v_exp_f32_e32 v56, v56
	v_exp_f32_e32 v57, v57
	v_add_f32_e32 v213, v213, v54
	v_add_f32_e32 v214, v214, v55
	v_add_f32_e32 v213, v213, v56
	s_waitcnt lgkmcnt(6)
	v_mfma_f32_32x32x16_bf16 v[18:33], v[166:169], v[34:37], v[18:33]
	ds_read_b64 v[166:167], v202 offset:4352
	ds_read_b64 v[168:169], v203 offset:4352
	v_add_f32_e32 v214, v214, v57
	v_cvt_pk_bf16_f32 v50, v50, v51
	v_cvt_pk_bf16_f32 v51, v52, v53
	v_cvt_pk_bf16_f32 v52, v54, v55
	v_cvt_pk_bf16_f32 v53, v56, v57
	v_exp_f32_e32 v58, v58
	v_exp_f32_e32 v59, v59
	s_waitcnt lgkmcnt(6)
	v_mfma_f32_32x32x16_bf16 v[2:17], v[170:173], v[42:45], v[2:17]
	ds_read_b64 v[170:171], v203 offset:16
	ds_read_b64 v[172:173], v203 offset:32
	v_exp_f32_e32 v60, v60
	v_exp_f32_e32 v61, v61
	v_add_f32_e32 v213, v213, v58
	v_add_f32_e32 v214, v214, v59
	v_add_f32_e32 v213, v213, v60
	s_waitcnt lgkmcnt(6)
	v_mfma_f32_32x32x16_bf16 v[18:33], v[174:177], v[42:45], v[18:33]
	ds_read_b64 v[174:175], v203 offset:4368
	ds_read_b64 v[176:177], v203 offset:4384
	s_waitcnt vmcnt(0)
	ds_write_b128 v204, v[188:191] offset:0
	ds_write_b64 v205, v[192:193] offset:8704
	ds_write_b64 v205, v[194:195] offset:8712
	global_load_dwordx4 v[188:191], v206, s[12:13]
	s_add_u32 s12, s12, 0x2000
	s_addc_u32 s13, s13, 0
	global_load_dwordx4 v[192:195], v207, s[14:15]
	s_add_u32 s14, s14, 0x80
	s_addc_u32 s15, s15, 0
	v_add_f32_e32 v214, v214, v61
	v_exp_f32_e32 v62, v62
	v_exp_f32_e32 v63, v63
	v_exp_f32_e32 v64, v64
	v_exp_f32_e32 v65, v65
	s_waitcnt lgkmcnt(9)
	v_mfma_f32_32x32x16_bf16 v[2:17], v[162:165], v[50:53], v[2:17]
	v_add_f32_e32 v213, v213, v62
	v_add_f32_e32 v214, v214, v63
	v_add_f32_e32 v213, v213, v64
	v_add_f32_e32 v214, v214, v65
	v_cvt_pk_bf16_f32 v58, v58, v59
	v_cvt_pk_bf16_f32 v59, v60, v61
	v_cvt_pk_bf16_f32 v60, v62, v63
	s_waitcnt lgkmcnt(7)
	v_mfma_f32_32x32x16_bf16 v[18:33], v[166:169], v[50:53], v[18:33]
	v_cvt_pk_bf16_f32 v61, v64, v65
	v_max3_f32 v216, v66, v67, v68
	v_max3_f32 v217, v82, v83, v84
	v_max3_f32 v216, v216, v69, v70
	v_max3_f32 v217, v217, v85, v86
	v_max3_f32 v216, v216, v71, v72
	v_max3_f32 v217, v217, v87, v88
	v_max3_f32 v216, v216, v73, v74
	s_waitcnt lgkmcnt(5)
	v_mfma_f32_32x32x16_bf16 v[2:17], v[170:173], v[58:61], v[2:17]
	v_max3_f32 v217, v217, v89, v90
	v_max3_f32 v216, v216, v75, v76
	v_max3_f32 v217, v217, v91, v92
	v_max3_f32 v216, v216, v77, v78
	v_max3_f32 v217, v217, v93, v94
	v_max3_f32 v216, v216, v79, v80
	v_max3_f32 v217, v217, v95, v96
	v_max_f32_e32 v216, v216, v81
	s_waitcnt lgkmcnt(3)
	v_mfma_f32_32x32x16_bf16 v[18:33], v[174:177], v[58:61], v[18:33]
	v_max_f32_e32 v217, v217, v97
	v_max_f32_e32 v216, v216, v217
	v_mov_b32_e32 v217, v216
	s_nop 1
	v_permlane32_swap_b32_e32 v216, v217
	v_max_f32_e32 v215, v216, v217
	v_cmp_lt_f32_e32 vcc, 4.0, v215
	s_cbranch_vccz .Lna_nr_c0
	s_nop 15
	v_max_f32_e32 v216, v215, v220
	v_exp_f32_e64 v217, -v216
	v_add_f32_e32 v212, v212, v216
	v_and_b32_e32 v217, v217, v221
	v_sub_f32_e32 v66, v66, v216
	v_sub_f32_e32 v67, v67, v216
	v_sub_f32_e32 v68, v68, v216
	v_sub_f32_e32 v69, v69, v216
	v_sub_f32_e32 v70, v70, v216
	v_sub_f32_e32 v71, v71, v216
	v_sub_f32_e32 v72, v72, v216
	v_sub_f32_e32 v73, v73, v216
	v_sub_f32_e32 v74, v74, v216
	v_sub_f32_e32 v75, v75, v216
	v_sub_f32_e32 v76, v76, v216
	v_sub_f32_e32 v77, v77, v216
	v_sub_f32_e32 v78, v78, v216
	v_sub_f32_e32 v79, v79, v216
	v_sub_f32_e32 v80, v80, v216
	v_sub_f32_e32 v81, v81, v216
	v_sub_f32_e32 v82, v82, v216
	v_sub_f32_e32 v83, v83, v216
	v_sub_f32_e32 v84, v84, v216
	v_sub_f32_e32 v85, v85, v216
	v_sub_f32_e32 v86, v86, v216
	v_sub_f32_e32 v87, v87, v216
	v_sub_f32_e32 v88, v88, v216
	v_sub_f32_e32 v89, v89, v216
	v_sub_f32_e32 v90, v90, v216
	v_sub_f32_e32 v91, v91, v216
	v_sub_f32_e32 v92, v92, v216
	v_sub_f32_e32 v93, v93, v216
	v_sub_f32_e32 v94, v94, v216
	v_sub_f32_e32 v95, v95, v216
	v_sub_f32_e32 v96, v96, v216
	v_sub_f32_e32 v97, v97, v216
	v_sub_f32_e32 v114, v114, v216
	v_sub_f32_e32 v115, v115, v216
	v_sub_f32_e32 v116, v116, v216
	v_sub_f32_e32 v117, v117, v216
	v_sub_f32_e32 v118, v118, v216
	v_sub_f32_e32 v119, v119, v216
	v_sub_f32_e32 v120, v120, v216
	v_sub_f32_e32 v121, v121, v216
	v_sub_f32_e32 v122, v122, v216
	v_sub_f32_e32 v123, v123, v216
	v_sub_f32_e32 v124, v124, v216
	v_sub_f32_e32 v125, v125, v216
	v_sub_f32_e32 v126, v126, v216
	v_sub_f32_e32 v127, v127, v216
	v_sub_f32_e32 v128, v128, v216
	v_sub_f32_e32 v129, v129, v216
	v_sub_f32_e32 v130, v130, v216
	v_sub_f32_e32 v131, v131, v216
	v_sub_f32_e32 v132, v132, v216
	v_sub_f32_e32 v133, v133, v216
	v_sub_f32_e32 v134, v134, v216
	v_sub_f32_e32 v135, v135, v216
	v_sub_f32_e32 v136, v136, v216
	v_sub_f32_e32 v137, v137, v216
	v_sub_f32_e32 v138, v138, v216
	v_sub_f32_e32 v139, v139, v216
	v_sub_f32_e32 v140, v140, v216
	v_sub_f32_e32 v141, v141, v216
	v_sub_f32_e32 v142, v142, v216
	v_sub_f32_e32 v143, v143, v216
	v_sub_f32_e32 v144, v144, v216
	v_sub_f32_e32 v145, v145, v216
	v_mul_f32_e32 v213, v213, v217
	v_mul_f32_e32 v214, v214, v217
	v_mul_f32_e32 v2, v2, v217
	v_mul_f32_e32 v3, v3, v217
	v_mul_f32_e32 v4, v4, v217
	v_mul_f32_e32 v5, v5, v217
	v_mul_f32_e32 v6, v6, v217
	v_mul_f32_e32 v7, v7, v217
	v_mul_f32_e32 v8, v8, v217
	v_mul_f32_e32 v9, v9, v217
	v_mul_f32_e32 v10, v10, v217
	v_mul_f32_e32 v11, v11, v217
	v_mul_f32_e32 v12, v12, v217
	v_mul_f32_e32 v13, v13, v217
	v_mul_f32_e32 v14, v14, v217
	v_mul_f32_e32 v15, v15, v217
	v_mul_f32_e32 v16, v16, v217
	v_mul_f32_e32 v17, v17, v217
	v_mul_f32_e32 v18, v18, v217
	v_mul_f32_e32 v19, v19, v217
	v_mul_f32_e32 v20, v20, v217
	v_mul_f32_e32 v21, v21, v217
	v_mul_f32_e32 v22, v22, v217
	v_mul_f32_e32 v23, v23, v217
	v_mul_f32_e32 v24, v24, v217
	v_mul_f32_e32 v25, v25, v217
	v_mul_f32_e32 v26, v26, v217
	v_mul_f32_e32 v27, v27, v217
	v_mul_f32_e32 v28, v28, v217
	v_mul_f32_e32 v29, v29, v217
	v_mul_f32_e32 v30, v30, v217
	v_mul_f32_e32 v31, v31, v217
	v_mul_f32_e32 v32, v32, v217
	v_mul_f32_e32 v33, v33, v217
.Lna_nr_c0:
	s_waitcnt lgkmcnt(0)
	s_barrier
	ds_read_b128 v[146:149], v199 offset:0
	ds_read_b128 v[150:153], v200 offset:0
	ds_read_b128 v[154:157], v199 offset:32
	ds_read_b128 v[158:161], v200 offset:32
	v_exp_f32_e32 v66, v66
	v_exp_f32_e32 v67, v67
	v_exp_f32_e32 v68, v68
	v_exp_f32_e32 v69, v69
	s_waitcnt lgkmcnt(3)
	v_mfma_f32_32x32x16_bf16 v[34:49], v[146:149], v[98:101], v[114:129]
	ds_read_b128 v[146:149], v199 offset:64
	v_add_f32_e32 v213, v213, v66
	v_add_f32_e32 v214, v214, v67
	v_add_f32_e32 v213, v213, v68
	v_add_f32_e32 v214, v214, v69
	v_exp_f32_e32 v70, v70
	v_exp_f32_e32 v71, v71
	s_waitcnt lgkmcnt(3)
	v_mfma_f32_32x32x16_bf16 v[50:65], v[150:153], v[98:101], v[130:145]
	ds_read_b128 v[150:153], v200 offset:64
	v_exp_f32_e32 v72, v72
	v_exp_f32_e32 v73, v73
	v_add_f32_e32 v213, v213, v70
	v_add_f32_e32 v214, v214, v71
	v_add_f32_e32 v213, v213, v72
	v_add_f32_e32 v214, v214, v73
	s_waitcnt lgkmcnt(3)
	v_mfma_f32_32x32x16_bf16 v[34:49], v[154:157], v[102:105], v[34:49]
	ds_read_b128 v[154:157], v199 offset:96
	v_cvt_pk_bf16_f32 v66, v66, v67
	v_cvt_pk_bf16_f32 v67, v68, v69
	v_cvt_pk_bf16_f32 v68, v70, v71
	v_cvt_pk_bf16_f32 v69, v72, v73
	v_exp_f32_e32 v74, v74
	v_exp_f32_e32 v75, v75
	s_waitcnt lgkmcnt(3)
	v_mfma_f32_32x32x16_bf16 v[50:65], v[158:161], v[102:105], v[50:65]
	ds_read_b128 v[158:161], v200 offset:96
	v_exp_f32_e32 v76, v76
	v_exp_f32_e32 v77, v77
	v_add_f32_e32 v213, v213, v74
	v_add_f32_e32 v214, v214, v75
	v_add_f32_e32 v213, v213, v76
	v_add_f32_e32 v214, v214, v77
	s_waitcnt lgkmcnt(3)
	v_mfma_f32_32x32x16_bf16 v[34:49], v[146:149], v[106:109], v[34:49]
	ds_read_b64 v[162:163], v201 offset:8704
	ds_read_b64 v[164:165], v201 offset:8720
	v_exp_f32_e32 v78, v78
	v_exp_f32_e32 v79, v79
	v_exp_f32_e32 v80, v80
	v_exp_f32_e32 v81, v81
	s_waitcnt lgkmcnt(4)
	v_mfma_f32_32x32x16_bf16 v[50:65], v[150:153], v[106:109], v[50:65]
	ds_read_b64 v[166:167], v201 offset:13056
	ds_read_b64 v[168:169], v201 offset:13072
	v_add_f32_e32 v213, v213, v78
	v_add_f32_e32 v214, v214, v79
	v_add_f32_e32 v213, v213, v80
	v_add_f32_e32 v214, v214, v81
	v_cvt_pk_bf16_f32 v74, v74, v75
	v_cvt_pk_bf16_f32 v75, v76, v77
	v_cvt_pk_bf16_f32 v76, v78, v79
	v_cvt_pk_bf16_f32 v77, v80, v81
	s_waitcnt lgkmcnt(5)
	v_mfma_f32_32x32x16_bf16 v[34:49], v[154:157], v[110:113], v[34:49]
	ds_read_b64 v[170:171], v201 offset:8736
	ds_read_b64 v[172:173], v201 offset:8752
	v_exp_f32_e32 v82, v82
	v_exp_f32_e32 v83, v83
	v_exp_f32_e32 v84, v84
	v_exp_f32_e32 v85, v85
	s_waitcnt lgkmcnt(6)
	v_mfma_f32_32x32x16_bf16 v[50:65], v[158:161], v[110:113], v[50:65]
	ds_read_b64 v[174:175], v201 offset:13088
	ds_read_b64 v[176:177], v201 offset:13104
	v_add_f32_e32 v213, v213, v82
	v_add_f32_e32 v214, v214, v83
	v_add_f32_e32 v213, v213, v84
	v_add_f32_e32 v214, v214, v85
	v_exp_f32_e32 v86, v86
	v_exp_f32_e32 v87, v87
	s_waitcnt lgkmcnt(6)
	s_nop 1
	v_mfma_f32_32x32x16_bf16 v[2:17], v[162:165], v[66:69], v[2:17]
	ds_read_b64 v[162:163], v202 offset:8704
	ds_read_b64 v[164:165], v203 offset:8704
	v_exp_f32_e32 v88, v88
	v_exp_f32_e32 v89, v89
	v_add_f32_e32 v213, v213, v86
	v_add_f32_e32 v214, v214, v87
	v_add_f32_e32 v213, v213, v88
	s_waitcnt lgkmcnt(6)
	v_mfma_f32_32x32x16_bf16 v[18:33], v[166:169], v[66:69], v[18:33]
	ds_read_b64 v[166:167], v202 offset:13056
	ds_read_b64 v[168:169], v203 offset:13056
	v_add_f32_e32 v214, v214, v89
	v_cvt_pk_bf16_f32 v82, v82, v83
	v_cvt_pk_bf16_f32 v83, v84, v85
	v_cvt_pk_bf16_f32 v84, v86, v87
	v_cvt_pk_bf16_f32 v85, v88, v89
	v_exp_f32_e32 v90, v90
	v_exp_f32_e32 v91, v91
	s_waitcnt lgkmcnt(6)
	v_mfma_f32_32x32x16_bf16 v[2:17], v[170:173], v[74:77], v[2:17]
	ds_read_b64 v[170:171], v203 offset:8720
	ds_read_b64 v[172:173], v203 offset:8736
	v_exp_f32_e32 v92, v92
	v_exp_f32_e32 v93, v93
	v_add_f32_e32 v213, v213, v90
	v_add_f32_e32 v214, v214, v91
	v_add_f32_e32 v213, v213, v92
	s_waitcnt lgkmcnt(6)
	v_mfma_f32_32x32x16_bf16 v[18:33], v[174:177], v[74:77], v[18:33]
	ds_read_b64 v[174:175], v203 offset:13072
	ds_read_b64 v[176:177], v203 offset:13088
	s_waitcnt vmcnt(0)
	ds_write_b128 v204, v[188:191] offset:9216
	ds_write_b64 v205, v[192:193] offset:0
	ds_write_b64 v205, v[194:195] offset:8
	global_load_dwordx4 v[192:195], v207, s[14:15]
	s_add_u32 s14, s14, 0x80
	s_addc_u32 s15, s15, 0
	v_add_f32_e32 v214, v214, v93
	v_exp_f32_e32 v94, v94
	v_exp_f32_e32 v95, v95
	v_exp_f32_e32 v96, v96
	v_exp_f32_e32 v97, v97
	s_waitcnt lgkmcnt(9)
	v_mfma_f32_32x32x16_bf16 v[2:17], v[162:165], v[82:85], v[2:17]
	v_add_f32_e32 v213, v213, v94
	v_add_f32_e32 v214, v214, v95
	v_add_f32_e32 v213, v213, v96
	v_add_f32_e32 v214, v214, v97
	v_cvt_pk_bf16_f32 v90, v90, v91
	v_cvt_pk_bf16_f32 v91, v92, v93
	v_cvt_pk_bf16_f32 v92, v94, v95
	s_waitcnt lgkmcnt(7)
	v_mfma_f32_32x32x16_bf16 v[18:33], v[166:169], v[82:85], v[18:33]
	v_cvt_pk_bf16_f32 v93, v96, v97
	v_max3_f32 v216, v34, v35, v36
	v_max3_f32 v217, v50, v51, v52
	v_max3_f32 v216, v216, v37, v38
	v_max3_f32 v217, v217, v53, v54
	v_max3_f32 v216, v216, v39, v40
	v_max3_f32 v217, v217, v55, v56
	v_max3_f32 v216, v216, v41, v42
	s_waitcnt lgkmcnt(5)
	v_mfma_f32_32x32x16_bf16 v[2:17], v[170:173], v[90:93], v[2:17]
	v_max3_f32 v217, v217, v57, v58
	v_max3_f32 v216, v216, v43, v44
	v_max3_f32 v217, v217, v59, v60
	v_max3_f32 v216, v216, v45, v46
	v_max3_f32 v217, v217, v61, v62
	v_max3_f32 v216, v216, v47, v48
	v_max3_f32 v217, v217, v63, v64
	v_max_f32_e32 v216, v216, v49
	s_waitcnt lgkmcnt(3)
	v_mfma_f32_32x32x16_bf16 v[18:33], v[174:177], v[90:93], v[18:33]
	v_max_f32_e32 v217, v217, v65
	v_max_f32_e32 v216, v216, v217
	v_mov_b32_e32 v217, v216
	s_nop 1
	v_permlane32_swap_b32_e32 v216, v217
	v_max_f32_e32 v215, v216, v217
	v_cmp_lt_f32_e32 vcc, 4.0, v215
	s_cbranch_vccz .Lna_nr_c1
	s_nop 15
	v_max_f32_e32 v216, v215, v220
	v_exp_f32_e64 v217, -v216
	v_add_f32_e32 v212, v212, v216
	v_and_b32_e32 v217, v217, v221
	v_sub_f32_e32 v34, v34, v216
	v_sub_f32_e32 v35, v35, v216
	v_sub_f32_e32 v36, v36, v216
	v_sub_f32_e32 v37, v37, v216
	v_sub_f32_e32 v38, v38, v216
	v_sub_f32_e32 v39, v39, v216
	v_sub_f32_e32 v40, v40, v216
	v_sub_f32_e32 v41, v41, v216
	v_sub_f32_e32 v42, v42, v216
	v_sub_f32_e32 v43, v43, v216
	v_sub_f32_e32 v44, v44, v216
	v_sub_f32_e32 v45, v45, v216
	v_sub_f32_e32 v46, v46, v216
	v_sub_f32_e32 v47, v47, v216
	v_sub_f32_e32 v48, v48, v216
	v_sub_f32_e32 v49, v49, v216
	v_sub_f32_e32 v50, v50, v216
	v_sub_f32_e32 v51, v51, v216
	v_sub_f32_e32 v52, v52, v216
	v_sub_f32_e32 v53, v53, v216
	v_sub_f32_e32 v54, v54, v216
	v_sub_f32_e32 v55, v55, v216
	v_sub_f32_e32 v56, v56, v216
	v_sub_f32_e32 v57, v57, v216
	v_sub_f32_e32 v58, v58, v216
	v_sub_f32_e32 v59, v59, v216
	v_sub_f32_e32 v60, v60, v216
	v_sub_f32_e32 v61, v61, v216
	v_sub_f32_e32 v62, v62, v216
	v_sub_f32_e32 v63, v63, v216
	v_sub_f32_e32 v64, v64, v216
	v_sub_f32_e32 v65, v65, v216
	v_sub_f32_e32 v114, v114, v216
	v_sub_f32_e32 v115, v115, v216
	v_sub_f32_e32 v116, v116, v216
	v_sub_f32_e32 v117, v117, v216
	v_sub_f32_e32 v118, v118, v216
	v_sub_f32_e32 v119, v119, v216
	v_sub_f32_e32 v120, v120, v216
	v_sub_f32_e32 v121, v121, v216
	v_sub_f32_e32 v122, v122, v216
	v_sub_f32_e32 v123, v123, v216
	v_sub_f32_e32 v124, v124, v216
	v_sub_f32_e32 v125, v125, v216
	v_sub_f32_e32 v126, v126, v216
	v_sub_f32_e32 v127, v127, v216
	v_sub_f32_e32 v128, v128, v216
	v_sub_f32_e32 v129, v129, v216
	v_sub_f32_e32 v130, v130, v216
	v_sub_f32_e32 v131, v131, v216
	v_sub_f32_e32 v132, v132, v216
	v_sub_f32_e32 v133, v133, v216
	v_sub_f32_e32 v134, v134, v216
	v_sub_f32_e32 v135, v135, v216
	v_sub_f32_e32 v136, v136, v216
	v_sub_f32_e32 v137, v137, v216
	v_sub_f32_e32 v138, v138, v216
	v_sub_f32_e32 v139, v139, v216
	v_sub_f32_e32 v140, v140, v216
	v_sub_f32_e32 v141, v141, v216
	v_sub_f32_e32 v142, v142, v216
	v_sub_f32_e32 v143, v143, v216
	v_sub_f32_e32 v144, v144, v216
	v_sub_f32_e32 v145, v145, v216
	v_mul_f32_e32 v213, v213, v217
	v_mul_f32_e32 v214, v214, v217
	v_mul_f32_e32 v2, v2, v217
	v_mul_f32_e32 v3, v3, v217
	v_mul_f32_e32 v4, v4, v217
	v_mul_f32_e32 v5, v5, v217
	v_mul_f32_e32 v6, v6, v217
	v_mul_f32_e32 v7, v7, v217
	v_mul_f32_e32 v8, v8, v217
	v_mul_f32_e32 v9, v9, v217
	v_mul_f32_e32 v10, v10, v217
	v_mul_f32_e32 v11, v11, v217
	v_mul_f32_e32 v12, v12, v217
	v_mul_f32_e32 v13, v13, v217
	v_mul_f32_e32 v14, v14, v217
	v_mul_f32_e32 v15, v15, v217
	v_mul_f32_e32 v16, v16, v217
	v_mul_f32_e32 v17, v17, v217
	v_mul_f32_e32 v18, v18, v217
	v_mul_f32_e32 v19, v19, v217
	v_mul_f32_e32 v20, v20, v217
	v_mul_f32_e32 v21, v21, v217
	v_mul_f32_e32 v22, v22, v217
	v_mul_f32_e32 v23, v23, v217
	v_mul_f32_e32 v24, v24, v217
	v_mul_f32_e32 v25, v25, v217
	v_mul_f32_e32 v26, v26, v217
	v_mul_f32_e32 v27, v27, v217
	v_mul_f32_e32 v28, v28, v217
	v_mul_f32_e32 v29, v29, v217
	v_mul_f32_e32 v30, v30, v217
	v_mul_f32_e32 v31, v31, v217
	v_mul_f32_e32 v32, v32, v217
	v_mul_f32_e32 v33, v33, v217
.Lna_nr_c1:
	s_waitcnt lgkmcnt(0)
	s_barrier
	ds_read_b128 v[146:149], v199 offset:9216
	ds_read_b128 v[150:153], v200 offset:9216
	ds_read_b128 v[154:157], v199 offset:9248
	ds_read_b128 v[158:161], v200 offset:9248
	v_exp_f32_e32 v34, v34
	v_exp_f32_e32 v35, v35
	v_exp_f32_e32 v36, v36
	v_exp_f32_e32 v37, v37
	s_waitcnt lgkmcnt(3)
	v_mfma_f32_32x32x16_bf16 v[66:81], v[146:149], v[98:101], v[114:129]
	ds_read_b128 v[146:149], v199 offset:9280
	v_add_f32_e32 v213, v213, v34
	v_add_f32_e32 v214, v214, v35
	v_add_f32_e32 v213, v213, v36
	v_add_f32_e32 v214, v214, v37
	v_exp_f32_e32 v38, v38
	v_exp_f32_e32 v39, v39
	s_waitcnt lgkmcnt(3)
	v_mfma_f32_32x32x16_bf16 v[82:97], v[150:153], v[98:101], v[130:145]
	ds_read_b128 v[150:153], v200 offset:9280
	v_exp_f32_e32 v40, v40
	v_exp_f32_e32 v41, v41
	v_add_f32_e32 v213, v213, v38
	v_add_f32_e32 v214, v214, v39
	v_add_f32_e32 v213, v213, v40
	v_add_f32_e32 v214, v214, v41
	s_waitcnt lgkmcnt(3)
	v_mfma_f32_32x32x16_bf16 v[66:81], v[154:157], v[102:105], v[66:81]
	ds_read_b128 v[154:157], v199 offset:9312
	v_cvt_pk_bf16_f32 v34, v34, v35
	v_cvt_pk_bf16_f32 v35, v36, v37
	v_cvt_pk_bf16_f32 v36, v38, v39
	v_cvt_pk_bf16_f32 v37, v40, v41
	v_exp_f32_e32 v42, v42
	v_exp_f32_e32 v43, v43
	s_waitcnt lgkmcnt(3)
	v_mfma_f32_32x32x16_bf16 v[82:97], v[158:161], v[102:105], v[82:97]
	ds_read_b128 v[158:161], v200 offset:9312
	v_exp_f32_e32 v44, v44
	v_exp_f32_e32 v45, v45
	v_add_f32_e32 v213, v213, v42
	v_add_f32_e32 v214, v214, v43
	v_add_f32_e32 v213, v213, v44
	v_add_f32_e32 v214, v214, v45
	s_waitcnt lgkmcnt(3)
	v_mfma_f32_32x32x16_bf16 v[66:81], v[146:149], v[106:109], v[66:81]
	ds_read_b64 v[162:163], v201 offset:0
	ds_read_b64 v[164:165], v201 offset:16
	v_exp_f32_e32 v46, v46
	v_exp_f32_e32 v47, v47
	v_exp_f32_e32 v48, v48
	v_exp_f32_e32 v49, v49
	s_waitcnt lgkmcnt(4)
	v_mfma_f32_32x32x16_bf16 v[82:97], v[150:153], v[106:109], v[82:97]
	ds_read_b64 v[166:167], v201 offset:4352
	ds_read_b64 v[168:169], v201 offset:4368
	v_add_f32_e32 v213, v213, v46
	v_add_f32_e32 v214, v214, v47
	v_add_f32_e32 v213, v213, v48
	v_add_f32_e32 v214, v214, v49
	v_cvt_pk_bf16_f32 v42, v42, v43
	v_cvt_pk_bf16_f32 v43, v44, v45
	v_cvt_pk_bf16_f32 v44, v46, v47
	v_cvt_pk_bf16_f32 v45, v48, v49
	s_waitcnt lgkmcnt(5)
	v_mfma_f32_32x32x16_bf16 v[66:81], v[154:157], v[110:113], v[66:81]
	ds_read_b64 v[170:171], v201 offset:32
	ds_read_b64 v[172:173], v201 offset:48
	v_exp_f32_e32 v50, v50
	v_exp_f32_e32 v51, v51
	v_exp_f32_e32 v52, v52
	v_exp_f32_e32 v53, v53
	s_waitcnt lgkmcnt(6)
	v_mfma_f32_32x32x16_bf16 v[82:97], v[158:161], v[110:113], v[82:97]
	ds_read_b64 v[174:175], v201 offset:4384
	ds_read_b64 v[176:177], v201 offset:4400
	v_add_f32_e32 v213, v213, v50
	v_add_f32_e32 v214, v214, v51
	v_add_f32_e32 v213, v213, v52
	v_add_f32_e32 v214, v214, v53
	v_exp_f32_e32 v54, v54
	v_exp_f32_e32 v55, v55
	s_waitcnt lgkmcnt(6)
	s_nop 1
	v_mfma_f32_32x32x16_bf16 v[2:17], v[162:165], v[34:37], v[2:17]
	ds_read_b64 v[162:163], v202 offset:0
	ds_read_b64 v[164:165], v203 offset:0
	v_exp_f32_e32 v56, v56
	v_exp_f32_e32 v57, v57
	v_add_f32_e32 v213, v213, v54
	v_add_f32_e32 v214, v214, v55
	v_add_f32_e32 v213, v213, v56
	s_waitcnt lgkmcnt(6)
	v_mfma_f32_32x32x16_bf16 v[18:33], v[166:169], v[34:37], v[18:33]
	ds_read_b64 v[166:167], v202 offset:4352
	ds_read_b64 v[168:169], v203 offset:4352
	v_add_f32_e32 v214, v214, v57
	v_cvt_pk_bf16_f32 v50, v50, v51
	v_cvt_pk_bf16_f32 v51, v52, v53
	v_cvt_pk_bf16_f32 v52, v54, v55
	v_cvt_pk_bf16_f32 v53, v56, v57
	v_exp_f32_e32 v58, v58
	v_exp_f32_e32 v59, v59
	s_waitcnt lgkmcnt(6)
	v_mfma_f32_32x32x16_bf16 v[2:17], v[170:173], v[42:45], v[2:17]
	ds_read_b64 v[170:171], v203 offset:16
	ds_read_b64 v[172:173], v203 offset:32
	v_exp_f32_e32 v60, v60
	v_exp_f32_e32 v61, v61
	v_add_f32_e32 v213, v213, v58
	v_add_f32_e32 v214, v214, v59
	v_add_f32_e32 v213, v213, v60
	s_waitcnt lgkmcnt(6)
	v_mfma_f32_32x32x16_bf16 v[18:33], v[174:177], v[42:45], v[18:33]
	ds_read_b64 v[174:175], v203 offset:4368
	ds_read_b64 v[176:177], v203 offset:4384
	s_waitcnt vmcnt(0)
	ds_write_b64 v205, v[192:193] offset:8704
	ds_write_b64 v205, v[194:195] offset:8712
	v_add_f32_e32 v214, v214, v61
	v_exp_f32_e32 v62, v62
	v_exp_f32_e32 v63, v63
	v_exp_f32_e32 v64, v64
	v_exp_f32_e32 v65, v65
	s_waitcnt lgkmcnt(8)
	v_mfma_f32_32x32x16_bf16 v[2:17], v[162:165], v[50:53], v[2:17]
	v_add_f32_e32 v213, v213, v62
	v_add_f32_e32 v214, v214, v63
	v_add_f32_e32 v213, v213, v64
	v_add_f32_e32 v214, v214, v65
	v_cvt_pk_bf16_f32 v58, v58, v59
	v_cvt_pk_bf16_f32 v59, v60, v61
	v_cvt_pk_bf16_f32 v60, v62, v63
	s_waitcnt lgkmcnt(6)
	v_mfma_f32_32x32x16_bf16 v[18:33], v[166:169], v[50:53], v[18:33]
	v_cvt_pk_bf16_f32 v61, v64, v65
	v_max3_f32 v216, v66, v67, v68
	v_max3_f32 v217, v82, v83, v84
	v_max3_f32 v216, v216, v69, v70
	v_max3_f32 v217, v217, v85, v86
	v_max3_f32 v216, v216, v71, v72
	v_max3_f32 v217, v217, v87, v88
	v_max3_f32 v216, v216, v73, v74
	s_waitcnt lgkmcnt(4)
	v_mfma_f32_32x32x16_bf16 v[2:17], v[170:173], v[58:61], v[2:17]
	v_max3_f32 v217, v217, v89, v90
	v_max3_f32 v216, v216, v75, v76
	v_max3_f32 v217, v217, v91, v92
	v_max3_f32 v216, v216, v77, v78
	v_max3_f32 v217, v217, v93, v94
	v_max3_f32 v216, v216, v79, v80
	v_max3_f32 v217, v217, v95, v96
	v_max_f32_e32 v216, v216, v81
	s_waitcnt lgkmcnt(2)
	v_mfma_f32_32x32x16_bf16 v[18:33], v[174:177], v[58:61], v[18:33]
	v_max_f32_e32 v217, v217, v97
	v_max_f32_e32 v216, v216, v217
	v_mov_b32_e32 v217, v216
	s_nop 1
	v_permlane32_swap_b32_e32 v216, v217
	v_max_f32_e32 v215, v216, v217
	v_cmp_lt_f32_e32 vcc, 4.0, v215
	s_cbranch_vccz .Lna_nr_c2
	s_nop 15
	v_max_f32_e32 v216, v215, v220
	v_exp_f32_e64 v217, -v216
	v_add_f32_e32 v212, v212, v216
	v_and_b32_e32 v217, v217, v221
	v_sub_f32_e32 v66, v66, v216
	v_sub_f32_e32 v67, v67, v216
	v_sub_f32_e32 v68, v68, v216
	v_sub_f32_e32 v69, v69, v216
	v_sub_f32_e32 v70, v70, v216
	v_sub_f32_e32 v71, v71, v216
	v_sub_f32_e32 v72, v72, v216
	v_sub_f32_e32 v73, v73, v216
	v_sub_f32_e32 v74, v74, v216
	v_sub_f32_e32 v75, v75, v216
	v_sub_f32_e32 v76, v76, v216
	v_sub_f32_e32 v77, v77, v216
	v_sub_f32_e32 v78, v78, v216
	v_sub_f32_e32 v79, v79, v216
	v_sub_f32_e32 v80, v80, v216
	v_sub_f32_e32 v81, v81, v216
	v_sub_f32_e32 v82, v82, v216
	v_sub_f32_e32 v83, v83, v216
	v_sub_f32_e32 v84, v84, v216
	v_sub_f32_e32 v85, v85, v216
	v_sub_f32_e32 v86, v86, v216
	v_sub_f32_e32 v87, v87, v216
	v_sub_f32_e32 v88, v88, v216
	v_sub_f32_e32 v89, v89, v216
	v_sub_f32_e32 v90, v90, v216
	v_sub_f32_e32 v91, v91, v216
	v_sub_f32_e32 v92, v92, v216
	v_sub_f32_e32 v93, v93, v216
	v_sub_f32_e32 v94, v94, v216
	v_sub_f32_e32 v95, v95, v216
	v_sub_f32_e32 v96, v96, v216
	v_sub_f32_e32 v97, v97, v216
	v_sub_f32_e32 v114, v114, v216
	v_sub_f32_e32 v115, v115, v216
	v_sub_f32_e32 v116, v116, v216
	v_sub_f32_e32 v117, v117, v216
	v_sub_f32_e32 v118, v118, v216
	v_sub_f32_e32 v119, v119, v216
	v_sub_f32_e32 v120, v120, v216
	v_sub_f32_e32 v121, v121, v216
	v_sub_f32_e32 v122, v122, v216
	v_sub_f32_e32 v123, v123, v216
	v_sub_f32_e32 v124, v124, v216
	v_sub_f32_e32 v125, v125, v216
	v_sub_f32_e32 v126, v126, v216
	v_sub_f32_e32 v127, v127, v216
	v_sub_f32_e32 v128, v128, v216
	v_sub_f32_e32 v129, v129, v216
	v_sub_f32_e32 v130, v130, v216
	v_sub_f32_e32 v131, v131, v216
	v_sub_f32_e32 v132, v132, v216
	v_sub_f32_e32 v133, v133, v216
	v_sub_f32_e32 v134, v134, v216
	v_sub_f32_e32 v135, v135, v216
	v_sub_f32_e32 v136, v136, v216
	v_sub_f32_e32 v137, v137, v216
	v_sub_f32_e32 v138, v138, v216
	v_sub_f32_e32 v139, v139, v216
	v_sub_f32_e32 v140, v140, v216
	v_sub_f32_e32 v141, v141, v216
	v_sub_f32_e32 v142, v142, v216
	v_sub_f32_e32 v143, v143, v216
	v_sub_f32_e32 v144, v144, v216
	v_sub_f32_e32 v145, v145, v216
	v_mul_f32_e32 v213, v213, v217
	v_mul_f32_e32 v214, v214, v217
	v_mul_f32_e32 v2, v2, v217
	v_mul_f32_e32 v3, v3, v217
	v_mul_f32_e32 v4, v4, v217
	v_mul_f32_e32 v5, v5, v217
	v_mul_f32_e32 v6, v6, v217
	v_mul_f32_e32 v7, v7, v217
	v_mul_f32_e32 v8, v8, v217
	v_mul_f32_e32 v9, v9, v217
	v_mul_f32_e32 v10, v10, v217
	v_mul_f32_e32 v11, v11, v217
	v_mul_f32_e32 v12, v12, v217
	v_mul_f32_e32 v13, v13, v217
	v_mul_f32_e32 v14, v14, v217
	v_mul_f32_e32 v15, v15, v217
	v_mul_f32_e32 v16, v16, v217
	v_mul_f32_e32 v17, v17, v217
	v_mul_f32_e32 v18, v18, v217
	v_mul_f32_e32 v19, v19, v217
	v_mul_f32_e32 v20, v20, v217
	v_mul_f32_e32 v21, v21, v217
	v_mul_f32_e32 v22, v22, v217
	v_mul_f32_e32 v23, v23, v217
	v_mul_f32_e32 v24, v24, v217
	v_mul_f32_e32 v25, v25, v217
	v_mul_f32_e32 v26, v26, v217
	v_mul_f32_e32 v27, v27, v217
	v_mul_f32_e32 v28, v28, v217
	v_mul_f32_e32 v29, v29, v217
	v_mul_f32_e32 v30, v30, v217
	v_mul_f32_e32 v31, v31, v217
	v_mul_f32_e32 v32, v32, v217
	v_mul_f32_e32 v33, v33, v217
.Lna_nr_c2:
	s_waitcnt lgkmcnt(0)
	s_barrier
	global_load_dwordx2 v[146:147], v218, s[30:31] offset:0
	global_load_dwordx2 v[148:149], v218, s[30:31] offset:16
	global_load_dwordx2 v[150:151], v218, s[30:31] offset:32
	global_load_dwordx2 v[152:153], v218, s[30:31] offset:48
	global_load_dwordx2 v[154:155], v218, s[30:31] offset:64
	global_load_dwordx2 v[156:157], v218, s[30:31] offset:80
	global_load_dwordx2 v[158:159], v218, s[30:31] offset:96
	global_load_dwordx2 v[160:161], v218, s[30:31] offset:112
	v_exp_f32_e32 v66, v66
	v_exp_f32_e32 v67, v67
	v_exp_f32_e32 v68, v68
	v_exp_f32_e32 v69, v69
	v_add_f32_e32 v213, v213, v66
	v_add_f32_e32 v214, v214, v67
	v_add_f32_e32 v213, v213, v68
	v_add_f32_e32 v214, v214, v69
	v_exp_f32_e32 v70, v70
	ds_read_b64 v[162:163], v201 offset:8704
	ds_read_b64 v[164:165], v201 offset:8720
	ds_read_b64 v[166:167], v201 offset:13056
	ds_read_b64 v[168:169], v201 offset:13072
	ds_read_b64 v[170:171], v201 offset:8736
	ds_read_b64 v[172:173], v201 offset:8752
	ds_read_b64 v[174:175], v201 offset:13088
	ds_read_b64 v[176:177], v201 offset:13104
	v_exp_f32_e32 v71, v71
	v_exp_f32_e32 v72, v72
	v_exp_f32_e32 v73, v73
	v_add_f32_e32 v213, v213, v70
	v_add_f32_e32 v214, v214, v71
	v_add_f32_e32 v213, v213, v72
	v_add_f32_e32 v214, v214, v73
	v_cvt_pk_bf16_f32 v66, v66, v67
	v_cvt_pk_bf16_f32 v67, v68, v69
	v_cvt_pk_bf16_f32 v68, v70, v71
	v_cvt_pk_bf16_f32 v69, v72, v73
	s_waitcnt lgkmcnt(6)
	s_nop 1
	v_mfma_f32_32x32x16_bf16 v[2:17], v[162:165], v[66:69], v[2:17]
	ds_read_b64 v[162:163], v202 offset:8704
	ds_read_b64 v[164:165], v203 offset:8704
	s_waitcnt lgkmcnt(6)
	v_mfma_f32_32x32x16_bf16 v[18:33], v[166:169], v[66:69], v[18:33]
	ds_read_b64 v[166:167], v202 offset:13056
	ds_read_b64 v[168:169], v203 offset:13056
	v_exp_f32_e32 v74, v74
	v_exp_f32_e32 v75, v75
	v_exp_f32_e32 v76, v76
	v_exp_f32_e32 v77, v77
	v_add_f32_e32 v213, v213, v74
	v_add_f32_e32 v214, v214, v75
	v_add_f32_e32 v213, v213, v76
	v_add_f32_e32 v214, v214, v77
	v_exp_f32_e32 v78, v78
	v_exp_f32_e32 v79, v79
	v_exp_f32_e32 v80, v80
	v_exp_f32_e32 v81, v81
	v_add_f32_e32 v213, v213, v78
	v_add_f32_e32 v214, v214, v79
	v_add_f32_e32 v213, v213, v80
	v_add_f32_e32 v214, v214, v81
	v_cvt_pk_bf16_f32 v74, v74, v75
	v_cvt_pk_bf16_f32 v75, v76, v77
	v_cvt_pk_bf16_f32 v76, v78, v79
	v_cvt_pk_bf16_f32 v77, v80, v81
	s_waitcnt lgkmcnt(6)
	s_nop 1
	v_mfma_f32_32x32x16_bf16 v[2:17], v[170:173], v[74:77], v[2:17]
	ds_read_b64 v[170:171], v203 offset:8720
	ds_read_b64 v[172:173], v203 offset:8736
	s_waitcnt lgkmcnt(6)
	v_mfma_f32_32x32x16_bf16 v[18:33], v[174:177], v[74:77], v[18:33]
	ds_read_b64 v[174:175], v203 offset:13072
	ds_read_b64 v[176:177], v203 offset:13088
	v_exp_f32_e32 v82, v82
	v_exp_f32_e32 v83, v83
	v_exp_f32_e32 v84, v84
	v_exp_f32_e32 v85, v85
	v_add_f32_e32 v213, v213, v82
	v_add_f32_e32 v214, v214, v83
	v_add_f32_e32 v213, v213, v84
	v_add_f32_e32 v214, v214, v85
	v_exp_f32_e32 v86, v86
	v_exp_f32_e32 v87, v87
	v_exp_f32_e32 v88, v88
	v_exp_f32_e32 v89, v89
	v_add_f32_e32 v213, v213, v86
	v_add_f32_e32 v214, v214, v87
	v_add_f32_e32 v213, v213, v88
	v_add_f32_e32 v214, v214, v89
	v_cvt_pk_bf16_f32 v82, v82, v83
	v_cvt_pk_bf16_f32 v83, v84, v85
	v_cvt_pk_bf16_f32 v84, v86, v87
	v_cvt_pk_bf16_f32 v85, v88, v89
	s_waitcnt lgkmcnt(6)
	s_nop 1
	v_mfma_f32_32x32x16_bf16 v[2:17], v[162:165], v[82:85], v[2:17]
	s_waitcnt lgkmcnt(4)
	v_mfma_f32_32x32x16_bf16 v[18:33], v[166:169], v[82:85], v[18:33]
	v_exp_f32_e32 v90, v90
	v_exp_f32_e32 v91, v91
	v_exp_f32_e32 v92, v92
	v_exp_f32_e32 v93, v93
	v_add_f32_e32 v213, v213, v90
	v_add_f32_e32 v214, v214, v91
	v_add_f32_e32 v213, v213, v92
	v_add_f32_e32 v214, v214, v93
	v_exp_f32_e32 v94, v94
	v_exp_f32_e32 v95, v95
	v_exp_f32_e32 v96, v96
	v_exp_f32_e32 v97, v97
	v_add_f32_e32 v213, v213, v94
	v_add_f32_e32 v214, v214, v95
	v_add_f32_e32 v213, v213, v96
	v_add_f32_e32 v214, v214, v97
	v_cvt_pk_bf16_f32 v90, v90, v91
	v_cvt_pk_bf16_f32 v91, v92, v93
	v_cvt_pk_bf16_f32 v92, v94, v95
	v_cvt_pk_bf16_f32 v93, v96, v97
	s_waitcnt lgkmcnt(2)
	s_nop 1
	v_mfma_f32_32x32x16_bf16 v[2:17], v[170:173], v[90:93], v[2:17]
	s_waitcnt lgkmcnt(0)
	v_mfma_f32_32x32x16_bf16 v[18:33], v[174:177], v[90:93], v[18:33]
	s_waitcnt lgkmcnt(0)
	s_barrier
	v_add_f32_e32 v213, v213, v214
	v_mov_b32_e32 v217, v213
	s_nop 1
	v_permlane32_swap_b32_e32 v213, v217
	v_add_f32_e32 v216, v213, v217
	v_div_scale_f32 v217, s[36:37], v216, v216, 1.0
	v_rcp_f32_e32 v223, v217
	v_div_scale_f32 v224, vcc, 1.0, v216, 1.0
	v_fma_f32 v225, -v217, v223, 1.0
	v_fmac_f32_e32 v223, v225, v223
	v_mul_f32_e32 v225, v224, v223
	v_fma_f32 v226, -v217, v225, v224
	v_fmac_f32_e32 v225, v226, v223
	v_fma_f32 v217, -v217, v225, v224
	v_div_fmas_f32 v217, v217, v223, v225
	v_div_fixup_f32 v216, v217, v216, 1.0
	s_nop 15
	v_mul_f32_e32 v2, v2, v216
	v_mul_f32_e32 v3, v3, v216
	v_mul_f32_e32 v4, v4, v216
	v_mul_f32_e32 v5, v5, v216
	v_mul_f32_e32 v6, v6, v216
	v_mul_f32_e32 v7, v7, v216
	v_mul_f32_e32 v8, v8, v216
	v_mul_f32_e32 v9, v9, v216
	v_mul_f32_e32 v10, v10, v216
	v_mul_f32_e32 v11, v11, v216
	v_mul_f32_e32 v12, v12, v216
	v_mul_f32_e32 v13, v13, v216
	v_mul_f32_e32 v14, v14, v216
	v_mul_f32_e32 v15, v15, v216
	v_mul_f32_e32 v16, v16, v216
	v_mul_f32_e32 v17, v17, v216
	v_mul_f32_e32 v18, v18, v216
	v_mul_f32_e32 v19, v19, v216
	v_mul_f32_e32 v20, v20, v216
	v_mul_f32_e32 v21, v21, v216
	v_mul_f32_e32 v22, v22, v216
	v_mul_f32_e32 v23, v23, v216
	v_mul_f32_e32 v24, v24, v216
	v_mul_f32_e32 v25, v25, v216
	v_mul_f32_e32 v26, v26, v216
	v_mul_f32_e32 v27, v27, v216
	v_mul_f32_e32 v28, v28, v216
	v_mul_f32_e32 v29, v29, v216
	v_mul_f32_e32 v30, v30, v216
	v_mul_f32_e32 v31, v31, v216
	v_mul_f32_e32 v32, v32, v216
	v_mul_f32_e32 v33, v33, v216
	s_waitcnt vmcnt(0)
	v_lshlrev_b32_e32 v223, 16, v146
	v_and_b32_e32 v224, 0xffff0000, v146
	v_lshlrev_b32_e32 v225, 16, v147
	v_and_b32_e32 v226, 0xffff0000, v147
	v_mul_f32_e32 v2, v2, v223
	v_mul_f32_e32 v3, v3, v224
	v_mul_f32_e32 v4, v4, v225
	v_mul_f32_e32 v5, v5, v226
	v_cvt_pk_bf16_f32 v146, v2, v3
	v_cvt_pk_bf16_f32 v147, v4, v5
	global_store_dwordx2 v218, v[146:147], s[30:31] offset:0
	v_lshlrev_b32_e32 v223, 16, v148
	v_and_b32_e32 v224, 0xffff0000, v148
	v_lshlrev_b32_e32 v225, 16, v149
	v_and_b32_e32 v226, 0xffff0000, v149
	v_mul_f32_e32 v6, v6, v223
	v_mul_f32_e32 v7, v7, v224
	v_mul_f32_e32 v8, v8, v225
	v_mul_f32_e32 v9, v9, v226
	v_cvt_pk_bf16_f32 v148, v6, v7
	v_cvt_pk_bf16_f32 v149, v8, v9
	global_store_dwordx2 v218, v[148:149], s[30:31] offset:16
	v_lshlrev_b32_e32 v223, 16, v150
	v_and_b32_e32 v224, 0xffff0000, v150
	v_lshlrev_b32_e32 v225, 16, v151
	v_and_b32_e32 v226, 0xffff0000, v151
	v_mul_f32_e32 v10, v10, v223
	v_mul_f32_e32 v11, v11, v224
	v_mul_f32_e32 v12, v12, v225
	v_mul_f32_e32 v13, v13, v226
	v_cvt_pk_bf16_f32 v150, v10, v11
	v_cvt_pk_bf16_f32 v151, v12, v13
	global_store_dwordx2 v218, v[150:151], s[30:31] offset:32
	v_lshlrev_b32_e32 v223, 16, v152
	v_and_b32_e32 v224, 0xffff0000, v152
	v_lshlrev_b32_e32 v225, 16, v153
	v_and_b32_e32 v226, 0xffff0000, v153
	v_mul_f32_e32 v14, v14, v223
	v_mul_f32_e32 v15, v15, v224
	v_mul_f32_e32 v16, v16, v225
	v_mul_f32_e32 v17, v17, v226
	v_cvt_pk_bf16_f32 v152, v14, v15
	v_cvt_pk_bf16_f32 v153, v16, v17
	global_store_dwordx2 v218, v[152:153], s[30:31] offset:48
	v_lshlrev_b32_e32 v223, 16, v154
	v_and_b32_e32 v224, 0xffff0000, v154
	v_lshlrev_b32_e32 v225, 16, v155
	v_and_b32_e32 v226, 0xffff0000, v155
	v_mul_f32_e32 v18, v18, v223
	v_mul_f32_e32 v19, v19, v224
	v_mul_f32_e32 v20, v20, v225
	v_mul_f32_e32 v21, v21, v226
	v_cvt_pk_bf16_f32 v154, v18, v19
	v_cvt_pk_bf16_f32 v155, v20, v21
	global_store_dwordx2 v218, v[154:155], s[30:31] offset:64
	v_lshlrev_b32_e32 v223, 16, v156
	v_and_b32_e32 v224, 0xffff0000, v156
	v_lshlrev_b32_e32 v225, 16, v157
	v_and_b32_e32 v226, 0xffff0000, v157
	v_mul_f32_e32 v22, v22, v223
	v_mul_f32_e32 v23, v23, v224
	v_mul_f32_e32 v24, v24, v225
	v_mul_f32_e32 v25, v25, v226
	v_cvt_pk_bf16_f32 v156, v22, v23
	v_cvt_pk_bf16_f32 v157, v24, v25
	global_store_dwordx2 v218, v[156:157], s[30:31] offset:80
	v_lshlrev_b32_e32 v223, 16, v158
	v_and_b32_e32 v224, 0xffff0000, v158
	v_lshlrev_b32_e32 v225, 16, v159
	v_and_b32_e32 v226, 0xffff0000, v159
	v_mul_f32_e32 v26, v26, v223
	v_mul_f32_e32 v27, v27, v224
	v_mul_f32_e32 v28, v28, v225
	v_mul_f32_e32 v29, v29, v226
	v_cvt_pk_bf16_f32 v158, v26, v27
	v_cvt_pk_bf16_f32 v159, v28, v29
	global_store_dwordx2 v218, v[158:159], s[30:31] offset:96
	v_lshlrev_b32_e32 v223, 16, v160
	v_and_b32_e32 v224, 0xffff0000, v160
	v_lshlrev_b32_e32 v225, 16, v161
	v_and_b32_e32 v226, 0xffff0000, v161
	v_mul_f32_e32 v30, v30, v223
	v_mul_f32_e32 v31, v31, v224
	v_mul_f32_e32 v32, v32, v225
	v_mul_f32_e32 v33, v33, v226
	v_cvt_pk_bf16_f32 v160, v30, v31
	v_cvt_pk_bf16_f32 v161, v32, v33
	global_store_dwordx2 v218, v[160:161], s[30:31] offset:112
	s_add_i32 s10, s10, s9
	s_cmpk_lt_i32 s10, 0x200
	s_cbranch_scc1 .Lna_unit
	s_mov_b32 s88, s9

.Lmla_unit:
	s_lshr_b32 s17, s2, 4
	s_and_b32 s18, s2, 15
	s_mul_i32 s19, s17, 0xcc000
	s_add_u32 s4, s78, s19
	s_addc_u32 s5, s79, 0
	s_mul_i32 s19, s17, 0x88000
	s_add_u32 s19, s19, 0x1a00000
	s_add_u32 s10, s78, s19
	s_addc_u32 s11, s79, 0
	s_lshl_b32 s19, s17, 12
	s_lshl_b32 s20, s18, 8
	s_add_u32 s19, s19, s20
	s_mul_i32 s19, s19, 0xc0
	s_add_u32 s19, s19, 0x1400000
	s_add_u32 s12, s80, s19
	s_addc_u32 s13, s81, 0
	s_lshr_b32 s19, s17, 3
	s_lshl_b32 s19, s19, 12
	s_add_u32 s19, s19, s20
	s_lshl_b32 s19, s19, 10
	s_and_b32 s21, s17, 7
	s_lshl_b32 s21, s21, 7
	s_add_u32 s19, s19, s21
	s_add_u32 s19, s19, 0x7900000
	s_add_u32 s14, s80, s19
	s_addc_u32 s15, s81, 0
	global_load_dwordx4 v[98:101], v237, s[12:13] offset:0
	global_load_dwordx4 v[102:105], v237, s[12:13] offset:32
	global_load_dwordx4 v[106:109], v237, s[12:13] offset:64
	global_load_dwordx4 v[110:113], v237, s[12:13] offset:96
	global_load_dwordx4 v[114:117], v237, s[12:13] offset:128
	global_load_dwordx4 v[118:121], v237, s[12:13] offset:160
	global_load_dwordx4 v[200:203], v226, s[4:5]
	global_load_dwordx4 v[204:207], v227, s[4:5]
	global_load_dwordx4 v[208:211], v228, s[4:5]
	global_load_dwordx4 v[66:69], v229, s[10:11]
	s_add_u32 s4, s4, 0x6000
	s_addc_u32 s5, s5, 0
	global_load_dwordx4 v[70:73], v226, s[4:5]
	global_load_dwordx4 v[74:77], v227, s[4:5]
	global_load_dwordx4 v[78:81], v228, s[4:5]
	global_load_dwordx4 v[82:85], v229, s[10:11] offset:128
	global_load_dwordx4 v[216:219], v229, s[10:11] offset:256
	s_add_u32 s4, s4, 0x6000
	s_addc_u32 s5, s5, 0
	s_add_u32 s10, s10, 0x180
	s_addc_u32 s11, s11, 0
	v_mov_b32_e32 v2, 0
	v_mov_b32_e32 v3, 0
	v_mov_b32_e32 v4, 0
	v_mov_b32_e32 v5, 0
	v_mov_b32_e32 v6, 0
	v_mov_b32_e32 v7, 0
	v_mov_b32_e32 v8, 0
	v_mov_b32_e32 v9, 0
	v_mov_b32_e32 v10, 0
	v_mov_b32_e32 v11, 0
	v_mov_b32_e32 v12, 0
	v_mov_b32_e32 v13, 0
	v_mov_b32_e32 v14, 0
	v_mov_b32_e32 v15, 0
	v_mov_b32_e32 v16, 0
	v_mov_b32_e32 v17, 0
	v_mov_b32_e32 v18, 0
	v_mov_b32_e32 v19, 0
	v_mov_b32_e32 v20, 0
	v_mov_b32_e32 v21, 0
	v_mov_b32_e32 v22, 0
	v_mov_b32_e32 v23, 0
	v_mov_b32_e32 v24, 0
	v_mov_b32_e32 v25, 0
	v_mov_b32_e32 v26, 0
	v_mov_b32_e32 v27, 0
	v_mov_b32_e32 v28, 0
	v_mov_b32_e32 v29, 0
	v_mov_b32_e32 v30, 0
	v_mov_b32_e32 v31, 0
	v_mov_b32_e32 v32, 0
	v_mov_b32_e32 v33, 0
	v_mov_b32_e32 v122, 0
	v_mov_b32_e32 v123, 0
	v_mov_b32_e32 v124, 0
	v_mov_b32_e32 v125, 0
	v_mov_b32_e32 v126, 0
	v_mov_b32_e32 v127, 0
	v_mov_b32_e32 v128, 0
	v_mov_b32_e32 v129, 0
	v_mov_b32_e32 v130, 0
	v_mov_b32_e32 v131, 0
	v_mov_b32_e32 v132, 0
	v_mov_b32_e32 v133, 0
	v_mov_b32_e32 v134, 0
	v_mov_b32_e32 v135, 0
	v_mov_b32_e32 v136, 0
	v_mov_b32_e32 v137, 0
	v_mov_b32_e32 v230, 0
	v_mov_b32_e32 v231, 0
	v_mov_b32_e32 v232, 0
	s_waitcnt vmcnt(5)
	ds_write_b128 v222, v[200:203]
	ds_write_b128 v223, v[204:207]
	ds_write_b128 v224, v[208:211]
	ds_write_b64 v225, v[66:67]
	ds_write_b64 v225, v[68:69] offset:8
	s_waitcnt vmcnt(1)
	ds_write_b128 v222, v[70:73] offset:26624
	ds_write_b128 v223, v[74:77] offset:26624
	ds_write_b128 v224, v[78:81] offset:26624
	ds_write_b64 v225, v[82:83] offset:8704
	ds_write_b64 v225, v[84:85] offset:8712
	s_waitcnt lgkmcnt(0)
	s_barrier
	ds_read_b128 v[138:141], v220 offset:0
	ds_read_b128 v[142:145], v220 offset:6656
	ds_read_b128 v[146:149], v220 offset:32
	ds_read_b128 v[150:153], v220 offset:6688
	ds_read_b128 v[154:157], v220 offset:64
	ds_read_b128 v[158:161], v220 offset:6720
	ds_read_b128 v[66:69], v220 offset:96
	ds_read_b128 v[70:73], v220 offset:6752
	ds_read_b128 v[74:77], v220 offset:128
	ds_read_b128 v[78:81], v220 offset:6784
	ds_read_b128 v[82:85], v220 offset:160
	ds_read_b128 v[86:89], v220 offset:6816
	s_waitcnt lgkmcnt(11)
	v_mfma_f32_32x32x16_bf16 v[34:49], v[138:141], v[98:101], v[122:137]
	s_waitcnt lgkmcnt(10)
	v_mfma_f32_32x32x16_bf16 v[50:65], v[142:145], v[98:101], v[122:137]
	s_waitcnt lgkmcnt(9)
	v_mfma_f32_32x32x16_bf16 v[34:49], v[146:149], v[102:105], v[34:49]
	s_waitcnt lgkmcnt(8)
	v_mfma_f32_32x32x16_bf16 v[50:65], v[150:153], v[102:105], v[50:65]
	s_waitcnt lgkmcnt(7)
	v_mfma_f32_32x32x16_bf16 v[34:49], v[154:157], v[106:109], v[34:49]
	s_waitcnt lgkmcnt(6)
	v_mfma_f32_32x32x16_bf16 v[50:65], v[158:161], v[106:109], v[50:65]
	s_waitcnt lgkmcnt(5)
	v_mfma_f32_32x32x16_bf16 v[34:49], v[66:69], v[110:113], v[34:49]
	s_waitcnt lgkmcnt(4)
	v_mfma_f32_32x32x16_bf16 v[50:65], v[70:73], v[110:113], v[50:65]
	s_waitcnt lgkmcnt(3)
	v_mfma_f32_32x32x16_bf16 v[34:49], v[74:77], v[114:117], v[34:49]
	s_waitcnt lgkmcnt(2)
	v_mfma_f32_32x32x16_bf16 v[50:65], v[78:81], v[114:117], v[50:65]
	s_waitcnt lgkmcnt(1)
	v_mfma_f32_32x32x16_bf16 v[34:49], v[82:85], v[118:121], v[34:49]
	s_waitcnt lgkmcnt(0)
	v_mfma_f32_32x32x16_bf16 v[50:65], v[86:89], v[118:121], v[50:65]
	s_nop 15
	v_max3_f32 v234, v34, v35, v36
	v_max3_f32 v235, v50, v51, v52
	v_max3_f32 v234, v234, v37, v38
	v_max3_f32 v235, v235, v53, v54
	v_max3_f32 v234, v234, v39, v40
	v_max3_f32 v235, v235, v55, v56
	v_max3_f32 v234, v234, v41, v42
	v_max3_f32 v235, v235, v57, v58
	v_max3_f32 v234, v234, v43, v44
	v_max3_f32 v235, v235, v59, v60
	v_max3_f32 v234, v234, v45, v46
	v_max3_f32 v235, v235, v61, v62
	v_max3_f32 v234, v234, v47, v48
	v_max3_f32 v235, v235, v63, v64
	v_max3_f32 v234, v234, v49, v65
	v_max_f32_e32 v234, v234, v235
	v_mov_b32_e32 v235, v234
	s_nop 1
	v_permlane32_swap_b32_e32 v234, v235
	v_max_f32_e32 v233, v234, v235
	s_nop 15
	v_add_f32_e32 v230, v230, v233
	v_sub_f32_e32 v34, v34, v233
	v_sub_f32_e32 v35, v35, v233
	v_sub_f32_e32 v36, v36, v233
	v_sub_f32_e32 v37, v37, v233
	v_sub_f32_e32 v38, v38, v233
	v_sub_f32_e32 v39, v39, v233
	v_sub_f32_e32 v40, v40, v233
	v_sub_f32_e32 v41, v41, v233
	v_sub_f32_e32 v42, v42, v233
	v_sub_f32_e32 v43, v43, v233
	v_sub_f32_e32 v44, v44, v233
	v_sub_f32_e32 v45, v45, v233
	v_sub_f32_e32 v46, v46, v233
	v_sub_f32_e32 v47, v47, v233
	v_sub_f32_e32 v48, v48, v233
	v_sub_f32_e32 v49, v49, v233
	v_sub_f32_e32 v50, v50, v233
	v_sub_f32_e32 v51, v51, v233
	v_sub_f32_e32 v52, v52, v233
	v_sub_f32_e32 v53, v53, v233
	v_sub_f32_e32 v54, v54, v233
	v_sub_f32_e32 v55, v55, v233
	v_sub_f32_e32 v56, v56, v233
	v_sub_f32_e32 v57, v57, v233
	v_sub_f32_e32 v58, v58, v233
	v_sub_f32_e32 v59, v59, v233
	v_sub_f32_e32 v60, v60, v233
	v_sub_f32_e32 v61, v61, v233
	v_sub_f32_e32 v62, v62, v233
	v_sub_f32_e32 v63, v63, v233
	v_sub_f32_e32 v64, v64, v233
	v_sub_f32_e32 v65, v65, v233
	v_sub_f32_e32 v122, 0, v230
	v_mov_b32_e32 v123, v122
	v_mov_b32_e32 v124, v122
	v_mov_b32_e32 v125, v122
	v_mov_b32_e32 v126, v122
	v_mov_b32_e32 v127, v122
	v_mov_b32_e32 v128, v122
	v_mov_b32_e32 v129, v122
	v_mov_b32_e32 v130, v122
	v_mov_b32_e32 v131, v122
	v_mov_b32_e32 v132, v122
	v_mov_b32_e32 v133, v122
	v_mov_b32_e32 v134, v122
	v_mov_b32_e32 v135, v122
	v_mov_b32_e32 v136, v122
	v_mov_b32_e32 v137, v122
	ds_read_b128 v[138:141], v220 offset:13312
	ds_read_b128 v[142:145], v220 offset:19968
	ds_read_b128 v[146:149], v220 offset:13344
	ds_read_b128 v[150:153], v220 offset:20000
	ds_read_b128 v[154:157], v220 offset:13376
	ds_read_b128 v[158:161], v220 offset:20032
	s_movk_i32 s16, 16
.Lmla_loop:
	v_exp_f32_e32 v34, v34
	v_exp_f32_e32 v35, v35
	v_exp_f32_e32 v36, v36
	v_exp_f32_e32 v37, v37
	s_waitcnt lgkmcnt(5)
	v_mfma_f32_32x32x16_bf16 v[66:81], v[138:141], v[98:101], v[122:137]
	ds_read_b128 v[138:141], v220 offset:13408
	v_add_f32_e32 v231, v231, v34
	v_add_f32_e32 v232, v232, v35
	v_exp_f32_e32 v38, v38
	v_exp_f32_e32 v39, v39
	s_waitcnt lgkmcnt(5)
	v_mfma_f32_32x32x16_bf16 v[82:97], v[142:145], v[98:101], v[122:137]
	ds_read_b128 v[142:145], v220 offset:20064
	v_add_f32_e32 v231, v231, v36
	v_add_f32_e32 v232, v232, v37
	v_exp_f32_e32 v40, v40
	v_exp_f32_e32 v41, v41
	s_waitcnt lgkmcnt(5)
	v_mfma_f32_32x32x16_bf16 v[66:81], v[146:149], v[102:105], v[66:81]
	ds_read_b128 v[146:149], v220 offset:13440
	global_load_dwordx4 v[200:203], v226, s[4:5]
	global_load_dwordx4 v[204:207], v227, s[4:5]
	global_load_dwordx4 v[208:211], v228, s[4:5]
	s_add_u32 s4, s4, 0x6000
	s_addc_u32 s5, s5, 0
	global_load_dwordx4 v[212:215], v229, s[10:11]
	s_add_u32 s10, s10, 0x80
	s_addc_u32 s11, s11, 0
	v_add_f32_e32 v231, v231, v38
	v_add_f32_e32 v232, v232, v39
	v_add_f32_e32 v231, v231, v40
	v_add_f32_e32 v232, v232, v41
	v_cvt_pk_bf16_f32 v34, v34, v35
	v_cvt_pk_bf16_f32 v35, v36, v37
	s_waitcnt lgkmcnt(5)
	v_mfma_f32_32x32x16_bf16 v[82:97], v[150:153], v[102:105], v[82:97]
	ds_read_b128 v[150:153], v220 offset:20096
	v_cvt_pk_bf16_f32 v36, v38, v39
	v_cvt_pk_bf16_f32 v37, v40, v41
	v_exp_f32_e32 v42, v42
	v_exp_f32_e32 v43, v43
	s_waitcnt lgkmcnt(5)
	v_mfma_f32_32x32x16_bf16 v[66:81], v[154:157], v[106:109], v[66:81]
	ds_read_b128 v[154:157], v220 offset:13472
	v_exp_f32_e32 v44, v44
	v_exp_f32_e32 v45, v45
	v_add_f32_e32 v231, v231, v42
	v_add_f32_e32 v232, v232, v43
	s_waitcnt lgkmcnt(5)
	v_mfma_f32_32x32x16_bf16 v[82:97], v[158:161], v[106:109], v[82:97]
	ds_read_b128 v[158:161], v220 offset:20128
	v_exp_f32_e32 v46, v46
	v_exp_f32_e32 v47, v47
	v_add_f32_e32 v231, v231, v44
	v_add_f32_e32 v232, v232, v45
	v_exp_f32_e32 v48, v48
	s_waitcnt lgkmcnt(5)
	v_mfma_f32_32x32x16_bf16 v[66:81], v[138:141], v[110:113], v[66:81]
	ds_read_b64 v[162:163], v221 offset:0
	ds_read_b64 v[164:165], v221 offset:16
	v_exp_f32_e32 v49, v49
	v_add_f32_e32 v231, v231, v46
	v_add_f32_e32 v232, v232, v47
	v_add_f32_e32 v231, v231, v48
	s_waitcnt lgkmcnt(6)
	v_mfma_f32_32x32x16_bf16 v[82:97], v[142:145], v[110:113], v[82:97]
	ds_read_b64 v[166:167], v221 offset:4352
	ds_read_b64 v[168:169], v221 offset:4368
	v_add_f32_e32 v232, v232, v49
	v_cvt_pk_bf16_f32 v42, v42, v43
	v_cvt_pk_bf16_f32 v43, v44, v45
	v_cvt_pk_bf16_f32 v44, v46, v47
	v_cvt_pk_bf16_f32 v45, v48, v49
	v_exp_f32_e32 v50, v50
	s_waitcnt lgkmcnt(7)
	v_mfma_f32_32x32x16_bf16 v[66:81], v[146:149], v[114:117], v[66:81]
	ds_read_b64 v[170:171], v221 offset:32
	ds_read_b64 v[172:173], v221 offset:48
	v_exp_f32_e32 v51, v51
	v_exp_f32_e32 v52, v52
	v_exp_f32_e32 v53, v53
	s_waitcnt lgkmcnt(8)
	v_mfma_f32_32x32x16_bf16 v[82:97], v[150:153], v[114:117], v[82:97]
	ds_read_b64 v[174:175], v221 offset:4384
	ds_read_b64 v[176:177], v221 offset:4400
	v_add_f32_e32 v231, v231, v50
	v_add_f32_e32 v232, v232, v51
	v_exp_f32_e32 v54, v54
	v_exp_f32_e32 v55, v55
	s_waitcnt lgkmcnt(9)
	v_mfma_f32_32x32x16_bf16 v[66:81], v[154:157], v[118:121], v[66:81]
	ds_read_b64 v[180:181], v221 offset:64
	ds_read_b64 v[182:183], v221 offset:80
	v_add_f32_e32 v231, v231, v52
	v_add_f32_e32 v232, v232, v53
	v_exp_f32_e32 v56, v56
	v_exp_f32_e32 v57, v57
	s_waitcnt lgkmcnt(10)
	v_mfma_f32_32x32x16_bf16 v[82:97], v[158:161], v[118:121], v[82:97]
	ds_read_b64 v[184:185], v221 offset:4416
	ds_read_b64 v[186:187], v221 offset:4432
	v_add_f32_e32 v231, v231, v54
	v_add_f32_e32 v232, v232, v55
	v_add_f32_e32 v231, v231, v56
	v_add_f32_e32 v232, v232, v57
	v_cvt_pk_bf16_f32 v50, v50, v51
	v_cvt_pk_bf16_f32 v51, v52, v53
	v_cvt_pk_bf16_f32 v52, v54, v55
	s_waitcnt lgkmcnt(10)
	s_nop 1
	v_mfma_f32_32x32x16_bf16 v[2:17], v[162:165], v[34:37], v[2:17]
	ds_read_b64 v[188:189], v221 offset:96
	ds_read_b64 v[190:191], v221 offset:112
	v_cvt_pk_bf16_f32 v53, v56, v57
	v_exp_f32_e32 v58, v58
	v_exp_f32_e32 v59, v59
	v_exp_f32_e32 v60, v60
	s_waitcnt lgkmcnt(10)
	v_mfma_f32_32x32x16_bf16 v[18:33], v[166:169], v[34:37], v[18:33]
	ds_read_b64 v[192:193], v221 offset:4448
	ds_read_b64 v[194:195], v221 offset:4464
	v_exp_f32_e32 v61, v61
	v_add_f32_e32 v231, v231, v58
	v_add_f32_e32 v232, v232, v59
	v_exp_f32_e32 v62, v62
	s_waitcnt lgkmcnt(10)
	v_mfma_f32_32x32x16_bf16 v[2:17], v[170:173], v[42:45], v[2:17]
	v_exp_f32_e32 v63, v63
	v_add_f32_e32 v231, v231, v60
	v_add_f32_e32 v232, v232, v61
	v_exp_f32_e32 v64, v64
	s_waitcnt lgkmcnt(8)
	v_mfma_f32_32x32x16_bf16 v[18:33], v[174:177], v[42:45], v[18:33]
	s_waitcnt vmcnt(4)
	ds_write_b64 v225, v[216:217] offset:17408
	ds_write_b64 v225, v[218:219] offset:17416
	v_exp_f32_e32 v65, v65
	v_add_f32_e32 v231, v231, v62
	v_add_f32_e32 v232, v232, v63
	v_add_f32_e32 v231, v231, v64
	v_add_f32_e32 v232, v232, v65
	s_waitcnt lgkmcnt(8)
	v_mfma_f32_32x32x16_bf16 v[2:17], v[180:183], v[50:53], v[2:17]
	v_cvt_pk_bf16_f32 v58, v58, v59
	v_cvt_pk_bf16_f32 v59, v60, v61
	v_cvt_pk_bf16_f32 v60, v62, v63
	v_cvt_pk_bf16_f32 v61, v64, v65
	v_max3_f32 v234, v66, v67, v68
	v_max3_f32 v235, v82, v83, v84
	s_waitcnt lgkmcnt(6)
	v_mfma_f32_32x32x16_bf16 v[18:33], v[184:187], v[50:53], v[18:33]
	v_max3_f32 v234, v234, v69, v70
	v_max3_f32 v235, v235, v85, v86
	v_max3_f32 v234, v234, v71, v72
	v_max3_f32 v235, v235, v87, v88
	v_max3_f32 v234, v234, v73, v74
	v_max3_f32 v235, v235, v89, v90
	v_max3_f32 v234, v234, v75, v76
	s_waitcnt lgkmcnt(4)
	v_mfma_f32_32x32x16_bf16 v[2:17], v[188:191], v[58:61], v[2:17]
	v_max3_f32 v235, v235, v91, v92
	v_max3_f32 v234, v234, v77, v78
	v_max3_f32 v235, v235, v93, v94
	v_max3_f32 v234, v234, v79, v80
	v_max3_f32 v235, v235, v95, v96
	v_max3_f32 v234, v234, v81, v97
	s_waitcnt lgkmcnt(2)
	v_mfma_f32_32x32x16_bf16 v[18:33], v[192:195], v[58:61], v[18:33]
	v_max_f32_e32 v234, v234, v235
	v_mov_b32_e32 v235, v234
	s_nop 1
	v_permlane32_swap_b32_e32 v234, v235
	v_max_f32_e32 v233, v234, v235
	v_cmp_lt_f32_e32 vcc, 4.0, v233
	s_cbranch_vccz .Lmla_nr_p0
	s_nop 15
	v_max_f32_e32 v234, 0, v233
	v_exp_f32_e64 v235, -v234
	v_add_f32_e32 v230, v230, v234
	v_sub_f32_e32 v66, v66, v234
	v_sub_f32_e32 v67, v67, v234
	v_sub_f32_e32 v68, v68, v234
	v_sub_f32_e32 v69, v69, v234
	v_sub_f32_e32 v70, v70, v234
	v_sub_f32_e32 v71, v71, v234
	v_sub_f32_e32 v72, v72, v234
	v_sub_f32_e32 v73, v73, v234
	v_sub_f32_e32 v74, v74, v234
	v_sub_f32_e32 v75, v75, v234
	v_sub_f32_e32 v76, v76, v234
	v_sub_f32_e32 v77, v77, v234
	v_sub_f32_e32 v78, v78, v234
	v_sub_f32_e32 v79, v79, v234
	v_sub_f32_e32 v80, v80, v234
	v_sub_f32_e32 v81, v81, v234
	v_sub_f32_e32 v82, v82, v234
	v_sub_f32_e32 v83, v83, v234
	v_sub_f32_e32 v84, v84, v234
	v_sub_f32_e32 v85, v85, v234
	v_sub_f32_e32 v86, v86, v234
	v_sub_f32_e32 v87, v87, v234
	v_sub_f32_e32 v88, v88, v234
	v_sub_f32_e32 v89, v89, v234
	v_sub_f32_e32 v90, v90, v234
	v_sub_f32_e32 v91, v91, v234
	v_sub_f32_e32 v92, v92, v234
	v_sub_f32_e32 v93, v93, v234
	v_sub_f32_e32 v94, v94, v234
	v_sub_f32_e32 v95, v95, v234
	v_sub_f32_e32 v96, v96, v234
	v_sub_f32_e32 v97, v97, v234
	v_mul_f32_e32 v231, v231, v235
	v_mul_f32_e32 v232, v232, v235
	v_mul_f32_e32 v2, v2, v235
	v_mul_f32_e32 v3, v3, v235
	v_mul_f32_e32 v4, v4, v235
	v_mul_f32_e32 v5, v5, v235
	v_mul_f32_e32 v6, v6, v235
	v_mul_f32_e32 v7, v7, v235
	v_mul_f32_e32 v8, v8, v235
	v_mul_f32_e32 v9, v9, v235
	v_mul_f32_e32 v10, v10, v235
	v_mul_f32_e32 v11, v11, v235
	v_mul_f32_e32 v12, v12, v235
	v_mul_f32_e32 v13, v13, v235
	v_mul_f32_e32 v14, v14, v235
	v_mul_f32_e32 v15, v15, v235
	v_mul_f32_e32 v16, v16, v235
	v_mul_f32_e32 v17, v17, v235
	v_mul_f32_e32 v18, v18, v235
	v_mul_f32_e32 v19, v19, v235
	v_mul_f32_e32 v20, v20, v235
	v_mul_f32_e32 v21, v21, v235
	v_mul_f32_e32 v22, v22, v235
	v_mul_f32_e32 v23, v23, v235
	v_mul_f32_e32 v24, v24, v235
	v_mul_f32_e32 v25, v25, v235
	v_mul_f32_e32 v26, v26, v235
	v_mul_f32_e32 v27, v27, v235
	v_mul_f32_e32 v28, v28, v235
	v_mul_f32_e32 v29, v29, v235
	v_mul_f32_e32 v30, v30, v235
	v_mul_f32_e32 v31, v31, v235
	v_mul_f32_e32 v32, v32, v235
	v_mul_f32_e32 v33, v33, v235
	v_sub_f32_e32 v122, 0, v230
	v_mov_b32_e32 v123, v122
	v_mov_b32_e32 v124, v122
	v_mov_b32_e32 v125, v122
	v_mov_b32_e32 v126, v122
	v_mov_b32_e32 v127, v122
	v_mov_b32_e32 v128, v122
	v_mov_b32_e32 v129, v122
	v_mov_b32_e32 v130, v122
	v_mov_b32_e32 v131, v122
	v_mov_b32_e32 v132, v122
	v_mov_b32_e32 v133, v122
	v_mov_b32_e32 v134, v122
	v_mov_b32_e32 v135, v122
	v_mov_b32_e32 v136, v122
	v_mov_b32_e32 v137, v122
.Lmla_nr_p0:
	ds_read_b128 v[138:141], v220 offset:26624
	ds_read_b128 v[142:145], v220 offset:33280
	ds_read_b128 v[146:149], v220 offset:26656
	ds_read_b128 v[150:153], v220 offset:33312
	ds_read_b128 v[154:157], v220 offset:26688
	ds_read_b128 v[158:161], v220 offset:33344
	s_waitcnt lgkmcnt(6)
	s_barrier
	v_exp_f32_e32 v66, v66
	v_exp_f32_e32 v67, v67
	v_exp_f32_e32 v68, v68
	v_exp_f32_e32 v69, v69
	s_waitcnt lgkmcnt(5)
	v_mfma_f32_32x32x16_bf16 v[34:49], v[138:141], v[98:101], v[122:137]
	ds_read_b128 v[138:141], v220 offset:26720
	v_add_f32_e32 v231, v231, v66
	v_add_f32_e32 v232, v232, v67
	v_exp_f32_e32 v70, v70
	v_exp_f32_e32 v71, v71
	s_waitcnt lgkmcnt(5)
	v_mfma_f32_32x32x16_bf16 v[50:65], v[142:145], v[98:101], v[122:137]
	ds_read_b128 v[142:145], v220 offset:33376
	v_add_f32_e32 v231, v231, v68
	v_add_f32_e32 v232, v232, v69
	v_exp_f32_e32 v72, v72
	v_exp_f32_e32 v73, v73
	s_waitcnt lgkmcnt(5)
	v_mfma_f32_32x32x16_bf16 v[34:49], v[146:149], v[102:105], v[34:49]
	ds_read_b128 v[146:149], v220 offset:26752
	global_load_dwordx4 v[216:219], v229, s[10:11]
	s_add_u32 s10, s10, 0x80
	s_addc_u32 s11, s11, 0
	v_add_f32_e32 v231, v231, v70
	v_add_f32_e32 v232, v232, v71
	v_add_f32_e32 v231, v231, v72
	v_add_f32_e32 v232, v232, v73
	v_cvt_pk_bf16_f32 v66, v66, v67
	v_cvt_pk_bf16_f32 v67, v68, v69
	s_waitcnt lgkmcnt(5)
	v_mfma_f32_32x32x16_bf16 v[50:65], v[150:153], v[102:105], v[50:65]
	ds_read_b128 v[150:153], v220 offset:33408
	v_cvt_pk_bf16_f32 v68, v70, v71
	v_cvt_pk_bf16_f32 v69, v72, v73
	v_exp_f32_e32 v74, v74
	v_exp_f32_e32 v75, v75
	s_waitcnt lgkmcnt(5)
	v_mfma_f32_32x32x16_bf16 v[34:49], v[154:157], v[106:109], v[34:49]
	ds_read_b128 v[154:157], v220 offset:26784
	v_exp_f32_e32 v76, v76
	v_exp_f32_e32 v77, v77
	v_add_f32_e32 v231, v231, v74
	v_add_f32_e32 v232, v232, v75
	s_waitcnt lgkmcnt(5)
	v_mfma_f32_32x32x16_bf16 v[50:65], v[158:161], v[106:109], v[50:65]
	ds_read_b128 v[158:161], v220 offset:33440
	v_exp_f32_e32 v78, v78
	v_exp_f32_e32 v79, v79
	v_add_f32_e32 v231, v231, v76
	v_add_f32_e32 v232, v232, v77
	v_exp_f32_e32 v80, v80
	s_waitcnt lgkmcnt(5)
	v_mfma_f32_32x32x16_bf16 v[34:49], v[138:141], v[110:113], v[34:49]
	ds_read_b64 v[162:163], v221 offset:8704
	ds_read_b64 v[164:165], v221 offset:8720
	v_exp_f32_e32 v81, v81
	v_add_f32_e32 v231, v231, v78
	v_add_f32_e32 v232, v232, v79
	v_add_f32_e32 v231, v231, v80
	s_waitcnt lgkmcnt(6)
	v_mfma_f32_32x32x16_bf16 v[50:65], v[142:145], v[110:113], v[50:65]
	ds_read_b64 v[166:167], v221 offset:13056
	ds_read_b64 v[168:169], v221 offset:13072
	v_add_f32_e32 v232, v232, v81
	v_cvt_pk_bf16_f32 v74, v74, v75
	v_cvt_pk_bf16_f32 v75, v76, v77
	v_cvt_pk_bf16_f32 v76, v78, v79
	v_cvt_pk_bf16_f32 v77, v80, v81
	v_exp_f32_e32 v82, v82
	s_waitcnt lgkmcnt(7)
	v_mfma_f32_32x32x16_bf16 v[34:49], v[146:149], v[114:117], v[34:49]
	ds_read_b64 v[170:171], v221 offset:8736
	ds_read_b64 v[172:173], v221 offset:8752
	v_exp_f32_e32 v83, v83
	v_exp_f32_e32 v84, v84
	v_exp_f32_e32 v85, v85
	s_waitcnt lgkmcnt(8)
	v_mfma_f32_32x32x16_bf16 v[50:65], v[150:153], v[114:117], v[50:65]
	ds_read_b64 v[174:175], v221 offset:13088
	ds_read_b64 v[176:177], v221 offset:13104
	v_add_f32_e32 v231, v231, v82
	v_add_f32_e32 v232, v232, v83
	v_exp_f32_e32 v86, v86
	v_exp_f32_e32 v87, v87
	s_waitcnt lgkmcnt(9)
	v_mfma_f32_32x32x16_bf16 v[34:49], v[154:157], v[118:121], v[34:49]
	ds_read_b64 v[180:181], v221 offset:8768
	ds_read_b64 v[182:183], v221 offset:8784
	v_add_f32_e32 v231, v231, v84
	v_add_f32_e32 v232, v232, v85
	v_exp_f32_e32 v88, v88
	v_exp_f32_e32 v89, v89
	s_waitcnt lgkmcnt(10)
	v_mfma_f32_32x32x16_bf16 v[50:65], v[158:161], v[118:121], v[50:65]
	ds_read_b64 v[184:185], v221 offset:13120
	ds_read_b64 v[186:187], v221 offset:13136
	v_add_f32_e32 v231, v231, v86
	v_add_f32_e32 v232, v232, v87
	v_add_f32_e32 v231, v231, v88
	v_add_f32_e32 v232, v232, v89
	v_cvt_pk_bf16_f32 v82, v82, v83
	v_cvt_pk_bf16_f32 v83, v84, v85
	v_cvt_pk_bf16_f32 v84, v86, v87
	s_waitcnt lgkmcnt(10)
	s_nop 1
	v_mfma_f32_32x32x16_bf16 v[2:17], v[162:165], v[66:69], v[2:17]
	ds_read_b64 v[188:189], v221 offset:8800
	ds_read_b64 v[190:191], v221 offset:8816
	v_cvt_pk_bf16_f32 v85, v88, v89
	v_exp_f32_e32 v90, v90
	v_exp_f32_e32 v91, v91
	v_exp_f32_e32 v92, v92
	s_waitcnt lgkmcnt(10)
	v_mfma_f32_32x32x16_bf16 v[18:33], v[166:169], v[66:69], v[18:33]
	ds_read_b64 v[192:193], v221 offset:13152
	ds_read_b64 v[194:195], v221 offset:13168
	v_exp_f32_e32 v93, v93
	v_add_f32_e32 v231, v231, v90
	v_add_f32_e32 v232, v232, v91
	v_exp_f32_e32 v94, v94
	s_waitcnt lgkmcnt(10)
	v_mfma_f32_32x32x16_bf16 v[2:17], v[170:173], v[74:77], v[2:17]
	v_exp_f32_e32 v95, v95
	v_add_f32_e32 v231, v231, v92
	v_add_f32_e32 v232, v232, v93
	v_exp_f32_e32 v96, v96
	s_waitcnt lgkmcnt(8)
	v_mfma_f32_32x32x16_bf16 v[18:33], v[174:177], v[74:77], v[18:33]
	s_waitcnt vmcnt(1)
	ds_write_b128 v222, v[200:203] offset:0
	ds_write_b128 v223, v[204:207] offset:0
	ds_write_b128 v224, v[208:211] offset:0
	ds_write_b64 v225, v[212:213] offset:26112
	ds_write_b64 v225, v[214:215] offset:26120
	v_exp_f32_e32 v97, v97
	v_add_f32_e32 v231, v231, v94
	v_add_f32_e32 v232, v232, v95
	v_add_f32_e32 v231, v231, v96
	v_add_f32_e32 v232, v232, v97
	s_waitcnt lgkmcnt(11)
	v_mfma_f32_32x32x16_bf16 v[2:17], v[180:183], v[82:85], v[2:17]
	v_cvt_pk_bf16_f32 v90, v90, v91
	v_cvt_pk_bf16_f32 v91, v92, v93
	v_cvt_pk_bf16_f32 v92, v94, v95
	v_cvt_pk_bf16_f32 v93, v96, v97
	v_max3_f32 v234, v34, v35, v36
	v_max3_f32 v235, v50, v51, v52
	s_waitcnt lgkmcnt(9)
	v_mfma_f32_32x32x16_bf16 v[18:33], v[184:187], v[82:85], v[18:33]
	v_max3_f32 v234, v234, v37, v38
	v_max3_f32 v235, v235, v53, v54
	v_max3_f32 v234, v234, v39, v40
	v_max3_f32 v235, v235, v55, v56
	v_max3_f32 v234, v234, v41, v42
	v_max3_f32 v235, v235, v57, v58
	v_max3_f32 v234, v234, v43, v44
	s_waitcnt lgkmcnt(7)
	v_mfma_f32_32x32x16_bf16 v[2:17], v[188:191], v[90:93], v[2:17]
	v_max3_f32 v235, v235, v59, v60
	v_max3_f32 v234, v234, v45, v46
	v_max3_f32 v235, v235, v61, v62
	v_max3_f32 v234, v234, v47, v48
	v_max3_f32 v235, v235, v63, v64
	v_max3_f32 v234, v234, v49, v65
	s_waitcnt lgkmcnt(5)
	v_mfma_f32_32x32x16_bf16 v[18:33], v[192:195], v[90:93], v[18:33]
	v_max_f32_e32 v234, v234, v235
	v_mov_b32_e32 v235, v234
	s_nop 1
	v_permlane32_swap_b32_e32 v234, v235
	v_max_f32_e32 v233, v234, v235
	v_cmp_lt_f32_e32 vcc, 4.0, v233
	s_cbranch_vccz .Lmla_nr_p1
	s_nop 15
	v_max_f32_e32 v234, 0, v233
	v_exp_f32_e64 v235, -v234
	v_add_f32_e32 v230, v230, v234
	v_sub_f32_e32 v34, v34, v234
	v_sub_f32_e32 v35, v35, v234
	v_sub_f32_e32 v36, v36, v234
	v_sub_f32_e32 v37, v37, v234
	v_sub_f32_e32 v38, v38, v234
	v_sub_f32_e32 v39, v39, v234
	v_sub_f32_e32 v40, v40, v234
	v_sub_f32_e32 v41, v41, v234
	v_sub_f32_e32 v42, v42, v234
	v_sub_f32_e32 v43, v43, v234
	v_sub_f32_e32 v44, v44, v234
	v_sub_f32_e32 v45, v45, v234
	v_sub_f32_e32 v46, v46, v234
	v_sub_f32_e32 v47, v47, v234
	v_sub_f32_e32 v48, v48, v234
	v_sub_f32_e32 v49, v49, v234
	v_sub_f32_e32 v50, v50, v234
	v_sub_f32_e32 v51, v51, v234
	v_sub_f32_e32 v52, v52, v234
	v_sub_f32_e32 v53, v53, v234
	v_sub_f32_e32 v54, v54, v234
	v_sub_f32_e32 v55, v55, v234
	v_sub_f32_e32 v56, v56, v234
	v_sub_f32_e32 v57, v57, v234
	v_sub_f32_e32 v58, v58, v234
	v_sub_f32_e32 v59, v59, v234
	v_sub_f32_e32 v60, v60, v234
	v_sub_f32_e32 v61, v61, v234
	v_sub_f32_e32 v62, v62, v234
	v_sub_f32_e32 v63, v63, v234
	v_sub_f32_e32 v64, v64, v234
	v_sub_f32_e32 v65, v65, v234
	v_mul_f32_e32 v231, v231, v235
	v_mul_f32_e32 v232, v232, v235
	v_mul_f32_e32 v2, v2, v235
	v_mul_f32_e32 v3, v3, v235
	v_mul_f32_e32 v4, v4, v235
	v_mul_f32_e32 v5, v5, v235
	v_mul_f32_e32 v6, v6, v235
	v_mul_f32_e32 v7, v7, v235
	v_mul_f32_e32 v8, v8, v235
	v_mul_f32_e32 v9, v9, v235
	v_mul_f32_e32 v10, v10, v235
	v_mul_f32_e32 v11, v11, v235
	v_mul_f32_e32 v12, v12, v235
	v_mul_f32_e32 v13, v13, v235
	v_mul_f32_e32 v14, v14, v235
	v_mul_f32_e32 v15, v15, v235
	v_mul_f32_e32 v16, v16, v235
	v_mul_f32_e32 v17, v17, v235
	v_mul_f32_e32 v18, v18, v235
	v_mul_f32_e32 v19, v19, v235
	v_mul_f32_e32 v20, v20, v235
	v_mul_f32_e32 v21, v21, v235
	v_mul_f32_e32 v22, v22, v235
	v_mul_f32_e32 v23, v23, v235
	v_mul_f32_e32 v24, v24, v235
	v_mul_f32_e32 v25, v25, v235
	v_mul_f32_e32 v26, v26, v235
	v_mul_f32_e32 v27, v27, v235
	v_mul_f32_e32 v28, v28, v235
	v_mul_f32_e32 v29, v29, v235
	v_mul_f32_e32 v30, v30, v235
	v_mul_f32_e32 v31, v31, v235
	v_mul_f32_e32 v32, v32, v235
	v_mul_f32_e32 v33, v33, v235
	v_sub_f32_e32 v122, 0, v230
	v_mov_b32_e32 v123, v122
	v_mov_b32_e32 v124, v122
	v_mov_b32_e32 v125, v122
	v_mov_b32_e32 v126, v122
	v_mov_b32_e32 v127, v122
	v_mov_b32_e32 v128, v122
	v_mov_b32_e32 v129, v122
	v_mov_b32_e32 v130, v122
	v_mov_b32_e32 v131, v122
	v_mov_b32_e32 v132, v122
	v_mov_b32_e32 v133, v122
	v_mov_b32_e32 v134, v122
	v_mov_b32_e32 v135, v122
	v_mov_b32_e32 v136, v122
	v_mov_b32_e32 v137, v122
.Lmla_nr_p1:
	ds_read_b128 v[138:141], v220 offset:39936
	ds_read_b128 v[142:145], v220 offset:46592
	ds_read_b128 v[146:149], v220 offset:39968
	ds_read_b128 v[150:153], v220 offset:46624
	ds_read_b128 v[154:157], v220 offset:40000
	ds_read_b128 v[158:161], v220 offset:46656
	s_waitcnt lgkmcnt(6)
	s_barrier
	v_exp_f32_e32 v34, v34
	v_exp_f32_e32 v35, v35
	v_exp_f32_e32 v36, v36
	v_exp_f32_e32 v37, v37
	s_waitcnt lgkmcnt(5)
	v_mfma_f32_32x32x16_bf16 v[66:81], v[138:141], v[98:101], v[122:137]
	ds_read_b128 v[138:141], v220 offset:40032
	v_add_f32_e32 v231, v231, v34
	v_add_f32_e32 v232, v232, v35
	v_exp_f32_e32 v38, v38
	v_exp_f32_e32 v39, v39
	s_waitcnt lgkmcnt(5)
	v_mfma_f32_32x32x16_bf16 v[82:97], v[142:145], v[98:101], v[122:137]
	ds_read_b128 v[142:145], v220 offset:46688
	v_add_f32_e32 v231, v231, v36
	v_add_f32_e32 v232, v232, v37
	v_exp_f32_e32 v40, v40
	v_exp_f32_e32 v41, v41
	s_waitcnt lgkmcnt(5)
	v_mfma_f32_32x32x16_bf16 v[66:81], v[146:149], v[102:105], v[66:81]
	ds_read_b128 v[146:149], v220 offset:40064
	global_load_dwordx4 v[200:203], v226, s[4:5]
	global_load_dwordx4 v[204:207], v227, s[4:5]
	global_load_dwordx4 v[208:211], v228, s[4:5]
	s_add_u32 s4, s4, 0x6000
	s_addc_u32 s5, s5, 0
	global_load_dwordx4 v[212:215], v229, s[10:11]
	s_add_u32 s10, s10, 0x80
	s_addc_u32 s11, s11, 0
	v_add_f32_e32 v231, v231, v38
	v_add_f32_e32 v232, v232, v39
	v_add_f32_e32 v231, v231, v40
	v_add_f32_e32 v232, v232, v41
	v_cvt_pk_bf16_f32 v34, v34, v35
	v_cvt_pk_bf16_f32 v35, v36, v37
	s_waitcnt lgkmcnt(5)
	v_mfma_f32_32x32x16_bf16 v[82:97], v[150:153], v[102:105], v[82:97]
	ds_read_b128 v[150:153], v220 offset:46720
	v_cvt_pk_bf16_f32 v36, v38, v39
	v_cvt_pk_bf16_f32 v37, v40, v41
	v_exp_f32_e32 v42, v42
	v_exp_f32_e32 v43, v43
	s_waitcnt lgkmcnt(5)
	v_mfma_f32_32x32x16_bf16 v[66:81], v[154:157], v[106:109], v[66:81]
	ds_read_b128 v[154:157], v220 offset:40096
	v_exp_f32_e32 v44, v44
	v_exp_f32_e32 v45, v45
	v_add_f32_e32 v231, v231, v42
	v_add_f32_e32 v232, v232, v43
	s_waitcnt lgkmcnt(5)
	v_mfma_f32_32x32x16_bf16 v[82:97], v[158:161], v[106:109], v[82:97]
	ds_read_b128 v[158:161], v220 offset:46752
	v_exp_f32_e32 v46, v46
	v_exp_f32_e32 v47, v47
	v_add_f32_e32 v231, v231, v44
	v_add_f32_e32 v232, v232, v45
	v_exp_f32_e32 v48, v48
	s_waitcnt lgkmcnt(5)
	v_mfma_f32_32x32x16_bf16 v[66:81], v[138:141], v[110:113], v[66:81]
	ds_read_b64 v[162:163], v221 offset:17408
	ds_read_b64 v[164:165], v221 offset:17424
	v_exp_f32_e32 v49, v49
	v_add_f32_e32 v231, v231, v46
	v_add_f32_e32 v232, v232, v47
	v_add_f32_e32 v231, v231, v48
	s_waitcnt lgkmcnt(6)
	v_mfma_f32_32x32x16_bf16 v[82:97], v[142:145], v[110:113], v[82:97]
	ds_read_b64 v[166:167], v221 offset:21760
	ds_read_b64 v[168:169], v221 offset:21776
	v_add_f32_e32 v232, v232, v49
	v_cvt_pk_bf16_f32 v42, v42, v43
	v_cvt_pk_bf16_f32 v43, v44, v45
	v_cvt_pk_bf16_f32 v44, v46, v47
	v_cvt_pk_bf16_f32 v45, v48, v49
	v_exp_f32_e32 v50, v50
	s_waitcnt lgkmcnt(7)
	v_mfma_f32_32x32x16_bf16 v[66:81], v[146:149], v[114:117], v[66:81]
	ds_read_b64 v[170:171], v221 offset:17440
	ds_read_b64 v[172:173], v221 offset:17456
	v_exp_f32_e32 v51, v51
	v_exp_f32_e32 v52, v52
	v_exp_f32_e32 v53, v53
	s_waitcnt lgkmcnt(8)
	v_mfma_f32_32x32x16_bf16 v[82:97], v[150:153], v[114:117], v[82:97]
	ds_read_b64 v[174:175], v221 offset:21792
	ds_read_b64 v[176:177], v221 offset:21808
	v_add_f32_e32 v231, v231, v50
	v_add_f32_e32 v232, v232, v51
	v_exp_f32_e32 v54, v54
	v_exp_f32_e32 v55, v55
	s_waitcnt lgkmcnt(9)
	v_mfma_f32_32x32x16_bf16 v[66:81], v[154:157], v[118:121], v[66:81]
	ds_read_b64 v[180:181], v221 offset:17472
	ds_read_b64 v[182:183], v221 offset:17488
	v_add_f32_e32 v231, v231, v52
	v_add_f32_e32 v232, v232, v53
	v_exp_f32_e32 v56, v56
	v_exp_f32_e32 v57, v57
	s_waitcnt lgkmcnt(10)
	v_mfma_f32_32x32x16_bf16 v[82:97], v[158:161], v[118:121], v[82:97]
	ds_read_b64 v[184:185], v221 offset:21824
	ds_read_b64 v[186:187], v221 offset:21840
	v_add_f32_e32 v231, v231, v54
	v_add_f32_e32 v232, v232, v55
	v_add_f32_e32 v231, v231, v56
	v_add_f32_e32 v232, v232, v57
	v_cvt_pk_bf16_f32 v50, v50, v51
	v_cvt_pk_bf16_f32 v51, v52, v53
	v_cvt_pk_bf16_f32 v52, v54, v55
	s_waitcnt lgkmcnt(10)
	s_nop 1
	v_mfma_f32_32x32x16_bf16 v[2:17], v[162:165], v[34:37], v[2:17]
	ds_read_b64 v[188:189], v221 offset:17504
	ds_read_b64 v[190:191], v221 offset:17520
	v_cvt_pk_bf16_f32 v53, v56, v57
	v_exp_f32_e32 v58, v58
	v_exp_f32_e32 v59, v59
	v_exp_f32_e32 v60, v60
	s_waitcnt lgkmcnt(10)
	v_mfma_f32_32x32x16_bf16 v[18:33], v[166:169], v[34:37], v[18:33]
	ds_read_b64 v[192:193], v221 offset:21856
	ds_read_b64 v[194:195], v221 offset:21872
	v_exp_f32_e32 v61, v61
	v_add_f32_e32 v231, v231, v58
	v_add_f32_e32 v232, v232, v59
	v_exp_f32_e32 v62, v62
	s_waitcnt lgkmcnt(10)
	v_mfma_f32_32x32x16_bf16 v[2:17], v[170:173], v[42:45], v[2:17]
	v_exp_f32_e32 v63, v63
	v_add_f32_e32 v231, v231, v60
	v_add_f32_e32 v232, v232, v61
	v_exp_f32_e32 v64, v64
	s_waitcnt lgkmcnt(8)
	v_mfma_f32_32x32x16_bf16 v[18:33], v[174:177], v[42:45], v[18:33]
	s_waitcnt vmcnt(4)
	ds_write_b64 v225, v[216:217] offset:0
	ds_write_b64 v225, v[218:219] offset:8
	v_exp_f32_e32 v65, v65
	v_add_f32_e32 v231, v231, v62
	v_add_f32_e32 v232, v232, v63
	v_add_f32_e32 v231, v231, v64
	v_add_f32_e32 v232, v232, v65
	s_waitcnt lgkmcnt(8)
	v_mfma_f32_32x32x16_bf16 v[2:17], v[180:183], v[50:53], v[2:17]
	v_cvt_pk_bf16_f32 v58, v58, v59
	v_cvt_pk_bf16_f32 v59, v60, v61
	v_cvt_pk_bf16_f32 v60, v62, v63
	v_cvt_pk_bf16_f32 v61, v64, v65
	v_max3_f32 v234, v66, v67, v68
	v_max3_f32 v235, v82, v83, v84
	s_waitcnt lgkmcnt(6)
	v_mfma_f32_32x32x16_bf16 v[18:33], v[184:187], v[50:53], v[18:33]
	v_max3_f32 v234, v234, v69, v70
	v_max3_f32 v235, v235, v85, v86
	v_max3_f32 v234, v234, v71, v72
	v_max3_f32 v235, v235, v87, v88
	v_max3_f32 v234, v234, v73, v74
	v_max3_f32 v235, v235, v89, v90
	v_max3_f32 v234, v234, v75, v76
	s_waitcnt lgkmcnt(4)
	v_mfma_f32_32x32x16_bf16 v[2:17], v[188:191], v[58:61], v[2:17]
	v_max3_f32 v235, v235, v91, v92
	v_max3_f32 v234, v234, v77, v78
	v_max3_f32 v235, v235, v93, v94
	v_max3_f32 v234, v234, v79, v80
	v_max3_f32 v235, v235, v95, v96
	v_max3_f32 v234, v234, v81, v97
	s_waitcnt lgkmcnt(2)
	v_mfma_f32_32x32x16_bf16 v[18:33], v[192:195], v[58:61], v[18:33]
	v_max_f32_e32 v234, v234, v235
	v_mov_b32_e32 v235, v234
	s_nop 1
	v_permlane32_swap_b32_e32 v234, v235
	v_max_f32_e32 v233, v234, v235
	v_cmp_lt_f32_e32 vcc, 4.0, v233
	s_cbranch_vccz .Lmla_nr_p2
	s_nop 15
	v_max_f32_e32 v234, 0, v233
	v_exp_f32_e64 v235, -v234
	v_add_f32_e32 v230, v230, v234
	v_sub_f32_e32 v66, v66, v234
	v_sub_f32_e32 v67, v67, v234
	v_sub_f32_e32 v68, v68, v234
	v_sub_f32_e32 v69, v69, v234
	v_sub_f32_e32 v70, v70, v234
	v_sub_f32_e32 v71, v71, v234
	v_sub_f32_e32 v72, v72, v234
	v_sub_f32_e32 v73, v73, v234
	v_sub_f32_e32 v74, v74, v234
	v_sub_f32_e32 v75, v75, v234
	v_sub_f32_e32 v76, v76, v234
	v_sub_f32_e32 v77, v77, v234
	v_sub_f32_e32 v78, v78, v234
	v_sub_f32_e32 v79, v79, v234
	v_sub_f32_e32 v80, v80, v234
	v_sub_f32_e32 v81, v81, v234
	v_sub_f32_e32 v82, v82, v234
	v_sub_f32_e32 v83, v83, v234
	v_sub_f32_e32 v84, v84, v234
	v_sub_f32_e32 v85, v85, v234
	v_sub_f32_e32 v86, v86, v234
	v_sub_f32_e32 v87, v87, v234
	v_sub_f32_e32 v88, v88, v234
	v_sub_f32_e32 v89, v89, v234
	v_sub_f32_e32 v90, v90, v234
	v_sub_f32_e32 v91, v91, v234
	v_sub_f32_e32 v92, v92, v234
	v_sub_f32_e32 v93, v93, v234
	v_sub_f32_e32 v94, v94, v234
	v_sub_f32_e32 v95, v95, v234
	v_sub_f32_e32 v96, v96, v234
	v_sub_f32_e32 v97, v97, v234
	v_mul_f32_e32 v231, v231, v235
	v_mul_f32_e32 v232, v232, v235
	v_mul_f32_e32 v2, v2, v235
	v_mul_f32_e32 v3, v3, v235
	v_mul_f32_e32 v4, v4, v235
	v_mul_f32_e32 v5, v5, v235
	v_mul_f32_e32 v6, v6, v235
	v_mul_f32_e32 v7, v7, v235
	v_mul_f32_e32 v8, v8, v235
	v_mul_f32_e32 v9, v9, v235
	v_mul_f32_e32 v10, v10, v235
	v_mul_f32_e32 v11, v11, v235
	v_mul_f32_e32 v12, v12, v235
	v_mul_f32_e32 v13, v13, v235
	v_mul_f32_e32 v14, v14, v235
	v_mul_f32_e32 v15, v15, v235
	v_mul_f32_e32 v16, v16, v235
	v_mul_f32_e32 v17, v17, v235
	v_mul_f32_e32 v18, v18, v235
	v_mul_f32_e32 v19, v19, v235
	v_mul_f32_e32 v20, v20, v235
	v_mul_f32_e32 v21, v21, v235
	v_mul_f32_e32 v22, v22, v235
	v_mul_f32_e32 v23, v23, v235
	v_mul_f32_e32 v24, v24, v235
	v_mul_f32_e32 v25, v25, v235
	v_mul_f32_e32 v26, v26, v235
	v_mul_f32_e32 v27, v27, v235
	v_mul_f32_e32 v28, v28, v235
	v_mul_f32_e32 v29, v29, v235
	v_mul_f32_e32 v30, v30, v235
	v_mul_f32_e32 v31, v31, v235
	v_mul_f32_e32 v32, v32, v235
	v_mul_f32_e32 v33, v33, v235
	v_sub_f32_e32 v122, 0, v230
	v_mov_b32_e32 v123, v122
	v_mov_b32_e32 v124, v122
	v_mov_b32_e32 v125, v122
	v_mov_b32_e32 v126, v122
	v_mov_b32_e32 v127, v122
	v_mov_b32_e32 v128, v122
	v_mov_b32_e32 v129, v122
	v_mov_b32_e32 v130, v122
	v_mov_b32_e32 v131, v122
	v_mov_b32_e32 v132, v122
	v_mov_b32_e32 v133, v122
	v_mov_b32_e32 v134, v122
	v_mov_b32_e32 v135, v122
	v_mov_b32_e32 v136, v122
	v_mov_b32_e32 v137, v122
.Lmla_nr_p2:
	ds_read_b128 v[138:141], v220 offset:0
	ds_read_b128 v[142:145], v220 offset:6656
	ds_read_b128 v[146:149], v220 offset:32
	ds_read_b128 v[150:153], v220 offset:6688
	ds_read_b128 v[154:157], v220 offset:64
	ds_read_b128 v[158:161], v220 offset:6720
	s_waitcnt lgkmcnt(6)
	s_barrier
	v_exp_f32_e32 v66, v66
	v_exp_f32_e32 v67, v67
	v_exp_f32_e32 v68, v68
	v_exp_f32_e32 v69, v69
	s_waitcnt lgkmcnt(5)
	v_mfma_f32_32x32x16_bf16 v[34:49], v[138:141], v[98:101], v[122:137]
	ds_read_b128 v[138:141], v220 offset:96
	v_add_f32_e32 v231, v231, v66
	v_add_f32_e32 v232, v232, v67
	v_exp_f32_e32 v70, v70
	v_exp_f32_e32 v71, v71
	s_waitcnt lgkmcnt(5)
	v_mfma_f32_32x32x16_bf16 v[50:65], v[142:145], v[98:101], v[122:137]
	ds_read_b128 v[142:145], v220 offset:6752
	v_add_f32_e32 v231, v231, v68
	v_add_f32_e32 v232, v232, v69
	v_exp_f32_e32 v72, v72
	v_exp_f32_e32 v73, v73
	s_waitcnt lgkmcnt(5)
	v_mfma_f32_32x32x16_bf16 v[34:49], v[146:149], v[102:105], v[34:49]
	ds_read_b128 v[146:149], v220 offset:128
	global_load_dwordx4 v[216:219], v229, s[10:11]
	s_add_u32 s10, s10, 0x80
	s_addc_u32 s11, s11, 0
	v_add_f32_e32 v231, v231, v70
	v_add_f32_e32 v232, v232, v71
	v_add_f32_e32 v231, v231, v72
	v_add_f32_e32 v232, v232, v73
	v_cvt_pk_bf16_f32 v66, v66, v67
	v_cvt_pk_bf16_f32 v67, v68, v69
	s_waitcnt lgkmcnt(5)
	v_mfma_f32_32x32x16_bf16 v[50:65], v[150:153], v[102:105], v[50:65]
	ds_read_b128 v[150:153], v220 offset:6784
	v_cvt_pk_bf16_f32 v68, v70, v71
	v_cvt_pk_bf16_f32 v69, v72, v73
	v_exp_f32_e32 v74, v74
	v_exp_f32_e32 v75, v75
	s_waitcnt lgkmcnt(5)
	v_mfma_f32_32x32x16_bf16 v[34:49], v[154:157], v[106:109], v[34:49]
	ds_read_b128 v[154:157], v220 offset:160
	v_exp_f32_e32 v76, v76
	v_exp_f32_e32 v77, v77
	v_add_f32_e32 v231, v231, v74
	v_add_f32_e32 v232, v232, v75
	s_waitcnt lgkmcnt(5)
	v_mfma_f32_32x32x16_bf16 v[50:65], v[158:161], v[106:109], v[50:65]
	ds_read_b128 v[158:161], v220 offset:6816
	v_exp_f32_e32 v78, v78
	v_exp_f32_e32 v79, v79
	v_add_f32_e32 v231, v231, v76
	v_add_f32_e32 v232, v232, v77
	v_exp_f32_e32 v80, v80
	s_waitcnt lgkmcnt(5)
	v_mfma_f32_32x32x16_bf16 v[34:49], v[138:141], v[110:113], v[34:49]
	ds_read_b64 v[162:163], v221 offset:26112
	ds_read_b64 v[164:165], v221 offset:26128
	v_exp_f32_e32 v81, v81
	v_add_f32_e32 v231, v231, v78
	v_add_f32_e32 v232, v232, v79
	v_add_f32_e32 v231, v231, v80
	s_waitcnt lgkmcnt(6)
	v_mfma_f32_32x32x16_bf16 v[50:65], v[142:145], v[110:113], v[50:65]
	ds_read_b64 v[166:167], v221 offset:30464
	ds_read_b64 v[168:169], v221 offset:30480
	v_add_f32_e32 v232, v232, v81
	v_cvt_pk_bf16_f32 v74, v74, v75
	v_cvt_pk_bf16_f32 v75, v76, v77
	v_cvt_pk_bf16_f32 v76, v78, v79
	v_cvt_pk_bf16_f32 v77, v80, v81
	v_exp_f32_e32 v82, v82
	s_waitcnt lgkmcnt(7)
	v_mfma_f32_32x32x16_bf16 v[34:49], v[146:149], v[114:117], v[34:49]
	ds_read_b64 v[170:171], v221 offset:26144
	ds_read_b64 v[172:173], v221 offset:26160
	v_exp_f32_e32 v83, v83
	v_exp_f32_e32 v84, v84
	v_exp_f32_e32 v85, v85
	s_waitcnt lgkmcnt(8)
	v_mfma_f32_32x32x16_bf16 v[50:65], v[150:153], v[114:117], v[50:65]
	ds_read_b64 v[174:175], v221 offset:30496
	ds_read_b64 v[176:177], v221 offset:30512
	v_add_f32_e32 v231, v231, v82
	v_add_f32_e32 v232, v232, v83
	v_exp_f32_e32 v86, v86
	v_exp_f32_e32 v87, v87
	s_waitcnt lgkmcnt(9)
	v_mfma_f32_32x32x16_bf16 v[34:49], v[154:157], v[118:121], v[34:49]
	ds_read_b64 v[180:181], v221 offset:26176
	ds_read_b64 v[182:183], v221 offset:26192
	v_add_f32_e32 v231, v231, v84
	v_add_f32_e32 v232, v232, v85
	v_exp_f32_e32 v88, v88
	v_exp_f32_e32 v89, v89
	s_waitcnt lgkmcnt(10)
	v_mfma_f32_32x32x16_bf16 v[50:65], v[158:161], v[118:121], v[50:65]
	ds_read_b64 v[184:185], v221 offset:30528
	ds_read_b64 v[186:187], v221 offset:30544
	v_add_f32_e32 v231, v231, v86
	v_add_f32_e32 v232, v232, v87
	v_add_f32_e32 v231, v231, v88
	v_add_f32_e32 v232, v232, v89
	v_cvt_pk_bf16_f32 v82, v82, v83
	v_cvt_pk_bf16_f32 v83, v84, v85
	v_cvt_pk_bf16_f32 v84, v86, v87
	s_waitcnt lgkmcnt(10)
	s_nop 1
	v_mfma_f32_32x32x16_bf16 v[2:17], v[162:165], v[66:69], v[2:17]
	ds_read_b64 v[188:189], v221 offset:26208
	ds_read_b64 v[190:191], v221 offset:26224
	v_cvt_pk_bf16_f32 v85, v88, v89
	v_exp_f32_e32 v90, v90
	v_exp_f32_e32 v91, v91
	v_exp_f32_e32 v92, v92
	s_waitcnt lgkmcnt(10)
	v_mfma_f32_32x32x16_bf16 v[18:33], v[166:169], v[66:69], v[18:33]
	ds_read_b64 v[192:193], v221 offset:30560
	ds_read_b64 v[194:195], v221 offset:30576
	v_exp_f32_e32 v93, v93
	v_add_f32_e32 v231, v231, v90
	v_add_f32_e32 v232, v232, v91
	v_exp_f32_e32 v94, v94
	s_waitcnt lgkmcnt(10)
	v_mfma_f32_32x32x16_bf16 v[2:17], v[170:173], v[74:77], v[2:17]
	v_exp_f32_e32 v95, v95
	v_add_f32_e32 v231, v231, v92
	v_add_f32_e32 v232, v232, v93
	v_exp_f32_e32 v96, v96
	s_waitcnt lgkmcnt(8)
	v_mfma_f32_32x32x16_bf16 v[18:33], v[174:177], v[74:77], v[18:33]
	s_waitcnt vmcnt(1)
	ds_write_b128 v222, v[200:203] offset:26624
	ds_write_b128 v223, v[204:207] offset:26624
	ds_write_b128 v224, v[208:211] offset:26624
	ds_write_b64 v225, v[212:213] offset:8704
	ds_write_b64 v225, v[214:215] offset:8712
	v_exp_f32_e32 v97, v97
	v_add_f32_e32 v231, v231, v94
	v_add_f32_e32 v232, v232, v95
	v_add_f32_e32 v231, v231, v96
	v_add_f32_e32 v232, v232, v97
	s_waitcnt lgkmcnt(11)
	v_mfma_f32_32x32x16_bf16 v[2:17], v[180:183], v[82:85], v[2:17]
	v_cvt_pk_bf16_f32 v90, v90, v91
	v_cvt_pk_bf16_f32 v91, v92, v93
	v_cvt_pk_bf16_f32 v92, v94, v95
	v_cvt_pk_bf16_f32 v93, v96, v97
	v_max3_f32 v234, v34, v35, v36
	v_max3_f32 v235, v50, v51, v52
	s_waitcnt lgkmcnt(9)
	v_mfma_f32_32x32x16_bf16 v[18:33], v[184:187], v[82:85], v[18:33]
	v_max3_f32 v234, v234, v37, v38
	v_max3_f32 v235, v235, v53, v54
	v_max3_f32 v234, v234, v39, v40
	v_max3_f32 v235, v235, v55, v56
	v_max3_f32 v234, v234, v41, v42
	v_max3_f32 v235, v235, v57, v58
	v_max3_f32 v234, v234, v43, v44
	s_waitcnt lgkmcnt(7)
	v_mfma_f32_32x32x16_bf16 v[2:17], v[188:191], v[90:93], v[2:17]
	v_max3_f32 v235, v235, v59, v60
	v_max3_f32 v234, v234, v45, v46
	v_max3_f32 v235, v235, v61, v62
	v_max3_f32 v234, v234, v47, v48
	v_max3_f32 v235, v235, v63, v64
	v_max3_f32 v234, v234, v49, v65
	s_waitcnt lgkmcnt(5)
	v_mfma_f32_32x32x16_bf16 v[18:33], v[192:195], v[90:93], v[18:33]
	v_max_f32_e32 v234, v234, v235
	v_mov_b32_e32 v235, v234
	s_nop 1
	v_permlane32_swap_b32_e32 v234, v235
	v_max_f32_e32 v233, v234, v235
	v_cmp_lt_f32_e32 vcc, 4.0, v233
	s_cbranch_vccz .Lmla_nr_p3
	s_nop 15
	v_max_f32_e32 v234, 0, v233
	v_exp_f32_e64 v235, -v234
	v_add_f32_e32 v230, v230, v234
	v_sub_f32_e32 v34, v34, v234
	v_sub_f32_e32 v35, v35, v234
	v_sub_f32_e32 v36, v36, v234
	v_sub_f32_e32 v37, v37, v234
	v_sub_f32_e32 v38, v38, v234
	v_sub_f32_e32 v39, v39, v234
	v_sub_f32_e32 v40, v40, v234
	v_sub_f32_e32 v41, v41, v234
	v_sub_f32_e32 v42, v42, v234
	v_sub_f32_e32 v43, v43, v234
	v_sub_f32_e32 v44, v44, v234
	v_sub_f32_e32 v45, v45, v234
	v_sub_f32_e32 v46, v46, v234
	v_sub_f32_e32 v47, v47, v234
	v_sub_f32_e32 v48, v48, v234
	v_sub_f32_e32 v49, v49, v234
	v_sub_f32_e32 v50, v50, v234
	v_sub_f32_e32 v51, v51, v234
	v_sub_f32_e32 v52, v52, v234
	v_sub_f32_e32 v53, v53, v234
	v_sub_f32_e32 v54, v54, v234
	v_sub_f32_e32 v55, v55, v234
	v_sub_f32_e32 v56, v56, v234
	v_sub_f32_e32 v57, v57, v234
	v_sub_f32_e32 v58, v58, v234
	v_sub_f32_e32 v59, v59, v234
	v_sub_f32_e32 v60, v60, v234
	v_sub_f32_e32 v61, v61, v234
	v_sub_f32_e32 v62, v62, v234
	v_sub_f32_e32 v63, v63, v234
	v_sub_f32_e32 v64, v64, v234
	v_sub_f32_e32 v65, v65, v234
	v_mul_f32_e32 v231, v231, v235
	v_mul_f32_e32 v232, v232, v235
	v_mul_f32_e32 v2, v2, v235
	v_mul_f32_e32 v3, v3, v235
	v_mul_f32_e32 v4, v4, v235
	v_mul_f32_e32 v5, v5, v235
	v_mul_f32_e32 v6, v6, v235
	v_mul_f32_e32 v7, v7, v235
	v_mul_f32_e32 v8, v8, v235
	v_mul_f32_e32 v9, v9, v235
	v_mul_f32_e32 v10, v10, v235
	v_mul_f32_e32 v11, v11, v235
	v_mul_f32_e32 v12, v12, v235
	v_mul_f32_e32 v13, v13, v235
	v_mul_f32_e32 v14, v14, v235
	v_mul_f32_e32 v15, v15, v235
	v_mul_f32_e32 v16, v16, v235
	v_mul_f32_e32 v17, v17, v235
	v_mul_f32_e32 v18, v18, v235
	v_mul_f32_e32 v19, v19, v235
	v_mul_f32_e32 v20, v20, v235
	v_mul_f32_e32 v21, v21, v235
	v_mul_f32_e32 v22, v22, v235
	v_mul_f32_e32 v23, v23, v235
	v_mul_f32_e32 v24, v24, v235
	v_mul_f32_e32 v25, v25, v235
	v_mul_f32_e32 v26, v26, v235
	v_mul_f32_e32 v27, v27, v235
	v_mul_f32_e32 v28, v28, v235
	v_mul_f32_e32 v29, v29, v235
	v_mul_f32_e32 v30, v30, v235
	v_mul_f32_e32 v31, v31, v235
	v_mul_f32_e32 v32, v32, v235
	v_mul_f32_e32 v33, v33, v235
	v_sub_f32_e32 v122, 0, v230
	v_mov_b32_e32 v123, v122
	v_mov_b32_e32 v124, v122
	v_mov_b32_e32 v125, v122
	v_mov_b32_e32 v126, v122
	v_mov_b32_e32 v127, v122
	v_mov_b32_e32 v128, v122
	v_mov_b32_e32 v129, v122
	v_mov_b32_e32 v130, v122
	v_mov_b32_e32 v131, v122
	v_mov_b32_e32 v132, v122
	v_mov_b32_e32 v133, v122
	v_mov_b32_e32 v134, v122
	v_mov_b32_e32 v135, v122
	v_mov_b32_e32 v136, v122
	v_mov_b32_e32 v137, v122
.Lmla_nr_p3:
	ds_read_b128 v[138:141], v220 offset:13312
	ds_read_b128 v[142:145], v220 offset:19968
	ds_read_b128 v[146:149], v220 offset:13344
	ds_read_b128 v[150:153], v220 offset:20000
	ds_read_b128 v[154:157], v220 offset:13376
	ds_read_b128 v[158:161], v220 offset:20032
	s_waitcnt lgkmcnt(6)
	s_barrier
	s_add_i32 s16, s16, -1
	s_cmp_lg_u32 s16, 0
	s_cbranch_scc1 .Lmla_loop
	v_exp_f32_e32 v34, v34
	v_exp_f32_e32 v35, v35
	v_exp_f32_e32 v36, v36
	v_exp_f32_e32 v37, v37
	s_waitcnt lgkmcnt(5)
	v_mfma_f32_32x32x16_bf16 v[66:81], v[138:141], v[98:101], v[122:137]
	ds_read_b128 v[138:141], v220 offset:13408
	v_add_f32_e32 v231, v231, v34
	v_add_f32_e32 v232, v232, v35
	v_exp_f32_e32 v38, v38
	v_exp_f32_e32 v39, v39
	s_waitcnt lgkmcnt(5)
	v_mfma_f32_32x32x16_bf16 v[82:97], v[142:145], v[98:101], v[122:137]
	ds_read_b128 v[142:145], v220 offset:20064
	v_add_f32_e32 v231, v231, v36
	v_add_f32_e32 v232, v232, v37
	v_exp_f32_e32 v40, v40
	v_exp_f32_e32 v41, v41
	s_waitcnt lgkmcnt(5)
	v_mfma_f32_32x32x16_bf16 v[66:81], v[146:149], v[102:105], v[66:81]
	ds_read_b128 v[146:149], v220 offset:13440
	global_load_dwordx4 v[212:215], v229, s[10:11]
	s_add_u32 s10, s10, 0x80
	s_addc_u32 s11, s11, 0
	v_add_f32_e32 v231, v231, v38
	v_add_f32_e32 v232, v232, v39
	v_add_f32_e32 v231, v231, v40
	v_add_f32_e32 v232, v232, v41
	v_cvt_pk_bf16_f32 v34, v34, v35
	v_cvt_pk_bf16_f32 v35, v36, v37
	s_waitcnt lgkmcnt(5)
	v_mfma_f32_32x32x16_bf16 v[82:97], v[150:153], v[102:105], v[82:97]
	ds_read_b128 v[150:153], v220 offset:20096
	v_cvt_pk_bf16_f32 v36, v38, v39
	v_cvt_pk_bf16_f32 v37, v40, v41
	v_exp_f32_e32 v42, v42
	v_exp_f32_e32 v43, v43
	s_waitcnt lgkmcnt(5)
	v_mfma_f32_32x32x16_bf16 v[66:81], v[154:157], v[106:109], v[66:81]
	ds_read_b128 v[154:157], v220 offset:13472
	v_exp_f32_e32 v44, v44
	v_exp_f32_e32 v45, v45
	v_add_f32_e32 v231, v231, v42
	v_add_f32_e32 v232, v232, v43
	s_waitcnt lgkmcnt(5)
	v_mfma_f32_32x32x16_bf16 v[82:97], v[158:161], v[106:109], v[82:97]
	ds_read_b128 v[158:161], v220 offset:20128
	v_exp_f32_e32 v46, v46
	v_exp_f32_e32 v47, v47
	v_add_f32_e32 v231, v231, v44
	v_add_f32_e32 v232, v232, v45
	v_exp_f32_e32 v48, v48
	s_waitcnt lgkmcnt(5)
	v_mfma_f32_32x32x16_bf16 v[66:81], v[138:141], v[110:113], v[66:81]
	ds_read_b64 v[162:163], v221 offset:0
	ds_read_b64 v[164:165], v221 offset:16
	v_exp_f32_e32 v49, v49
	v_add_f32_e32 v231, v231, v46
	v_add_f32_e32 v232, v232, v47
	v_add_f32_e32 v231, v231, v48
	s_waitcnt lgkmcnt(6)
	v_mfma_f32_32x32x16_bf16 v[82:97], v[142:145], v[110:113], v[82:97]
	ds_read_b64 v[166:167], v221 offset:4352
	ds_read_b64 v[168:169], v221 offset:4368
	v_add_f32_e32 v232, v232, v49
	v_cvt_pk_bf16_f32 v42, v42, v43
	v_cvt_pk_bf16_f32 v43, v44, v45
	v_cvt_pk_bf16_f32 v44, v46, v47
	v_cvt_pk_bf16_f32 v45, v48, v49
	v_exp_f32_e32 v50, v50
	s_waitcnt lgkmcnt(7)
	v_mfma_f32_32x32x16_bf16 v[66:81], v[146:149], v[114:117], v[66:81]
	ds_read_b64 v[170:171], v221 offset:32
	ds_read_b64 v[172:173], v221 offset:48
	v_exp_f32_e32 v51, v51
	v_exp_f32_e32 v52, v52
	v_exp_f32_e32 v53, v53
	s_waitcnt lgkmcnt(8)
	v_mfma_f32_32x32x16_bf16 v[82:97], v[150:153], v[114:117], v[82:97]
	ds_read_b64 v[174:175], v221 offset:4384
	ds_read_b64 v[176:177], v221 offset:4400
	v_add_f32_e32 v231, v231, v50
	v_add_f32_e32 v232, v232, v51
	v_exp_f32_e32 v54, v54
	v_exp_f32_e32 v55, v55
	s_waitcnt lgkmcnt(9)
	v_mfma_f32_32x32x16_bf16 v[66:81], v[154:157], v[118:121], v[66:81]
	ds_read_b64 v[180:181], v221 offset:64
	ds_read_b64 v[182:183], v221 offset:80
	v_add_f32_e32 v231, v231, v52
	v_add_f32_e32 v232, v232, v53
	v_exp_f32_e32 v56, v56
	v_exp_f32_e32 v57, v57
	s_waitcnt lgkmcnt(10)
	v_mfma_f32_32x32x16_bf16 v[82:97], v[158:161], v[118:121], v[82:97]
	ds_read_b64 v[184:185], v221 offset:4416
	ds_read_b64 v[186:187], v221 offset:4432
	v_add_f32_e32 v231, v231, v54
	v_add_f32_e32 v232, v232, v55
	v_add_f32_e32 v231, v231, v56
	v_add_f32_e32 v232, v232, v57
	v_cvt_pk_bf16_f32 v50, v50, v51
	v_cvt_pk_bf16_f32 v51, v52, v53
	v_cvt_pk_bf16_f32 v52, v54, v55
	s_waitcnt lgkmcnt(10)
	s_nop 1
	v_mfma_f32_32x32x16_bf16 v[2:17], v[162:165], v[34:37], v[2:17]
	ds_read_b64 v[188:189], v221 offset:96
	ds_read_b64 v[190:191], v221 offset:112
	v_cvt_pk_bf16_f32 v53, v56, v57
	v_exp_f32_e32 v58, v58
	v_exp_f32_e32 v59, v59
	v_exp_f32_e32 v60, v60
	s_waitcnt lgkmcnt(10)
	v_mfma_f32_32x32x16_bf16 v[18:33], v[166:169], v[34:37], v[18:33]
	ds_read_b64 v[192:193], v221 offset:4448
	ds_read_b64 v[194:195], v221 offset:4464
	v_exp_f32_e32 v61, v61
	v_add_f32_e32 v231, v231, v58
	v_add_f32_e32 v232, v232, v59
	v_exp_f32_e32 v62, v62
	s_waitcnt lgkmcnt(10)
	v_mfma_f32_32x32x16_bf16 v[2:17], v[170:173], v[42:45], v[2:17]
	v_exp_f32_e32 v63, v63
	v_add_f32_e32 v231, v231, v60
	v_add_f32_e32 v232, v232, v61
	v_exp_f32_e32 v64, v64
	s_waitcnt lgkmcnt(8)
	v_mfma_f32_32x32x16_bf16 v[18:33], v[174:177], v[42:45], v[18:33]
	s_waitcnt vmcnt(1)
	ds_write_b64 v225, v[216:217] offset:17408
	ds_write_b64 v225, v[218:219] offset:17416
	v_exp_f32_e32 v65, v65
	v_add_f32_e32 v231, v231, v62
	v_add_f32_e32 v232, v232, v63
	v_add_f32_e32 v231, v231, v64
	v_add_f32_e32 v232, v232, v65
	s_waitcnt lgkmcnt(8)
	v_mfma_f32_32x32x16_bf16 v[2:17], v[180:183], v[50:53], v[2:17]
	v_cvt_pk_bf16_f32 v58, v58, v59
	v_cvt_pk_bf16_f32 v59, v60, v61
	v_cvt_pk_bf16_f32 v60, v62, v63
	v_cvt_pk_bf16_f32 v61, v64, v65
	v_max3_f32 v234, v66, v67, v68
	v_max3_f32 v235, v82, v83, v84
	s_waitcnt lgkmcnt(6)
	v_mfma_f32_32x32x16_bf16 v[18:33], v[184:187], v[50:53], v[18:33]
	v_max3_f32 v234, v234, v69, v70
	v_max3_f32 v235, v235, v85, v86
	v_max3_f32 v234, v234, v71, v72
	v_max3_f32 v235, v235, v87, v88
	v_max3_f32 v234, v234, v73, v74
	v_max3_f32 v235, v235, v89, v90
	v_max3_f32 v234, v234, v75, v76
	s_waitcnt lgkmcnt(4)
	v_mfma_f32_32x32x16_bf16 v[2:17], v[188:191], v[58:61], v[2:17]
	v_max3_f32 v235, v235, v91, v92
	v_max3_f32 v234, v234, v77, v78
	v_max3_f32 v235, v235, v93, v94
	v_max3_f32 v234, v234, v79, v80
	v_max3_f32 v235, v235, v95, v96
	v_max3_f32 v234, v234, v81, v97
	s_waitcnt lgkmcnt(2)
	v_mfma_f32_32x32x16_bf16 v[18:33], v[192:195], v[58:61], v[18:33]
	v_max_f32_e32 v234, v234, v235
	v_mov_b32_e32 v235, v234
	s_nop 1
	v_permlane32_swap_b32_e32 v234, v235
	v_max_f32_e32 v233, v234, v235
	v_cmp_lt_f32_e32 vcc, 4.0, v233
	s_cbranch_vccz .Lmla_nr_t0
	s_nop 15
	v_max_f32_e32 v234, 0, v233
	v_exp_f32_e64 v235, -v234
	v_add_f32_e32 v230, v230, v234
	v_sub_f32_e32 v66, v66, v234
	v_sub_f32_e32 v67, v67, v234
	v_sub_f32_e32 v68, v68, v234
	v_sub_f32_e32 v69, v69, v234
	v_sub_f32_e32 v70, v70, v234
	v_sub_f32_e32 v71, v71, v234
	v_sub_f32_e32 v72, v72, v234
	v_sub_f32_e32 v73, v73, v234
	v_sub_f32_e32 v74, v74, v234
	v_sub_f32_e32 v75, v75, v234
	v_sub_f32_e32 v76, v76, v234
	v_sub_f32_e32 v77, v77, v234
	v_sub_f32_e32 v78, v78, v234
	v_sub_f32_e32 v79, v79, v234
	v_sub_f32_e32 v80, v80, v234
	v_sub_f32_e32 v81, v81, v234
	v_sub_f32_e32 v82, v82, v234
	v_sub_f32_e32 v83, v83, v234
	v_sub_f32_e32 v84, v84, v234
	v_sub_f32_e32 v85, v85, v234
	v_sub_f32_e32 v86, v86, v234
	v_sub_f32_e32 v87, v87, v234
	v_sub_f32_e32 v88, v88, v234
	v_sub_f32_e32 v89, v89, v234
	v_sub_f32_e32 v90, v90, v234
	v_sub_f32_e32 v91, v91, v234
	v_sub_f32_e32 v92, v92, v234
	v_sub_f32_e32 v93, v93, v234
	v_sub_f32_e32 v94, v94, v234
	v_sub_f32_e32 v95, v95, v234
	v_sub_f32_e32 v96, v96, v234
	v_sub_f32_e32 v97, v97, v234
	v_mul_f32_e32 v231, v231, v235
	v_mul_f32_e32 v232, v232, v235
	v_mul_f32_e32 v2, v2, v235
	v_mul_f32_e32 v3, v3, v235
	v_mul_f32_e32 v4, v4, v235
	v_mul_f32_e32 v5, v5, v235
	v_mul_f32_e32 v6, v6, v235
	v_mul_f32_e32 v7, v7, v235
	v_mul_f32_e32 v8, v8, v235
	v_mul_f32_e32 v9, v9, v235
	v_mul_f32_e32 v10, v10, v235
	v_mul_f32_e32 v11, v11, v235
	v_mul_f32_e32 v12, v12, v235
	v_mul_f32_e32 v13, v13, v235
	v_mul_f32_e32 v14, v14, v235
	v_mul_f32_e32 v15, v15, v235
	v_mul_f32_e32 v16, v16, v235
	v_mul_f32_e32 v17, v17, v235
	v_mul_f32_e32 v18, v18, v235
	v_mul_f32_e32 v19, v19, v235
	v_mul_f32_e32 v20, v20, v235
	v_mul_f32_e32 v21, v21, v235
	v_mul_f32_e32 v22, v22, v235
	v_mul_f32_e32 v23, v23, v235
	v_mul_f32_e32 v24, v24, v235
	v_mul_f32_e32 v25, v25, v235
	v_mul_f32_e32 v26, v26, v235
	v_mul_f32_e32 v27, v27, v235
	v_mul_f32_e32 v28, v28, v235
	v_mul_f32_e32 v29, v29, v235
	v_mul_f32_e32 v30, v30, v235
	v_mul_f32_e32 v31, v31, v235
	v_mul_f32_e32 v32, v32, v235
	v_mul_f32_e32 v33, v33, v235
	v_sub_f32_e32 v122, 0, v230
	v_mov_b32_e32 v123, v122
	v_mov_b32_e32 v124, v122
	v_mov_b32_e32 v125, v122
	v_mov_b32_e32 v126, v122
	v_mov_b32_e32 v127, v122
	v_mov_b32_e32 v128, v122
	v_mov_b32_e32 v129, v122
	v_mov_b32_e32 v130, v122
	v_mov_b32_e32 v131, v122
	v_mov_b32_e32 v132, v122
	v_mov_b32_e32 v133, v122
	v_mov_b32_e32 v134, v122
	v_mov_b32_e32 v135, v122
	v_mov_b32_e32 v136, v122
	v_mov_b32_e32 v137, v122
.Lmla_nr_t0:
	ds_read_b128 v[138:141], v220 offset:26624
	ds_read_b128 v[142:145], v220 offset:33280
	ds_read_b128 v[146:149], v220 offset:26656
	ds_read_b128 v[150:153], v220 offset:33312
	ds_read_b128 v[154:157], v220 offset:26688
	ds_read_b128 v[158:161], v220 offset:33344
	s_waitcnt lgkmcnt(6)
	s_barrier
	v_exp_f32_e32 v66, v66
	v_exp_f32_e32 v67, v67
	v_exp_f32_e32 v68, v68
	v_exp_f32_e32 v69, v69
	s_waitcnt lgkmcnt(5)
	v_mfma_f32_32x32x16_bf16 v[34:49], v[138:141], v[98:101], v[122:137]
	ds_read_b128 v[138:141], v220 offset:26720
	v_add_f32_e32 v231, v231, v66
	v_add_f32_e32 v232, v232, v67
	v_exp_f32_e32 v70, v70
	v_exp_f32_e32 v71, v71
	s_waitcnt lgkmcnt(5)
	v_mfma_f32_32x32x16_bf16 v[50:65], v[142:145], v[98:101], v[122:137]
	ds_read_b128 v[142:145], v220 offset:33376
	v_add_f32_e32 v231, v231, v68
	v_add_f32_e32 v232, v232, v69
	v_exp_f32_e32 v72, v72
	v_exp_f32_e32 v73, v73
	s_waitcnt lgkmcnt(5)
	v_mfma_f32_32x32x16_bf16 v[34:49], v[146:149], v[102:105], v[34:49]
	ds_read_b128 v[146:149], v220 offset:26752
	v_add_f32_e32 v231, v231, v70
	v_add_f32_e32 v232, v232, v71
	v_add_f32_e32 v231, v231, v72
	v_add_f32_e32 v232, v232, v73
	v_cvt_pk_bf16_f32 v66, v66, v67
	v_cvt_pk_bf16_f32 v67, v68, v69
	s_waitcnt lgkmcnt(5)
	v_mfma_f32_32x32x16_bf16 v[50:65], v[150:153], v[102:105], v[50:65]
	ds_read_b128 v[150:153], v220 offset:33408
	v_cvt_pk_bf16_f32 v68, v70, v71
	v_cvt_pk_bf16_f32 v69, v72, v73
	v_exp_f32_e32 v74, v74
	v_exp_f32_e32 v75, v75
	s_waitcnt lgkmcnt(5)
	v_mfma_f32_32x32x16_bf16 v[34:49], v[154:157], v[106:109], v[34:49]
	ds_read_b128 v[154:157], v220 offset:26784
	v_exp_f32_e32 v76, v76
	v_exp_f32_e32 v77, v77
	v_add_f32_e32 v231, v231, v74
	v_add_f32_e32 v232, v232, v75
	s_waitcnt lgkmcnt(5)
	v_mfma_f32_32x32x16_bf16 v[50:65], v[158:161], v[106:109], v[50:65]
	ds_read_b128 v[158:161], v220 offset:33440
	v_exp_f32_e32 v78, v78
	v_exp_f32_e32 v79, v79
	v_add_f32_e32 v231, v231, v76
	v_add_f32_e32 v232, v232, v77
	v_exp_f32_e32 v80, v80
	s_waitcnt lgkmcnt(5)
	v_mfma_f32_32x32x16_bf16 v[34:49], v[138:141], v[110:113], v[34:49]
	ds_read_b64 v[162:163], v221 offset:8704
	ds_read_b64 v[164:165], v221 offset:8720
	v_exp_f32_e32 v81, v81
	v_add_f32_e32 v231, v231, v78
	v_add_f32_e32 v232, v232, v79
	v_add_f32_e32 v231, v231, v80
	s_waitcnt lgkmcnt(6)
	v_mfma_f32_32x32x16_bf16 v[50:65], v[142:145], v[110:113], v[50:65]
	ds_read_b64 v[166:167], v221 offset:13056
	ds_read_b64 v[168:169], v221 offset:13072
	v_add_f32_e32 v232, v232, v81
	v_cvt_pk_bf16_f32 v74, v74, v75
	v_cvt_pk_bf16_f32 v75, v76, v77
	v_cvt_pk_bf16_f32 v76, v78, v79
	v_cvt_pk_bf16_f32 v77, v80, v81
	v_exp_f32_e32 v82, v82
	s_waitcnt lgkmcnt(7)
	v_mfma_f32_32x32x16_bf16 v[34:49], v[146:149], v[114:117], v[34:49]
	ds_read_b64 v[170:171], v221 offset:8736
	ds_read_b64 v[172:173], v221 offset:8752
	v_exp_f32_e32 v83, v83
	v_exp_f32_e32 v84, v84
	v_exp_f32_e32 v85, v85
	s_waitcnt lgkmcnt(8)
	v_mfma_f32_32x32x16_bf16 v[50:65], v[150:153], v[114:117], v[50:65]
	ds_read_b64 v[174:175], v221 offset:13088
	ds_read_b64 v[176:177], v221 offset:13104
	v_add_f32_e32 v231, v231, v82
	v_add_f32_e32 v232, v232, v83
	v_exp_f32_e32 v86, v86
	v_exp_f32_e32 v87, v87
	s_waitcnt lgkmcnt(9)
	v_mfma_f32_32x32x16_bf16 v[34:49], v[154:157], v[118:121], v[34:49]
	ds_read_b64 v[180:181], v221 offset:8768
	ds_read_b64 v[182:183], v221 offset:8784
	v_add_f32_e32 v231, v231, v84
	v_add_f32_e32 v232, v232, v85
	v_exp_f32_e32 v88, v88
	v_exp_f32_e32 v89, v89
	s_waitcnt lgkmcnt(10)
	v_mfma_f32_32x32x16_bf16 v[50:65], v[158:161], v[118:121], v[50:65]
	ds_read_b64 v[184:185], v221 offset:13120
	ds_read_b64 v[186:187], v221 offset:13136
	v_add_f32_e32 v231, v231, v86
	v_add_f32_e32 v232, v232, v87
	v_add_f32_e32 v231, v231, v88
	v_add_f32_e32 v232, v232, v89
	v_cvt_pk_bf16_f32 v82, v82, v83
	v_cvt_pk_bf16_f32 v83, v84, v85
	v_cvt_pk_bf16_f32 v84, v86, v87
	s_waitcnt lgkmcnt(10)
	s_nop 1
	v_mfma_f32_32x32x16_bf16 v[2:17], v[162:165], v[66:69], v[2:17]
	ds_read_b64 v[188:189], v221 offset:8800
	ds_read_b64 v[190:191], v221 offset:8816
	v_cvt_pk_bf16_f32 v85, v88, v89
	v_exp_f32_e32 v90, v90
	v_exp_f32_e32 v91, v91
	v_exp_f32_e32 v92, v92
	s_waitcnt lgkmcnt(10)
	v_mfma_f32_32x32x16_bf16 v[18:33], v[166:169], v[66:69], v[18:33]
	ds_read_b64 v[192:193], v221 offset:13152
	ds_read_b64 v[194:195], v221 offset:13168
	v_exp_f32_e32 v93, v93
	v_add_f32_e32 v231, v231, v90
	v_add_f32_e32 v232, v232, v91
	v_exp_f32_e32 v94, v94
	s_waitcnt lgkmcnt(10)
	v_mfma_f32_32x32x16_bf16 v[2:17], v[170:173], v[74:77], v[2:17]
	v_exp_f32_e32 v95, v95
	v_add_f32_e32 v231, v231, v92
	v_add_f32_e32 v232, v232, v93
	v_exp_f32_e32 v96, v96
	s_waitcnt lgkmcnt(8)
	v_mfma_f32_32x32x16_bf16 v[18:33], v[174:177], v[74:77], v[18:33]
	s_waitcnt vmcnt(0)
	ds_write_b64 v225, v[212:213] offset:26112
	ds_write_b64 v225, v[214:215] offset:26120
	v_exp_f32_e32 v97, v97
	v_add_f32_e32 v231, v231, v94
	v_add_f32_e32 v232, v232, v95
	v_add_f32_e32 v231, v231, v96
	v_add_f32_e32 v232, v232, v97
	s_waitcnt lgkmcnt(8)
	v_mfma_f32_32x32x16_bf16 v[2:17], v[180:183], v[82:85], v[2:17]
	v_cvt_pk_bf16_f32 v90, v90, v91
	v_cvt_pk_bf16_f32 v91, v92, v93
	v_cvt_pk_bf16_f32 v92, v94, v95
	v_cvt_pk_bf16_f32 v93, v96, v97
	v_max3_f32 v234, v34, v35, v36
	v_max3_f32 v235, v50, v51, v52
	s_waitcnt lgkmcnt(6)
	v_mfma_f32_32x32x16_bf16 v[18:33], v[184:187], v[82:85], v[18:33]
	v_max3_f32 v234, v234, v37, v38
	v_max3_f32 v235, v235, v53, v54
	v_max3_f32 v234, v234, v39, v40
	v_max3_f32 v235, v235, v55, v56
	v_max3_f32 v234, v234, v41, v42
	v_max3_f32 v235, v235, v57, v58
	v_max3_f32 v234, v234, v43, v44
	s_waitcnt lgkmcnt(4)
	v_mfma_f32_32x32x16_bf16 v[2:17], v[188:191], v[90:93], v[2:17]
	v_max3_f32 v235, v235, v59, v60
	v_max3_f32 v234, v234, v45, v46
	v_max3_f32 v235, v235, v61, v62
	v_max3_f32 v234, v234, v47, v48
	v_max3_f32 v235, v235, v63, v64
	v_max3_f32 v234, v234, v49, v65
	s_waitcnt lgkmcnt(2)
	v_mfma_f32_32x32x16_bf16 v[18:33], v[192:195], v[90:93], v[18:33]
	v_max_f32_e32 v234, v234, v235
	v_mov_b32_e32 v235, v234
	s_nop 1
	v_permlane32_swap_b32_e32 v234, v235
	v_max_f32_e32 v233, v234, v235
	v_cmp_lt_f32_e32 vcc, 4.0, v233
	s_cbranch_vccz .Lmla_nr_t1
	s_nop 15
	v_max_f32_e32 v234, 0, v233
	v_exp_f32_e64 v235, -v234
	v_add_f32_e32 v230, v230, v234
	v_sub_f32_e32 v34, v34, v234
	v_sub_f32_e32 v35, v35, v234
	v_sub_f32_e32 v36, v36, v234
	v_sub_f32_e32 v37, v37, v234
	v_sub_f32_e32 v38, v38, v234
	v_sub_f32_e32 v39, v39, v234
	v_sub_f32_e32 v40, v40, v234
	v_sub_f32_e32 v41, v41, v234
	v_sub_f32_e32 v42, v42, v234
	v_sub_f32_e32 v43, v43, v234
	v_sub_f32_e32 v44, v44, v234
	v_sub_f32_e32 v45, v45, v234
	v_sub_f32_e32 v46, v46, v234
	v_sub_f32_e32 v47, v47, v234
	v_sub_f32_e32 v48, v48, v234
	v_sub_f32_e32 v49, v49, v234
	v_sub_f32_e32 v50, v50, v234
	v_sub_f32_e32 v51, v51, v234
	v_sub_f32_e32 v52, v52, v234
	v_sub_f32_e32 v53, v53, v234
	v_sub_f32_e32 v54, v54, v234
	v_sub_f32_e32 v55, v55, v234
	v_sub_f32_e32 v56, v56, v234
	v_sub_f32_e32 v57, v57, v234
	v_sub_f32_e32 v58, v58, v234
	v_sub_f32_e32 v59, v59, v234
	v_sub_f32_e32 v60, v60, v234
	v_sub_f32_e32 v61, v61, v234
	v_sub_f32_e32 v62, v62, v234
	v_sub_f32_e32 v63, v63, v234
	v_sub_f32_e32 v64, v64, v234
	v_sub_f32_e32 v65, v65, v234
	v_mul_f32_e32 v231, v231, v235
	v_mul_f32_e32 v232, v232, v235
	v_mul_f32_e32 v2, v2, v235
	v_mul_f32_e32 v3, v3, v235
	v_mul_f32_e32 v4, v4, v235
	v_mul_f32_e32 v5, v5, v235
	v_mul_f32_e32 v6, v6, v235
	v_mul_f32_e32 v7, v7, v235
	v_mul_f32_e32 v8, v8, v235
	v_mul_f32_e32 v9, v9, v235
	v_mul_f32_e32 v10, v10, v235
	v_mul_f32_e32 v11, v11, v235
	v_mul_f32_e32 v12, v12, v235
	v_mul_f32_e32 v13, v13, v235
	v_mul_f32_e32 v14, v14, v235
	v_mul_f32_e32 v15, v15, v235
	v_mul_f32_e32 v16, v16, v235
	v_mul_f32_e32 v17, v17, v235
	v_mul_f32_e32 v18, v18, v235
	v_mul_f32_e32 v19, v19, v235
	v_mul_f32_e32 v20, v20, v235
	v_mul_f32_e32 v21, v21, v235
	v_mul_f32_e32 v22, v22, v235
	v_mul_f32_e32 v23, v23, v235
	v_mul_f32_e32 v24, v24, v235
	v_mul_f32_e32 v25, v25, v235
	v_mul_f32_e32 v26, v26, v235
	v_mul_f32_e32 v27, v27, v235
	v_mul_f32_e32 v28, v28, v235
	v_mul_f32_e32 v29, v29, v235
	v_mul_f32_e32 v30, v30, v235
	v_mul_f32_e32 v31, v31, v235
	v_mul_f32_e32 v32, v32, v235
	v_mul_f32_e32 v33, v33, v235
	v_sub_f32_e32 v122, 0, v230
	v_mov_b32_e32 v123, v122
	v_mov_b32_e32 v124, v122
	v_mov_b32_e32 v125, v122
	v_mov_b32_e32 v126, v122
	v_mov_b32_e32 v127, v122
	v_mov_b32_e32 v128, v122
	v_mov_b32_e32 v129, v122
	v_mov_b32_e32 v130, v122
	v_mov_b32_e32 v131, v122
	v_mov_b32_e32 v132, v122
	v_mov_b32_e32 v133, v122
	v_mov_b32_e32 v134, v122
	v_mov_b32_e32 v135, v122
	v_mov_b32_e32 v136, v122
	v_mov_b32_e32 v137, v122
.Lmla_nr_t1:
	ds_read_b128 v[138:141], v220 offset:39936
	ds_read_b128 v[142:145], v220 offset:46592
	ds_read_b128 v[146:149], v220 offset:39968
	ds_read_b128 v[150:153], v220 offset:46624
	ds_read_b128 v[154:157], v220 offset:40000
	ds_read_b128 v[158:161], v220 offset:46656
	s_waitcnt lgkmcnt(6)
	s_barrier
	global_load_dwordx2 v[200:201], v236, s[14:15] offset:0
	global_load_dwordx2 v[202:203], v236, s[14:15] offset:16
	global_load_dwordx2 v[204:205], v236, s[14:15] offset:32
	global_load_dwordx2 v[206:207], v236, s[14:15] offset:48
	global_load_dwordx2 v[208:209], v236, s[14:15] offset:64
	global_load_dwordx2 v[210:211], v236, s[14:15] offset:80
	global_load_dwordx2 v[212:213], v236, s[14:15] offset:96
	global_load_dwordx2 v[214:215], v236, s[14:15] offset:112
	v_exp_f32_e32 v34, v34
	v_exp_f32_e32 v35, v35
	v_exp_f32_e32 v36, v36
	v_exp_f32_e32 v37, v37
	s_waitcnt lgkmcnt(5)
	v_mfma_f32_32x32x16_bf16 v[66:81], v[138:141], v[98:101], v[122:137]
	ds_read_b128 v[138:141], v220 offset:40032
	v_add_f32_e32 v231, v231, v34
	v_add_f32_e32 v232, v232, v35
	v_exp_f32_e32 v38, v38
	v_exp_f32_e32 v39, v39
	s_waitcnt lgkmcnt(5)
	v_mfma_f32_32x32x16_bf16 v[82:97], v[142:145], v[98:101], v[122:137]
	ds_read_b128 v[142:145], v220 offset:46688
	v_add_f32_e32 v231, v231, v36
	v_add_f32_e32 v232, v232, v37
	v_exp_f32_e32 v40, v40
	v_exp_f32_e32 v41, v41
	s_waitcnt lgkmcnt(5)
	v_mfma_f32_32x32x16_bf16 v[66:81], v[146:149], v[102:105], v[66:81]
	ds_read_b128 v[146:149], v220 offset:40064
	v_add_f32_e32 v231, v231, v38
	v_add_f32_e32 v232, v232, v39
	v_add_f32_e32 v231, v231, v40
	v_add_f32_e32 v232, v232, v41
	v_cvt_pk_bf16_f32 v34, v34, v35
	v_cvt_pk_bf16_f32 v35, v36, v37
	s_waitcnt lgkmcnt(5)
	v_mfma_f32_32x32x16_bf16 v[82:97], v[150:153], v[102:105], v[82:97]
	ds_read_b128 v[150:153], v220 offset:46720
	v_cvt_pk_bf16_f32 v36, v38, v39
	v_cvt_pk_bf16_f32 v37, v40, v41
	v_exp_f32_e32 v42, v42
	v_exp_f32_e32 v43, v43
	s_waitcnt lgkmcnt(5)
	v_mfma_f32_32x32x16_bf16 v[66:81], v[154:157], v[106:109], v[66:81]
	ds_read_b128 v[154:157], v220 offset:40096
	v_exp_f32_e32 v44, v44
	v_exp_f32_e32 v45, v45
	v_add_f32_e32 v231, v231, v42
	v_add_f32_e32 v232, v232, v43
	s_waitcnt lgkmcnt(5)
	v_mfma_f32_32x32x16_bf16 v[82:97], v[158:161], v[106:109], v[82:97]
	ds_read_b128 v[158:161], v220 offset:46752
	v_exp_f32_e32 v46, v46
	v_exp_f32_e32 v47, v47
	v_add_f32_e32 v231, v231, v44
	v_add_f32_e32 v232, v232, v45
	v_exp_f32_e32 v48, v48
	s_waitcnt lgkmcnt(5)
	v_mfma_f32_32x32x16_bf16 v[66:81], v[138:141], v[110:113], v[66:81]
	ds_read_b64 v[162:163], v221 offset:17408
	ds_read_b64 v[164:165], v221 offset:17424
	v_exp_f32_e32 v49, v49
	v_add_f32_e32 v231, v231, v46
	v_add_f32_e32 v232, v232, v47
	v_add_f32_e32 v231, v231, v48
	s_waitcnt lgkmcnt(6)
	v_mfma_f32_32x32x16_bf16 v[82:97], v[142:145], v[110:113], v[82:97]
	ds_read_b64 v[166:167], v221 offset:21760
	ds_read_b64 v[168:169], v221 offset:21776
	v_add_f32_e32 v232, v232, v49
	v_cvt_pk_bf16_f32 v42, v42, v43
	v_cvt_pk_bf16_f32 v43, v44, v45
	v_cvt_pk_bf16_f32 v44, v46, v47
	v_cvt_pk_bf16_f32 v45, v48, v49
	v_exp_f32_e32 v50, v50
	s_waitcnt lgkmcnt(7)
	v_mfma_f32_32x32x16_bf16 v[66:81], v[146:149], v[114:117], v[66:81]
	ds_read_b64 v[170:171], v221 offset:17440
	ds_read_b64 v[172:173], v221 offset:17456
	v_exp_f32_e32 v51, v51
	v_exp_f32_e32 v52, v52
	v_exp_f32_e32 v53, v53
	s_waitcnt lgkmcnt(8)
	v_mfma_f32_32x32x16_bf16 v[82:97], v[150:153], v[114:117], v[82:97]
	ds_read_b64 v[174:175], v221 offset:21792
	ds_read_b64 v[176:177], v221 offset:21808
	v_add_f32_e32 v231, v231, v50
	v_add_f32_e32 v232, v232, v51
	v_exp_f32_e32 v54, v54
	v_exp_f32_e32 v55, v55
	s_waitcnt lgkmcnt(9)
	v_mfma_f32_32x32x16_bf16 v[66:81], v[154:157], v[118:121], v[66:81]
	ds_read_b64 v[180:181], v221 offset:17472
	ds_read_b64 v[182:183], v221 offset:17488
	v_add_f32_e32 v231, v231, v52
	v_add_f32_e32 v232, v232, v53
	v_exp_f32_e32 v56, v56
	v_exp_f32_e32 v57, v57
	s_waitcnt lgkmcnt(10)
	v_mfma_f32_32x32x16_bf16 v[82:97], v[158:161], v[118:121], v[82:97]
	ds_read_b64 v[184:185], v221 offset:21824
	ds_read_b64 v[186:187], v221 offset:21840
	v_add_f32_e32 v231, v231, v54
	v_add_f32_e32 v232, v232, v55
	v_add_f32_e32 v231, v231, v56
	v_add_f32_e32 v232, v232, v57
	v_cvt_pk_bf16_f32 v50, v50, v51
	v_cvt_pk_bf16_f32 v51, v52, v53
	v_cvt_pk_bf16_f32 v52, v54, v55
	s_waitcnt lgkmcnt(10)
	s_nop 1
	v_mfma_f32_32x32x16_bf16 v[2:17], v[162:165], v[34:37], v[2:17]
	ds_read_b64 v[188:189], v221 offset:17504
	ds_read_b64 v[190:191], v221 offset:17520
	v_cvt_pk_bf16_f32 v53, v56, v57
	v_exp_f32_e32 v58, v58
	v_exp_f32_e32 v59, v59
	v_exp_f32_e32 v60, v60
	s_waitcnt lgkmcnt(10)
	v_mfma_f32_32x32x16_bf16 v[18:33], v[166:169], v[34:37], v[18:33]
	ds_read_b64 v[192:193], v221 offset:21856
	ds_read_b64 v[194:195], v221 offset:21872
	v_exp_f32_e32 v61, v61
	v_add_f32_e32 v231, v231, v58
	v_add_f32_e32 v232, v232, v59
	v_exp_f32_e32 v62, v62
	s_waitcnt lgkmcnt(10)
	v_mfma_f32_32x32x16_bf16 v[2:17], v[170:173], v[42:45], v[2:17]
	v_exp_f32_e32 v63, v63
	v_add_f32_e32 v231, v231, v60
	v_add_f32_e32 v232, v232, v61
	v_exp_f32_e32 v64, v64
	s_waitcnt lgkmcnt(8)
	v_mfma_f32_32x32x16_bf16 v[18:33], v[174:177], v[42:45], v[18:33]
	v_exp_f32_e32 v65, v65
	v_add_f32_e32 v231, v231, v62
	v_add_f32_e32 v232, v232, v63
	v_add_f32_e32 v231, v231, v64
	v_add_f32_e32 v232, v232, v65
	s_waitcnt lgkmcnt(6)
	v_mfma_f32_32x32x16_bf16 v[2:17], v[180:183], v[50:53], v[2:17]
	v_cvt_pk_bf16_f32 v58, v58, v59
	v_cvt_pk_bf16_f32 v59, v60, v61
	v_cvt_pk_bf16_f32 v60, v62, v63
	v_cvt_pk_bf16_f32 v61, v64, v65
	v_max3_f32 v234, v66, v67, v68
	v_max3_f32 v235, v82, v83, v84
	s_waitcnt lgkmcnt(4)
	v_mfma_f32_32x32x16_bf16 v[18:33], v[184:187], v[50:53], v[18:33]
	v_max3_f32 v234, v234, v69, v70
	v_max3_f32 v235, v235, v85, v86
	v_max3_f32 v234, v234, v71, v72
	v_max3_f32 v235, v235, v87, v88
	v_max3_f32 v234, v234, v73, v74
	v_max3_f32 v235, v235, v89, v90
	v_max3_f32 v234, v234, v75, v76
	s_waitcnt lgkmcnt(2)
	v_mfma_f32_32x32x16_bf16 v[2:17], v[188:191], v[58:61], v[2:17]
	v_max3_f32 v235, v235, v91, v92
	v_max3_f32 v234, v234, v77, v78
	v_max3_f32 v235, v235, v93, v94
	v_max3_f32 v234, v234, v79, v80
	v_max3_f32 v235, v235, v95, v96
	v_max3_f32 v234, v234, v81, v97
	s_waitcnt lgkmcnt(0)
	v_mfma_f32_32x32x16_bf16 v[18:33], v[192:195], v[58:61], v[18:33]
	v_max_f32_e32 v234, v234, v235
	v_mov_b32_e32 v235, v234
	s_nop 1
	v_permlane32_swap_b32_e32 v234, v235
	v_max_f32_e32 v233, v234, v235
	v_cmp_lt_f32_e32 vcc, 4.0, v233
	s_cbranch_vccz .Lmla_nr_t2
	s_nop 15
	v_max_f32_e32 v234, 0, v233
	v_exp_f32_e64 v235, -v234
	v_add_f32_e32 v230, v230, v234
	v_sub_f32_e32 v66, v66, v234
	v_sub_f32_e32 v67, v67, v234
	v_sub_f32_e32 v68, v68, v234
	v_sub_f32_e32 v69, v69, v234
	v_sub_f32_e32 v70, v70, v234
	v_sub_f32_e32 v71, v71, v234
	v_sub_f32_e32 v72, v72, v234
	v_sub_f32_e32 v73, v73, v234
	v_sub_f32_e32 v74, v74, v234
	v_sub_f32_e32 v75, v75, v234
	v_sub_f32_e32 v76, v76, v234
	v_sub_f32_e32 v77, v77, v234
	v_sub_f32_e32 v78, v78, v234
	v_sub_f32_e32 v79, v79, v234
	v_sub_f32_e32 v80, v80, v234
	v_sub_f32_e32 v81, v81, v234
	v_sub_f32_e32 v82, v82, v234
	v_sub_f32_e32 v83, v83, v234
	v_sub_f32_e32 v84, v84, v234
	v_sub_f32_e32 v85, v85, v234
	v_sub_f32_e32 v86, v86, v234
	v_sub_f32_e32 v87, v87, v234
	v_sub_f32_e32 v88, v88, v234
	v_sub_f32_e32 v89, v89, v234
	v_sub_f32_e32 v90, v90, v234
	v_sub_f32_e32 v91, v91, v234
	v_sub_f32_e32 v92, v92, v234
	v_sub_f32_e32 v93, v93, v234
	v_sub_f32_e32 v94, v94, v234
	v_sub_f32_e32 v95, v95, v234
	v_sub_f32_e32 v96, v96, v234
	v_sub_f32_e32 v97, v97, v234
	v_mul_f32_e32 v231, v231, v235
	v_mul_f32_e32 v232, v232, v235
	v_mul_f32_e32 v2, v2, v235
	v_mul_f32_e32 v3, v3, v235
	v_mul_f32_e32 v4, v4, v235
	v_mul_f32_e32 v5, v5, v235
	v_mul_f32_e32 v6, v6, v235
	v_mul_f32_e32 v7, v7, v235
	v_mul_f32_e32 v8, v8, v235
	v_mul_f32_e32 v9, v9, v235
	v_mul_f32_e32 v10, v10, v235
	v_mul_f32_e32 v11, v11, v235
	v_mul_f32_e32 v12, v12, v235
	v_mul_f32_e32 v13, v13, v235
	v_mul_f32_e32 v14, v14, v235
	v_mul_f32_e32 v15, v15, v235
	v_mul_f32_e32 v16, v16, v235
	v_mul_f32_e32 v17, v17, v235
	v_mul_f32_e32 v18, v18, v235
	v_mul_f32_e32 v19, v19, v235
	v_mul_f32_e32 v20, v20, v235
	v_mul_f32_e32 v21, v21, v235
	v_mul_f32_e32 v22, v22, v235
	v_mul_f32_e32 v23, v23, v235
	v_mul_f32_e32 v24, v24, v235
	v_mul_f32_e32 v25, v25, v235
	v_mul_f32_e32 v26, v26, v235
	v_mul_f32_e32 v27, v27, v235
	v_mul_f32_e32 v28, v28, v235
	v_mul_f32_e32 v29, v29, v235
	v_mul_f32_e32 v30, v30, v235
	v_mul_f32_e32 v31, v31, v235
	v_mul_f32_e32 v32, v32, v235
	v_mul_f32_e32 v33, v33, v235
	v_sub_f32_e32 v122, 0, v230
	v_mov_b32_e32 v123, v122
	v_mov_b32_e32 v124, v122
	v_mov_b32_e32 v125, v122
	v_mov_b32_e32 v126, v122
	v_mov_b32_e32 v127, v122
	v_mov_b32_e32 v128, v122
	v_mov_b32_e32 v129, v122
	v_mov_b32_e32 v130, v122
	v_mov_b32_e32 v131, v122
	v_mov_b32_e32 v132, v122
	v_mov_b32_e32 v133, v122
	v_mov_b32_e32 v134, v122
	v_mov_b32_e32 v135, v122
	v_mov_b32_e32 v136, v122
	v_mov_b32_e32 v137, v122
